# mixer: all 988 hipcc SLP-packed v_pk_mul/add/fma_f32 split into scalar f32 pairs (packed f32 beside MFMAs is an issue-stall anti-lever); on top of stage B
# speedup vs baseline: 1.0064x; 1.0064x over previous
; #define LAS __attribute__((address_space(3)))
; template <bool DIAG> DI void sb_tile(const KFrag& kf, const VFrag& vf, const bf16x8 (&qf)[4], float& F, f32x16& o0, f32x16& o1, int r, int hh) {
;     const f32x16 st = qk_mma(kf, qf);
;     f32x16 w; float M[2];
; #pragma unroll
;     for (int run = 0; run < 2; ++run) {
;         float E = 1.f;
; #pragma unroll
;         for (int e = 7; e >= 0; --e) { const int i = 8 * run + e;
;             const float ex = __builtin_amdgcn_exp2f(__builtin_fminf(st[i], 100.f));
;             float sc = __builtin_amdgcn_rcpf(1.0f + ex), beta = ex * sc;
;             if (DIAG) { if (e + 8 * hh + 16 * run >= r) { sc = 1.f; beta = 0.f; } }
; DI void mixer_phase(const Params& p, unsigned char* ldsraw, int vid) {
;     ...
; #pragma unroll 4
;             for (int j = 0; j < 16; ++j) { const int q = wid * 16 + j, tr = q >> 1, half = q & 1;
;                 __builtin_amdgcn_global_load_lds((const unsigned*)(RR + (size_t)(t0 + tr) * 2048 + 1024 + half * 512 + ((ln ^ (tr & 15)) << 3)), (LAS unsigned*)((LAS unsigned char*)ldsraw + 4096 + tr * 2048 + half * 1024), 16, 0, 0); }
;         }
;         const unsigned char* gl = ldsraw + 4096;
;         {
;             f32x16 oA0, oA1, oB0, oB1; ZERO16(oA0); ZERO16(oA1); ZERO16(oB0); ZERO16(oB1);
;             bf16x8 qfA[4], qfB[4];
;             { const bf16_t* qp = QK + ((size_t)(t0 >> 5) * 8 + wid) * 2048 + ln * 8;
; #pragma unroll
;               for (int s = 0; s < 4; ++s) { qfA[s] = *(const bf16x8*)(qp + 512 * s); qfB[s] = *(const bf16x8*)(qp + 8 * 2048 + 512 * s); } }
;             const bf16_t* kb = QK + (size_t)T * 512 + (size_t)wid * 2048 + ln * 8;
;             const bf16_t* vb = VT + (size_t)wid * 2048 + ln * 8;
;             float FA = 1.f, FB = 1.f;
;             KFrag kc, kn; VFrag vc, vn;
;             load_kf(kc, kb + (size_t)((t0 + 32) >> 5) * 16384); load_vf(vc, vb + (size_t)((t0 + 32) >> 5) * 16384); load_kf(kn, kb + (size_t)(t0 >> 5) * 16384); load_vf(vn, vb + (size_t)(t0 >> 5) * 16384);
;             sb_tile<true>(kc, vc, qfB, FB, oB0, oB1, r, hh);
;             kc = kn; vc = vn;
;             int key0 = t0 - 32;
;             if (key0 >= 0) { load_kf(kn, kb + (size_t)(key0 >> 5) * 16384); load_vf(vn, vb + (size_t)(key0 >> 5) * 16384); }
;             sb_tile<true>(kc, vc, qfA, FA, oA0, oA1, r, hh);
.LBB0_397:
	s_ashr_i32 s5, s0, 1
	s_add_i32 s4, s5, s38
	v_bitop3_b32 v0, s5, v205, 14 bitop3:0x6c
	s_ashr_i32 s5, s4, 31
	s_lshl_b64 s[4:5], s[4:5], 12
	v_lshlrev_b32_e32 v0, 3, v0
	s_add_u32 s4, s44, s4
	v_ashrrev_i32_e32 v1, 31, v0
	s_addc_u32 s5, s45, s5
	s_add_i32 s9, s0, 2
	v_lshl_add_u64 v[0:1], v[0:1], 1, s[4:5]
	s_ashr_i32 s5, s9, 1
	s_add_i32 s8, s96, s1
	s_add_i32 s4, s5, s38
	s_add_i32 m0, s8, 0x1000
	v_lshl_add_u64 v[2:3], v[0:1], 0, s[84:85]
	v_bitop3_b32 v4, s5, v205, 15 bitop3:0x6c
	s_ashr_i32 s5, s4, 31
	global_load_lds_dwordx4 v[2:3], off
	s_add_i32 m0, s8, 0x1400
	s_lshl_b64 s[4:5], s[4:5], 12
	v_lshlrev_b32_e32 v2, 3, v4
	s_add_u32 s4, s44, s4
	v_lshl_add_u64 v[0:1], v[0:1], 0, s[86:87]
	v_ashrrev_i32_e32 v3, 31, v2
	s_addc_u32 s5, s45, s5
	global_load_lds_dwordx4 v[0:1], off
	v_lshl_add_u64 v[0:1], v[2:3], 1, s[4:5]
	s_add_i32 m0, s8, 0x1800
	v_lshl_add_u64 v[2:3], v[0:1], 0, s[84:85]
	v_lshl_add_u64 v[0:1], v[0:1], 0, s[86:87]
	global_load_lds_dwordx4 v[2:3], off
	s_add_i32 m0, s8, 0x1c00
	s_addk_i32 s1, 0x1000
	global_load_lds_dwordx4 v[0:1], off
	s_add_i32 s0, s0, 4
	s_cmpk_lg_i32 s1, 0x4000
	s_cbranch_scc1 .LBB0_397
	s_lshl_b32 s4, s72, 1
	s_ashr_i32 s5, s4, 31
	s_lshl_b64 s[0:1], s[4:5], 15
	v_lshlrev_b32_e32 v180, 3, v205
	s_add_u32 s8, s90, s0
	v_ashrrev_i32_e32 v181, 31, v180
	s_addc_u32 s9, s91, s1
	v_lshlrev_b64 v[28:29], 1, v[180:181]
	v_lshl_add_u64 v[44:45], s[8:9], 0, v[28:29]
	s_mov_b32 s5, 0x8000
	s_or_b32 s4, s4, 1
	v_add_co_u32_e32 v4, vcc, s5, v44
	s_ashr_i32 s5, s4, 31
	v_lshl_add_u64 v[184:185], s[54:55], 0, v[28:29]
	s_lshl_b64 s[4:5], s[4:5], 15
	v_lshl_add_u64 v[6:7], v[184:185], 0, s[4:5]
	global_load_dwordx4 v[0:3], v[6:7], off
	v_addc_co_u32_e32 v5, vcc, 0, v45, vcc
	global_load_dwordx4 v[80:83], v[4:5], off
	global_load_dwordx4 v[16:19], v[6:7], off offset:1024
	global_load_dwordx4 v[84:87], v[4:5], off offset:1024
	global_load_dwordx4 v[20:23], v[6:7], off offset:2048
	global_load_dwordx4 v[88:91], v[4:5], off offset:2048
	global_load_dwordx4 v[24:27], v[6:7], off offset:3072
	global_load_dwordx4 v[92:95], v[4:5], off offset:3072
	v_lshl_add_u64 v[186:187], s[62:63], 0, v[28:29]
	v_lshl_add_u64 v[28:29], v[184:185], 0, s[0:1]
	v_lshl_add_u64 v[30:31], v[186:187], 0, s[0:1]
	global_load_dwordx4 v[60:63], v[28:29], off
	global_load_dwordx4 v[56:59], v[28:29], off offset:1024
	global_load_dwordx4 v[52:55], v[28:29], off offset:2048
	global_load_dwordx4 v[48:51], v[28:29], off offset:3072
	global_load_dwordx4 v[76:79], v[30:31], off
	global_load_dwordx4 v[68:71], v[30:31], off offset:1024
	global_load_dwordx4 v[72:75], v[30:31], off offset:2048
	global_load_dwordx4 v[64:67], v[30:31], off offset:3072
	global_load_dwordx4 v[96:99], v[44:45], off
	global_load_dwordx4 v[100:103], v[44:45], off offset:1024
	v_ashrrev_i32_e32 v176, 5, v205
	v_lshlrev_b32_e32 v182, 3, v176
	v_and_b32_e32 v206, 31, v205
	v_or_b32_e32 v46, 7, v182
	v_or_b32_e32 v47, 6, v182
	v_cmp_lt_i32_e64 s[36:37], v46, v206
	v_cmp_lt_i32_e64 s[34:35], v47, v206
	v_add_u32_e32 v104, 23, v182
	v_add_u32_e32 v105, 22, v182
	v_cmp_lt_i32_e64 s[30:31], v104, v206
	v_cmp_lt_i32_e64 s[28:29], v105, v206
	v_add_u32_e32 v47, 21, v182
	v_cmp_lt_i32_e32 vcc, v203, v204
	v_cmp_lt_i32_e64 s[24:25], v47, v206
	v_or_b32_e32 v115, 5, v182
	v_or_b32_e32 v116, 4, v182
	v_add_u32_e32 v112, 16, v182
	v_cmp_lt_i32_e64 s[12:13], v115, v206
	v_or_b32_e32 v117, 3, v182
	v_cmp_lt_i32_e64 s[18:19], v112, v206
	v_cmp_lt_i32_e64 s[14:15], v116, v206
	v_or_b32_e32 v118, 2, v182
	v_add_u32_e32 v110, 18, v182
	v_cmp_lt_i32_e64 s[8:9], v117, v206
	v_or_b32_e32 v119, 1, v182
	v_add_u32_e32 v111, 17, v182
	v_cmp_lt_i32_e64 s[22:23], v110, v206
	v_cmp_lt_i32_e64 s[10:11], v118, v206
	v_cmp_lt_i32_e64 s[16:17], v111, v206
	v_cmp_lt_i32_e64 s[0:1], v182, v206
	s_sub_i32 s39, s38, 32
	s_cmp_lt_i32 s72, 1
	s_waitcnt vmcnt(0)
	v_mfma_f32_32x32x16_bf16 v[0:15], v[0:3], v[80:83], 0
	v_mov_b64_e32 v[126:127], v[78:79]
	v_mov_b64_e32 v[122:123], v[74:75]
	v_mov_b64_e32 v[142:143], v[62:63]
	v_mov_b64_e32 v[138:139], v[58:59]
	v_mov_b64_e32 v[134:135], v[54:55]
	v_mov_b64_e32 v[130:131], v[50:51]
	v_mov_b64_e32 v[120:121], v[72:73]
	v_mfma_f32_32x32x16_bf16 v[0:15], v[16:19], v[84:87], v[0:15]
	v_mov_b64_e32 v[124:125], v[76:77]
	v_mov_b64_e32 v[140:141], v[60:61]
	v_mov_b64_e32 v[136:137], v[56:57]
	v_mov_b64_e32 v[132:133], v[52:53]
	v_mov_b64_e32 v[128:129], v[48:49]
	v_mfma_f32_32x32x16_bf16 v[0:15], v[20:23], v[88:91], v[0:15]
	v_lshl_add_u64 v[20:21], v[186:187], 0, s[4:5]
	global_load_dwordx4 v[16:19], v[20:21], off
	global_load_dwordx4 v[36:39], v[20:21], off offset:1024
	global_load_dwordx4 v[40:43], v[20:21], off offset:2048
	global_load_dwordx4 v[32:35], v[20:21], off offset:3072
	v_cmp_gt_u32_e64 s[4:5], 32, v205
	v_mfma_f32_32x32x16_bf16 v[0:15], v[24:27], v[92:95], v[0:15]
	s_nop 11
	v_max_f32_e32 v7, v7, v7
	v_max_f32_e32 v6, v6, v6
	v_max_f32_e32 v5, v5, v5
	v_max_f32_e32 v4, v4, v4
	v_max_f32_e32 v2, v2, v2
	v_max_f32_e32 v15, v15, v15
	v_min_f32_e32 v7, 0x42c80000, v7
	v_min_f32_e32 v6, 0x42c80000, v6
	v_min_f32_e32 v5, 0x42c80000, v5
	v_min_f32_e32 v4, 0x42c80000, v4
	v_min_f32_e32 v2, 0x42c80000, v2
	v_min_f32_e32 v15, 0x42c80000, v15
	v_exp_f32_e32 v22, v7
	v_exp_f32_e32 v24, v6
	v_max_f32_e32 v1, v1, v1
	v_max_f32_e32 v14, v14, v14
	v_exp_f32_e32 v7, v5
	v_exp_f32_e32 v6, v4
	v_exp_f32_e32 v4, v2
	v_exp_f32_e32 v25, v15
	v_max_f32_e32 v3, v3, v3
	v_min_f32_e32 v1, 0x42c80000, v1
	v_min_f32_e32 v14, 0x42c80000, v14
	v_max_f32_e32 v0, v0, v0
	v_max_f32_e32 v12, v12, v12
	v_min_f32_e32 v3, 0x42c80000, v3
	v_exp_f32_e32 v1, v1
	v_exp_f32_e32 v26, v14
; template <bool DIAG> DI void sb_tile(const KFrag& kf, const VFrag& vf, const bf16x8 (&qf)[4], float& F, f32x16& o0, f32x16& o1, int r, int hh) {
;     const f32x16 st = qk_mma(kf, qf);
;     f32x16 w; float M[2];
; #pragma unroll
;     for (int run = 0; run < 2; ++run) {
;         float E = 1.f;
; #pragma unroll
;         for (int e = 7; e >= 0; --e) { const int i = 8 * run + e;
;             const float ex = __builtin_amdgcn_exp2f(__builtin_fminf(st[i], 100.f));
;             float sc = __builtin_amdgcn_rcpf(1.0f + ex), beta = ex * sc;
;             if (DIAG) { if (e + 8 * hh + 16 * run >= r) { sc = 1.f; beta = 0.f; } }
;             w[i] = beta * E; E *= sc; }
;         M[run] = E;
;     }
;     const float P0 = __shfl_xor(M[0], 32), P1 = __shfl_xor(M[1], 32);
;     const float off1 = F * (hh == 0 ? P1 : 1.f);
;     const float off0 = F * (M[1] * P1) * (hh == 0 ? P0 : 1.f);
;     F = F * (M[0] * P0) * (M[1] * P1);
; #pragma unroll
;     for (int i = 0; i < 16; ++i) w[i] *= (i < 8 ? off0 : off1);
;     pv_mma(vf, w, o0, o1);
; }
	v_max_f32_e32 v13, v13, v13
	v_min_f32_e32 v0, 0x42c80000, v0
	v_min_f32_e32 v12, 0x42c80000, v12
	v_exp_f32_e32 v5, v3
	v_add_f32_e32 v2, 1.0, v22
	v_add_f32_e32 v3, 1.0, v24
	v_min_f32_e32 v13, 0x42c80000, v13
	v_exp_f32_e32 v0, v0
	v_exp_f32_e32 v20, v12
	v_add_f32_e32 v12, 1.0, v7
	v_add_f32_e32 v27, 1.0, v4
	v_add_f32_e32 v30, 1.0, v25
	v_rcp_f32_e32 v108, v2
	v_rcp_f32_e32 v109, v3
	v_exp_f32_e32 v21, v13
	v_rcp_f32_e32 v15, v12
	v_rcp_f32_e32 v12, v27
	v_rcp_f32_e32 v27, v30
	v_max_f32_e32 v9, v9, v9
	v_add_f32_e32 v28, 1.0, v1
	v_add_f32_e32 v31, 1.0, v26
	v_min_f32_e32 v9, 0x42c80000, v9
	v_max_f32_e32 v8, v8, v8
	v_rcp_f32_e32 v3, v28
	v_rcp_f32_e32 v28, v31
	v_max_f32_e32 v11, v11, v11
	v_exp_f32_e32 v9, v9
	v_min_f32_e32 v8, 0x42c80000, v8
	v_add_f32_e32 v29, 1.0, v0
	v_mul_f32_e32 v22, v22, v108
	v_mul_f32_e32 v24, v24, v109
	v_min_f32_e32 v11, 0x42c80000, v11
	v_max_f32_e32 v10, v10, v10
	v_exp_f32_e32 v8, v8
	v_add_f32_e32 v13, 1.0, v6
	v_add_f32_e32 v23, 1.0, v5
	v_add_f32_e32 v106, 1.0, v21
	v_add_f32_e32 v107, 1.0, v20
	v_rcp_f32_e32 v2, v29
	v_cndmask_b32_e64 v30, 1.0, v108, s[36:37]
	v_mul_f32_e32 v29, v25, v27
	v_cndmask_b32_e64 v25, 0, v22, s[36:37]
	v_cndmask_b32_e64 v22, 0, v24, s[34:35]
	v_exp_f32_e32 v11, v11
	v_min_f32_e32 v10, 0x42c80000, v10
	v_rcp_f32_e32 v14, v13
	v_rcp_f32_e32 v13, v23
	v_rcp_f32_e32 v23, v106
	v_mul_f32_e32 v24, v30, v22
	v_rcp_f32_e32 v22, v107
	v_exp_f32_e32 v10, v10
	v_mul_f32_e32 v26, v26, v28
	v_cndmask_b32_e64 v105, 0, v29, s[30:31]
	v_add_f32_e32 v29, 1.0, v9
	v_cndmask_b32_e64 v46, 1.0, v27, s[30:31]
	v_cndmask_b32_e64 v26, 0, v26, s[28:29]
	v_rcp_f32_e32 v107, v29
	v_add_f32_e32 v29, 1.0, v8
	v_cndmask_b32_e64 v28, 1.0, v28, s[28:29]
	v_mul_f32_e32 v104, v46, v26
	v_add_u32_e32 v108, 20, v182
	v_add_f32_e32 v26, 1.0, v11
	v_rcp_f32_e32 v106, v29
	v_cndmask_b32_e32 v29, v202, v203, vcc
	v_rcp_f32_e32 v27, v26
	v_add_f32_e32 v26, 1.0, v10
	v_lshlrev_b32_e32 v181, 2, v29
	v_mul_f32_e32 v29, v46, v28
	v_mul_f32_e32 v20, v20, v22
	v_mul_f32_e32 v21, v21, v23
	v_cndmask_b32_e64 v23, 1.0, v23, s[24:25]
	v_cmp_lt_i32_e64 s[26:27], v108, v206
	v_cndmask_b32_e64 v31, 1.0, v109, s[34:35]
	v_rcp_f32_e32 v26, v26
	v_mul_f32_e32 v28, v23, v29
	v_cndmask_b32_e64 v21, 0, v21, s[24:25]
	v_cndmask_b32_e64 v20, 0, v20, s[26:27]
	v_add_u32_e32 v109, 19, v182
	v_mul_f32_e32 v112, v20, v28
	v_mul_f32_e32 v113, v21, v29
	v_mul_f32_e32 v6, v6, v14
	v_mul_f32_e32 v7, v7, v15
	v_mul_f32_e32 v21, v30, v31
	v_cndmask_b32_e64 v15, 1.0, v15, s[12:13]
	v_cndmask_b32_e64 v22, 1.0, v22, s[26:27]
	v_cmp_lt_i32_e64 s[20:21], v109, v206
	v_mul_f32_e32 v20, v15, v21
	v_cndmask_b32_e64 v14, 1.0, v14, s[14:15]
	v_cndmask_b32_e64 v23, 1.0, v27, s[20:21]
	v_mul_f32_e32 v109, v22, v28
	v_cndmask_b32_e64 v7, 0, v7, s[12:13]
	v_cndmask_b32_e64 v6, 0, v6, s[14:15]
	v_mul_f32_e32 v4, v4, v12
	v_mul_f32_e32 v5, v5, v13
	v_cndmask_b32_e64 v15, 1.0, v13, s[8:9]
	v_mul_f32_e32 v13, v14, v20
	v_cndmask_b32_e64 v46, 1.0, v26, s[22:23]
	v_mul_f32_e32 v108, v23, v109
	v_mul_f32_e32 v6, v6, v20
	v_mul_f32_e32 v7, v7, v21
	v_cndmask_b32_e64 v21, 1.0, v12, s[10:11]
	v_cndmask_b32_e64 v5, 0, v5, s[8:9]
	v_cndmask_b32_e64 v4, 0, v4, s[10:11]
	v_mul_f32_e32 v12, v15, v13
	v_cmp_lt_i32_e32 vcc, v119, v206
	v_cndmask_b32_e64 v22, 1.0, v107, s[16:17]
	v_mul_f32_e32 v111, v46, v108
	v_mul_f32_e32 v4, v4, v12
	v_mul_f32_e32 v5, v5, v13
	v_cndmask_b32_e32 v14, 1.0, v3, vcc
	v_mul_f32_e32 v13, v21, v12
	v_cndmask_b32_e64 v23, 1.0, v106, s[18:19]
	v_mul_f32_e32 v110, v22, v111
	v_cndmask_b32_e64 v15, 1.0, v2, s[0:1]
	v_mul_f32_e32 v12, v14, v13
	v_mul_f32_e32 v22, v23, v110
	v_mul_f32_e32 v47, v15, v12
	ds_bpermute_b32 v23, v181, v22
	ds_bpermute_b32 v144, v181, v47
	v_mul_f32_e32 v0, v0, v2
	v_mul_f32_e32 v1, v1, v3
	v_mul_f32_e32 v10, v10, v26
	v_mul_f32_e32 v11, v11, v27
	v_cndmask_b32_e32 v1, 0, v1, vcc
	s_waitcnt lgkmcnt(0)
	v_mul_f32_e32 v46, v22, v23
	v_cndmask_b32_e64 v0, 0, v0, s[0:1]
	v_cndmask_b32_e64 v2, 1.0, v144, s[4:5]
	v_mul_f32_e32 v0, v0, v12
	v_mul_f32_e32 v1, v1, v13
	v_mul_f32_e32 v2, v2, v46
	v_mul_f32_e32 v0, v0, v2
	v_mul_f32_e32 v1, v1, v2
	v_mul_f32_e32 v4, v4, v2
	v_mul_f32_e32 v5, v5, v2
	v_cvt_pk_bf16_f32 v0, v0, v1
	v_cvt_pk_bf16_f32 v1, v4, v5
	v_mul_f32_e32 v4, v8, v106
	v_mul_f32_e32 v5, v9, v107
	v_cndmask_b32_e64 v11, 0, v11, s[20:21]
	v_mul_f32_e32 v6, v6, v2
	v_mul_f32_e32 v7, v7, v2
	v_mul_f32_e32 v12, v24, v2
	v_mul_f32_e32 v13, v25, v2
	v_cndmask_b32_e64 v10, 0, v10, s[22:23]
	v_cndmask_b32_e64 v5, 0, v5, s[16:17]
	v_cndmask_b32_e64 v4, 0, v4, s[18:19]
	v_cndmask_b32_e64 v114, 1.0, v23, s[4:5]
	v_cvt_pk_bf16_f32 v2, v6, v7
	v_cvt_pk_bf16_f32 v3, v12, v13
	v_mul_f32_e32 v108, v10, v108
	v_mul_f32_e32 v109, v11, v109
	v_mul_f32_e32 v4, v4, v110
	v_mul_f32_e32 v5, v5, v111
	s_waitcnt vmcnt(3)
	v_mfma_f32_32x32x16_bf16 v[16:31], v[16:19], v[0:3], 0
	v_mul_f32_e64 v106, v114, v4
	v_mul_f32_e64 v107, v114, v5
	v_mul_f32_e64 v104, v114, v104
	v_mul_f32_e64 v105, v114, v105
	v_mov_b64_e32 v[118:119], v[70:71]
	v_mov_b64_e32 v[116:117], v[68:69]
	s_waitcnt vmcnt(1)
	v_mfma_f32_32x32x16_bf16 v[0:15], v[40:43], v[0:3], 0
	v_mul_f32_e64 v42, v114, v108
	v_mul_f32_e64 v43, v114, v109
	v_mul_f32_e64 v108, v114, v112
	v_mul_f32_e64 v109, v114, v113
	v_cvt_pk_bf16_f32 v40, v106, v107
	v_cvt_pk_bf16_f32 v41, v42, v43
	v_cvt_pk_bf16_f32 v42, v108, v109
	v_cvt_pk_bf16_f32 v43, v104, v105
	global_load_dwordx4 v[104:107], v[44:45], off offset:2048
	global_load_dwordx4 v[108:111], v[44:45], off offset:3072
	v_mfma_f32_32x32x16_bf16 v[16:31], v[36:39], v[40:43], v[16:31]
	v_mov_b64_e32 v[114:115], v[66:67]
	v_mov_b64_e32 v[112:113], v[64:65]
	s_waitcnt vmcnt(2)
	v_mfma_f32_32x32x16_bf16 v[0:15], v[32:35], v[40:43], v[0:15]
	s_cbranch_scc1 .LBB0_400
	s_lshr_b32 s72, s39, 5
	s_lshl_b64 s[64:65], s[72:73], 15
	v_lshl_add_u64 v[32:33], v[184:185], 0, s[64:65]
	global_load_dwordx4 v[140:143], v[32:33], off
	global_load_dwordx4 v[136:139], v[32:33], off offset:1024
	global_load_dwordx4 v[132:135], v[32:33], off offset:2048
	global_load_dwordx4 v[128:131], v[32:33], off offset:3072
	v_lshl_add_u64 v[32:33], v[186:187], 0, s[64:65]
	global_load_dwordx4 v[124:127], v[32:33], off
	global_load_dwordx4 v[116:119], v[32:33], off offset:1024
	global_load_dwordx4 v[120:123], v[32:33], off offset:2048
	global_load_dwordx4 v[112:115], v[32:33], off offset:3072
; template <bool DIAG> DI void sb_tile(const KFrag& kf, const VFrag& vf, const bf16x8 (&qf)[4], float& F, f32x16& o0, f32x16& o1, int r, int hh) {
;     const f32x16 st = qk_mma(kf, qf);
;     f32x16 w; float M[2];
; #pragma unroll
;     for (int run = 0; run < 2; ++run) {
;         float E = 1.f;
; #pragma unroll
;         for (int e = 7; e >= 0; --e) { const int i = 8 * run + e;
;             const float ex = __builtin_amdgcn_exp2f(__builtin_fminf(st[i], 100.f));
;             float sc = __builtin_amdgcn_rcpf(1.0f + ex), beta = ex * sc;
;             if (DIAG) { if (e + 8 * hh + 16 * run >= r) { sc = 1.f; beta = 0.f; } }
;             w[i] = beta * E; E *= sc; }
; DI void mixer_phase(const Params& p, unsigned char* ldsraw, int vid) {
;     ...
;             sb_tile<true>(kc, vc, qfA, FA, oA0, oA1, r, hh);
;             sb_tile<false>(kc, vc, qfB, FB, oB0, oB1, r, hh);
.LBB0_400:
	v_mul_f32_e32 v32, v47, v144
	v_mul_f32_e32 v151, v32, v46
	v_mfma_f32_32x32x16_bf16 v[32:47], v[60:63], v[96:99], 0
	v_mfma_f32_32x32x16_bf16 v[32:47], v[56:59], v[100:103], v[32:47]
	s_waitcnt vmcnt(1)
	v_mfma_f32_32x32x16_bf16 v[32:47], v[52:55], v[104:107], v[32:47]
	s_waitcnt vmcnt(0)
	v_mfma_f32_32x32x16_bf16 v[32:47], v[48:51], v[108:111], v[32:47]
	s_nop 11
	v_max_f32_e32 v32, v32, v32
	v_min_f32_e32 v32, 0x42c80000, v32
	v_exp_f32_e32 v162, v32
	v_max_f32_e32 v33, v33, v33
	v_min_f32_e32 v33, 0x42c80000, v33
	v_exp_f32_e32 v163, v33
	v_add_f32_e32 v32, 1.0, v162
	v_rcp_f32_e32 v164, v32
	v_max_f32_e32 v32, v47, v47
	v_min_f32_e32 v32, 0x42c80000, v32
	v_exp_f32_e32 v32, v32
	v_add_f32_e32 v33, 1.0, v163
	v_rcp_f32_e32 v165, v33
	v_max_f32_e32 v39, v39, v39
	v_add_f32_e32 v33, 1.0, v32
	v_rcp_f32_e32 v33, v33
	v_min_f32_e32 v39, 0x42c80000, v39
	v_exp_f32_e32 v39, v39
	v_max_f32_e32 v38, v38, v38
	v_mul_f32_e32 v32, v32, v33
	v_cndmask_b32_e64 v147, 0, v32, s[30:31]
	v_max_f32_e32 v32, v46, v46
	v_min_f32_e32 v32, 0x42c80000, v32
	v_exp_f32_e32 v32, v32
	v_cndmask_b32_e64 v172, 1.0, v33, s[30:31]
	v_add_f32_e32 v144, 1.0, v39
	v_rcp_f32_e32 v144, v144
	v_add_f32_e32 v33, 1.0, v32
	v_rcp_f32_e32 v33, v33
	v_min_f32_e32 v38, 0x42c80000, v38
	v_exp_f32_e32 v38, v38
	v_mul_f32_e32 v39, v39, v144
	v_mul_f32_e32 v32, v32, v33
	v_cndmask_b32_e64 v32, 0, v32, s[28:29]
	v_mul_f32_e32 v146, v172, v32
	v_max_f32_e32 v32, v45, v45
	v_min_f32_e32 v32, 0x42c80000, v32
	v_exp_f32_e32 v191, v32
	v_cndmask_b32_e64 v153, 0, v39, s[36:37]
	v_add_f32_e32 v39, 1.0, v38
	v_max_f32_e32 v37, v37, v37
	v_add_f32_e32 v32, 1.0, v191
	v_rcp_f32_e32 v193, v32
	v_max_f32_e32 v32, v44, v44
	v_min_f32_e32 v32, 0x42c80000, v32
	v_exp_f32_e32 v190, v32
	v_max_f32_e32 v36, v36, v36
	v_max_f32_e32 v35, v35, v35
	v_max_f32_e32 v34, v34, v34
	v_add_f32_e32 v32, 1.0, v190
	v_rcp_f32_e32 v192, v32
	v_max_f32_e32 v32, v43, v43
	v_min_f32_e32 v32, 0x42c80000, v32
	v_exp_f32_e32 v195, v32
	v_rcp_f32_e32 v39, v39
	v_min_f32_e32 v37, 0x42c80000, v37
	v_min_f32_e32 v36, 0x42c80000, v36
	v_add_f32_e32 v32, 1.0, v195
	v_rcp_f32_e32 v197, v32
	v_max_f32_e32 v32, v42, v42
	v_min_f32_e32 v32, 0x42c80000, v32
	v_exp_f32_e32 v194, v32
	v_min_f32_e32 v35, 0x42c80000, v35
	v_min_f32_e32 v34, 0x42c80000, v34
	v_exp_f32_e32 v155, v37
	v_add_f32_e32 v32, 1.0, v194
	v_rcp_f32_e32 v196, v32
	v_max_f32_e32 v32, v41, v41
	v_min_f32_e32 v32, 0x42c80000, v32
	v_exp_f32_e32 v175, v32
	v_exp_f32_e32 v154, v36
	v_exp_f32_e32 v159, v35
	v_exp_f32_e32 v158, v34
	v_add_f32_e32 v32, 1.0, v175
	v_rcp_f32_e32 v189, v32
	v_max_f32_e32 v32, v40, v40
	v_min_f32_e32 v32, 0x42c80000, v32
	v_exp_f32_e32 v174, v32
	v_mul_f32_e32 v38, v38, v39
	v_cndmask_b32_e64 v148, 1.0, v144, s[36:37]
	v_cndmask_b32_e64 v38, 0, v38, s[34:35]
	v_add_f32_e32 v37, 1.0, v155
	v_add_f32_e32 v36, 1.0, v154
	v_add_f32_e32 v35, 1.0, v159
	v_add_f32_e32 v34, 1.0, v158
	v_add_f32_e32 v32, 1.0, v174
	v_cndmask_b32_e64 v144, 1.0, v39, s[34:35]
	v_mul_f32_e32 v152, v148, v38
	v_rcp_f32_e32 v157, v37
	v_rcp_f32_e32 v156, v36
	v_rcp_f32_e32 v161, v35
	v_rcp_f32_e32 v160, v34
	v_cndmask_b32_e64 v198, 1.0, v33, s[28:29]
	v_rcp_f32_e32 v188, v32
	v_mfma_f32_32x32x16_bf16 v[32:47], v[60:63], v[80:83], 0
	v_mfma_f32_32x32x16_bf16 v[32:47], v[56:59], v[84:87], v[32:47]
	v_mfma_f32_32x32x16_bf16 v[32:47], v[52:55], v[88:91], v[32:47]
	v_mfma_f32_32x32x16_bf16 v[32:47], v[48:51], v[92:95], v[32:47]
	s_nop 11
	v_max_f32_e32 v32, v32, v32
	v_min_f32_e32 v32, 0x42c80000, v32
	v_exp_f32_e32 v58, v32
	v_max_f32_e32 v34, v34, v34
	v_min_f32_e32 v34, 0x42c80000, v34
	v_exp_f32_e32 v56, v34
	v_add_f32_e32 v32, 1.0, v58
	v_rcp_f32_e32 v48, v32
	v_max_f32_e32 v32, v47, v47
	v_min_f32_e32 v32, 0x42c80000, v32
	v_exp_f32_e32 v171, v32
	v_max_f32_e32 v39, v39, v39
	v_add_f32_e32 v34, 1.0, v56
	v_min_f32_e32 v39, 0x42c80000, v39
	v_max_f32_e32 v38, v38, v38
	v_rcp_f32_e32 v52, v34
	v_max_f32_e32 v34, v43, v43
	v_exp_f32_e32 v167, v39
	v_min_f32_e32 v38, 0x42c80000, v38
	v_min_f32_e32 v34, 0x42c80000, v34
	v_exp_f32_e32 v38, v38
	v_max_f32_e32 v33, v33, v33
	v_add_f32_e32 v32, 1.0, v171
	v_exp_f32_e32 v47, v34
	v_min_f32_e32 v33, 0x42c80000, v33
	v_rcp_f32_e32 v149, v32
	v_max_f32_e32 v32, v46, v46
	v_exp_f32_e32 v59, v33
	v_min_f32_e32 v32, 0x42c80000, v32
	v_add_f32_e32 v39, 1.0, v167
	v_max_f32_e32 v37, v37, v37
	v_exp_f32_e32 v32, v32
	v_rcp_f32_e32 v169, v39
	v_add_f32_e32 v39, 1.0, v38
	v_min_f32_e32 v37, 0x42c80000, v37
	v_add_f32_e32 v34, 1.0, v47
	v_rcp_f32_e32 v51, v39
	v_exp_f32_e32 v37, v37
	v_rcp_f32_e32 v39, v34
	v_max_f32_e32 v34, v42, v42
	v_add_f32_e32 v33, 1.0, v59
	v_min_f32_e32 v34, 0x42c80000, v34
	v_rcp_f32_e32 v49, v33
	v_add_f32_e32 v33, 1.0, v32
	v_exp_f32_e32 v46, v34
	v_rcp_f32_e32 v145, v33
	v_mul_f32_e32 v166, v38, v51
	v_add_f32_e32 v38, 1.0, v37
	v_rcp_f32_e32 v173, v38
	v_add_f32_e32 v34, 1.0, v46
	v_max_f32_e32 v35, v35, v35
	v_mul_f32_e32 v170, v32, v145
	v_max_f32_e32 v32, v45, v45
	v_rcp_f32_e32 v38, v34
	v_max_f32_e32 v34, v41, v41
	v_max_f32_e32 v36, v36, v36
	v_min_f32_e32 v35, 0x42c80000, v35
	v_min_f32_e32 v32, 0x42c80000, v32
	v_min_f32_e32 v34, 0x42c80000, v34
	v_mul_f32_e32 v55, v37, v173
	v_min_f32_e32 v36, 0x42c80000, v36
	v_exp_f32_e32 v57, v35
	v_exp_f32_e32 v37, v32
	v_exp_f32_e32 v61, v34
	v_exp_f32_e32 v50, v36
	v_add_f32_e32 v35, 1.0, v57
	v_add_f32_e32 v32, 1.0, v37
	v_add_f32_e32 v34, 1.0, v61
	v_add_f32_e32 v36, 1.0, v50
	v_rcp_f32_e32 v53, v35
	v_rcp_f32_e32 v33, v32
	v_max_f32_e32 v32, v44, v44
	v_rcp_f32_e32 v35, v34
	v_max_f32_e32 v34, v40, v40
	v_rcp_f32_e32 v168, v36
; template <bool DIAG> DI void sb_tile(const KFrag& kf, const VFrag& vf, const bf16x8 (&qf)[4], float& F, f32x16& o0, f32x16& o1, int r, int hh) {
;     ...
;         for (int e = 7; e >= 0; --e) { const int i = 8 * run + e;
;             const float ex = __builtin_amdgcn_exp2f(__builtin_fminf(st[i], 100.f));
;             float sc = __builtin_amdgcn_rcpf(1.0f + ex), beta = ex * sc;
;             if (DIAG) { if (e + 8 * hh + 16 * run >= r) { sc = 1.f; beta = 0.f; } }
;             w[i] = beta * E; E *= sc; }
;         M[run] = E;
;     }
;     const float P0 = __shfl_xor(M[0], 32), P1 = __shfl_xor(M[1], 32);
;     const float off1 = F * (hh == 0 ? P1 : 1.f);
;     const float off0 = F * (M[1] * P1) * (hh == 0 ? P0 : 1.f);
;     F = F * (M[0] * P0) * (M[1] * P1);
	v_min_f32_e32 v32, 0x42c80000, v32
	v_min_f32_e32 v34, 0x42c80000, v34
	v_exp_f32_e32 v36, v32
	v_exp_f32_e32 v60, v34
	v_mul_f32_e32 v40, v46, v38
	v_mul_f32_e32 v41, v47, v39
	v_mul_f32_e32 v46, v50, v168
	v_mul_f32_e32 v47, v51, v169
	v_add_f32_e32 v32, 1.0, v36
	v_add_f32_e32 v34, 1.0, v60
	v_mov_b32_e32 v199, v47
	v_rcp_f32_e32 v32, v32
	v_rcp_f32_e32 v34, v34
	v_mul_f32_e32 v50, v172, v198
	v_mul_f32_e32 v51, v173, v199
	v_mul_f32_e32 v42, v148, v144
	v_mul_f32_e32 v43, v149, v145
	v_mov_b32_e32 v54, v51
	v_mul_f32_e32 v172, v46, v54
	v_mul_f32_e32 v173, v47, v55
	v_mul_f32_e32 v46, v56, v52
	v_mul_f32_e32 v47, v57, v53
	v_cndmask_b32_e64 v56, 1.0, v193, s[24:25]
	v_mov_b32_e32 v57, v168
	v_mul_f32_e32 v54, v58, v48
	v_mul_f32_e32 v55, v59, v49
	v_mul_f32_e32 v58, v190, v192
	v_mul_f32_e32 v59, v191, v193
	v_mul_f32_e32 v56, v56, v50
	v_mul_f32_e32 v57, v57, v51
	v_mul_f32_e32 v44, v36, v32
	v_mul_f32_e32 v45, v37, v33
	v_mul_f32_e32 v36, v60, v34
	v_mul_f32_e32 v37, v61, v35
	v_cndmask_b32_e64 v60, 1.0, v192, s[26:27]
	v_cndmask_b32_e64 v59, 0, v59, s[24:25]
	v_cndmask_b32_e64 v58, 0, v58, s[26:27]
	v_mov_b32_e32 v62, v56
	v_mov_b32_e32 v63, v50
	v_mov_b32_e32 v61, v53
	v_mul_f32_e32 v50, v58, v62
	v_mul_f32_e32 v51, v59, v63
	v_mul_f32_e32 v58, v60, v56
	v_mul_f32_e32 v59, v61, v57
	v_cndmask_b32_e64 v60, 1.0, v196, s[22:23]
	v_mov_b32_e32 v56, v59
	v_mul_f32_e32 v190, v46, v56
	v_mul_f32_e32 v191, v47, v57
	v_cndmask_b32_e64 v46, 1.0, v197, s[20:21]
	v_mov_b32_e32 v47, v52
	v_mul_f32_e32 v56, v194, v196
	v_mul_f32_e32 v57, v195, v197
	v_mul_f32_e32 v46, v46, v58
	v_mul_f32_e32 v47, v47, v59
	v_cndmask_b32_e64 v57, 0, v57, s[20:21]
	v_cndmask_b32_e64 v56, 0, v56, s[22:23]
	v_mov_b32_e32 v61, v49
	v_mov_b32_e32 v52, v46
	v_mov_b32_e32 v53, v58
	v_mul_f32_e32 v52, v56, v52
	v_mul_f32_e32 v53, v57, v53
	v_mul_f32_e32 v56, v60, v46
	v_mul_f32_e32 v57, v61, v47
	v_cndmask_b32_e64 v58, 1.0, v189, s[16:17]
	v_mov_b32_e32 v59, v48
	v_mul_f32_e32 v48, v58, v56
	v_mul_f32_e32 v49, v59, v57
	ds_bpermute_b32 v63, v181, v49
	v_cndmask_b32_e64 v62, 1.0, v188, s[18:19]
	v_mov_b32_e32 v58, v48
	v_mul_f32_e32 v60, v174, v188
	v_mul_f32_e32 v61, v175, v189
	v_mov_b32_e32 v59, v56
	s_waitcnt lgkmcnt(0)
	v_mul_f32_e32 v48, v62, v48
	v_mul_f32_e32 v49, v63, v49
	ds_bpermute_b32 v150, v181, v48
	v_cndmask_b32_e64 v61, 0, v61, s[16:17]
	v_cndmask_b32_e64 v60, 0, v60, s[18:19]
	v_mul_f32_e32 v58, v60, v58
	v_mul_f32_e32 v59, v61, v59
	s_waitcnt lgkmcnt(0)
; #define MFMA32(a, b, c) __builtin_amdgcn_mfma_f32_32x32x16_bf16((a), (b), (c), 0, 0, 0)
; DI void pv_mma(const VFrag& f, const f32x16& w, f32x16& o0, f32x16& o1) {
; #pragma unroll
;     for (int s = 0; s < 2; ++s) { const bf16x8 pf = pack8(w, s); o0 = MFMA32(f.v[0][s], pf, o0); o1 = MFMA32(f.v[1][s], pf, o1); }
; }
; template <bool DIAG> DI void sb_tile(const KFrag& kf, const VFrag& vf, const bf16x8 (&qf)[4], float& F, f32x16& o0, f32x16& o1, int r, int hh) {
;     ...
;     const float P0 = __shfl_xor(M[0], 32), P1 = __shfl_xor(M[1], 32);
;     const float off1 = F * (hh == 0 ? P1 : 1.f);
;     const float off0 = F * (M[1] * P1) * (hh == 0 ? P0 : 1.f);
;     F = F * (M[0] * P0) * (M[1] * P1);
; #pragma unroll
;     for (int i = 0; i < 16; ++i) w[i] *= (i < 8 ? off0 : off1);
;     pv_mma(vf, w, o0, o1);
	v_cndmask_b32_e64 v46, 1.0, v150, s[4:5]
	v_mul_f32_e32 v174, v48, v150
	v_mul_f32_e32 v175, v49, v151
	v_mul_f32_e32 v48, v46, v58
	v_mul_f32_e32 v49, v46, v59
	v_mul_f32_e32 v52, v46, v52
	v_mul_f32_e32 v53, v46, v53
	v_mul_f32_e32 v50, v46, v50
	v_mul_f32_e32 v51, v46, v51
	v_mul_f32_e32 v58, v46, v146
	v_mul_f32_e32 v59, v46, v147
	v_mov_b32_e32 v46, v57
	v_mul_f32_e32 v192, v54, v46
	v_mul_f32_e32 v193, v55, v47
	v_cndmask_b32_e64 v46, 1.0, v157, s[12:13]
	v_mov_b32_e32 v47, v33
	v_mul_f32_e32 v46, v46, v42
	v_mul_f32_e32 v47, v47, v43
	v_cvt_pk_bf16_f32 v145, v52, v53
	v_cvt_pk_bf16_f32 v146, v50, v51
	v_cndmask_b32_e64 v50, 1.0, v156, s[14:15]
	v_mov_b32_e32 v53, v42
	v_mov_b32_e32 v51, v32
	v_mov_b32_e32 v42, v47
	v_cvt_pk_bf16_f32 v144, v48, v49
	v_mul_f32_e32 v48, v154, v156
	v_mul_f32_e32 v49, v155, v157
	v_mul_f32_e32 v32, v50, v46
	v_mul_f32_e32 v33, v51, v47
	v_mul_f32_e32 v154, v44, v42
	v_mul_f32_e32 v155, v45, v43
	v_cndmask_b32_e64 v42, 1.0, v161, s[8:9]
	v_mov_b32_e32 v43, v39
	v_mul_f32_e32 v44, v158, v160
	v_mul_f32_e32 v45, v159, v161
	v_mov_b32_e32 v47, v38
	v_mul_f32_e32 v38, v42, v32
	v_mul_f32_e32 v39, v43, v33
	v_mov_b32_e32 v52, v46
	v_cndmask_b32_e64 v46, 1.0, v160, s[10:11]
	v_cndmask_b32_e64 v45, 0, v45, s[8:9]
	v_cndmask_b32_e64 v44, 0, v44, s[10:11]
	v_mov_b32_e32 v42, v38
	v_mov_b32_e32 v43, v32
	v_mov_b32_e32 v32, v39
	v_mul_f32_e32 v42, v44, v42
	v_mul_f32_e32 v43, v45, v43
	v_mul_f32_e32 v44, v46, v38
	v_mul_f32_e32 v45, v47, v39
	v_mul_f32_e32 v156, v40, v32
	v_mul_f32_e32 v157, v41, v33
	v_cndmask_b32_e32 v32, 1.0, v165, vcc
	v_mov_b32_e32 v33, v35
	v_mul_f32_e32 v38, v162, v164
	v_mul_f32_e32 v39, v163, v165
	v_mul_f32_e32 v32, v32, v44
	v_mul_f32_e32 v33, v33, v45
	v_cndmask_b32_e64 v40, 1.0, v164, s[0:1]
	v_cndmask_b32_e32 v39, 0, v39, vcc
	v_cndmask_b32_e64 v38, 0, v38, s[0:1]
	v_mov_b32_e32 v41, v34
	v_mov_b32_e32 v34, v32
	v_mov_b32_e32 v35, v44
	v_mul_f32_e32 v34, v38, v34
	v_mul_f32_e32 v35, v39, v35
	v_mul_f32_e32 v38, v40, v32
	v_mul_f32_e32 v39, v41, v33
	ds_bpermute_b32 v40, v181, v38
	ds_bpermute_b32 v41, v181, v39
	v_cndmask_b32_e64 v49, 0, v49, s[12:13]
	v_cndmask_b32_e64 v48, 0, v48, s[14:15]
	v_mul_f32_e32 v48, v48, v52
	v_mul_f32_e32 v49, v49, v53
	s_waitcnt lgkmcnt(1)
	v_cndmask_b32_e64 v32, 1.0, v40, s[4:5]
	v_mov_b32_e32 v44, v33
	s_waitcnt lgkmcnt(0)
	v_cndmask_b32_e64 v33, 1.0, v41, s[4:5]
	v_mul_f32_e32 v32, v32, v174
	v_mul_f32_e32 v158, v38, v40
	v_mul_f32_e32 v159, v39, v41
	v_mul_f32_e32 v160, v36, v44
	v_mul_f32_e32 v161, v37, v45
	v_mul_f32_e32 v34, v34, v32
	v_mul_f32_e32 v35, v35, v32
	v_mul_f32_e32 v36, v42, v32
	v_mul_f32_e32 v37, v43, v32
	v_mul_f32_e32 v38, v48, v32
	v_mul_f32_e32 v39, v49, v32
	v_mul_f32_e32 v40, v152, v32
	v_mul_f32_e32 v41, v153, v32
	v_mul_f32_e32 v148, v151, v33
	v_cvt_pk_bf16_f32 v32, v34, v35
	v_cvt_pk_bf16_f32 v33, v36, v37
	v_cvt_pk_bf16_f32 v34, v38, v39
	v_cvt_pk_bf16_f32 v35, v40, v41
	v_cvt_pk_bf16_f32 v147, v58, v59
	v_cndmask_b32_e64 v150, 1.0, v63, s[4:5]
	v_mfma_f32_32x32x16_bf16 v[48:63], v[76:79], v[32:35], 0
	v_mul_f32_e32 v151, v151, v159
	v_mul_f32_e64 v188, v158, v174
	v_mul_f32_e64 v189, v159, v175
	v_mov_b32_e32 v158, v169
	v_mul_f32_e32 v159, v158, v167
	v_mul_f32_e32 v158, v158, v166
	v_mul_f32_e32 v160, v148, v160
	v_mul_f32_e32 v161, v148, v161
	v_mul_f32_e32 v156, v148, v156
	v_mul_f32_e32 v157, v148, v157
	v_mul_f32_e32 v154, v148, v154
	v_mul_f32_e32 v155, v148, v155
	v_mfma_f32_32x32x16_bf16 v[32:47], v[72:75], v[32:35], 0
	v_mfma_f32_32x32x16_bf16 v[48:63], v[68:71], v[144:147], v[48:63]
	v_mfma_f32_32x32x16_bf16 v[32:47], v[64:67], v[144:147], v[32:47]
	v_mul_f32_e32 v144, v150, v151
	v_mul_f32_e64 v146, v192, v144
	v_mul_f32_e64 v147, v193, v144
	v_mul_f32_e64 v150, v190, v144
	v_mul_f32_e64 v151, v191, v144
	v_mul_f32_e32 v152, v172, v144
	v_mul_f32_e32 v153, v173, v144
	v_mul_f32_e32 v158, v158, v144
	v_mul_f32_e32 v159, v159, v144
	v_mov_b32_e32 v144, v149
	v_mul_f32_e32 v145, v144, v171
	v_mul_f32_e32 v144, v144, v170
	v_mul_f32_e32 v149, v148, v145
	v_mul_f32_e32 v148, v148, v144
	v_cvt_pk_bf16_f32 v144, v146, v147
	v_cvt_pk_bf16_f32 v145, v150, v151
	v_cvt_pk_bf16_f32 v146, v152, v153
	v_cvt_pk_bf16_f32 v147, v158, v159
	s_nop 1
	v_mfma_f32_32x32x16_bf16 v[16:31], v[76:79], v[144:147], v[16:31]
	v_mfma_f32_32x32x16_bf16 v[0:15], v[72:75], v[144:147], v[0:15]
	v_cvt_pk_bf16_f32 v72, v160, v161
	v_cvt_pk_bf16_f32 v73, v156, v157
	v_cvt_pk_bf16_f32 v74, v154, v155
	v_cvt_pk_bf16_f32 v75, v148, v149
	s_nop 1
	v_mfma_f32_32x32x16_bf16 v[16:31], v[68:71], v[72:75], v[16:31]
	v_mfma_f32_32x32x16_bf16 v[0:15], v[64:67], v[72:75], v[0:15]
	s_branch .LBB0_403

; #define MFMA32(a, b, c) __builtin_amdgcn_mfma_f32_32x32x16_bf16((a), (b), (c), 0, 0, 0)
; DI f32x16 qk_mma(const KFrag& f, const bf16x8 (&qf)[4]) {
;     f32x16 st;
; #pragma unroll
;     for (int i = 0; i < 16; ++i) st[i] = 0.f;
; #pragma unroll
;     for (int s = 0; s < 4; ++s) st = MFMA32(f.k[s], qf[s], st);
;     return st;
; }
; template <bool DIAG> DI void sb_tile(const KFrag& kf, const VFrag& vf, const bf16x8 (&qf)[4], float& F, f32x16& o0, f32x16& o1, int r, int hh) {
;     const f32x16 st = qk_mma(kf, qf);
;     f32x16 w; float M[2];
; #pragma unroll
;     for (int run = 0; run < 2; ++run) {
;         float E = 1.f;
; #pragma unroll
;         for (int e = 7; e >= 0; --e) { const int i = 8 * run + e;
;             const float ex = __builtin_amdgcn_exp2f(__builtin_fminf(st[i], 100.f));
;             float sc = __builtin_amdgcn_rcpf(1.0f + ex), beta = ex * sc;
;             if (DIAG) { if (e + 8 * hh + 16 * run >= r) { sc = 1.f; beta = 0.f; } }
;             w[i] = beta * E; E *= sc; }
;         M[run] = E;
;     }
;     const float P0 = __shfl_xor(M[0], 32), P1 = __shfl_xor(M[1], 32);
;     const float off1 = F * (hh == 0 ? P1 : 1.f);
;     const float off0 = F * (M[1] * P1) * (hh == 0 ? P0 : 1.f);
;     F = F * (M[0] * P0) * (M[1] * P1);
; #pragma unroll
;     for (int i = 0; i < 16; ++i) w[i] *= (i < 8 ? off0 : off1);
;     pv_mma(vf, w, o0, o1);
; }
.LBB0_407:
	s_andn2_b64 vcc, exec, s[10:11]
	s_cbranch_vccnz .LBB0_409
	v_mfma_f32_32x32x16_bf16 v[64:79], v[140:143], v[96:99], 0
	v_mfma_f32_32x32x16_bf16 v[64:79], v[136:139], v[100:103], v[64:79]
	v_mfma_f32_32x32x16_bf16 v[64:79], v[132:135], v[104:107], v[64:79]
	v_mfma_f32_32x32x16_bf16 v[64:79], v[128:131], v[108:111], v[64:79]
	s_nop 11
	v_max_f32_e32 v71, v71, v71
	v_max_f32_e32 v65, v65, v65
	v_min_f32_e32 v71, 0x42c80000, v71
	v_max_f32_e32 v70, v70, v70
	v_max_f32_e32 v64, v64, v64
	v_min_f32_e32 v191, 0x42c80000, v65
	v_exp_f32_e32 v65, v71
	v_max_f32_e32 v69, v69, v69
	v_min_f32_e32 v70, 0x42c80000, v70
	v_min_f32_e32 v64, 0x42c80000, v64
	v_exp_f32_e32 v71, v191
	v_max_f32_e32 v79, v79, v79
	v_max_f32_e32 v68, v68, v68
	v_max_f32_e32 v67, v67, v67
	v_min_f32_e32 v69, 0x42c80000, v69
	v_exp_f32_e32 v207, v70
	v_exp_f32_e32 v70, v64
	v_min_f32_e32 v79, 0x42c80000, v79
	v_max_f32_e32 v78, v78, v78
	v_max_f32_e32 v66, v66, v66
	v_min_f32_e32 v68, 0x42c80000, v68
	v_min_f32_e32 v183, 0x42c80000, v67
	v_exp_f32_e32 v67, v69
	v_exp_f32_e32 v79, v79
	v_min_f32_e32 v78, 0x42c80000, v78
	v_max_f32_e32 v77, v77, v77
	v_min_f32_e32 v190, 0x42c80000, v66
	v_exp_f32_e32 v66, v68
	v_add_f32_e32 v64, 1.0, v65
	v_exp_f32_e32 v78, v78
	v_min_f32_e32 v77, 0x42c80000, v77
	v_max_f32_e32 v76, v76, v76
	v_exp_f32_e32 v69, v183
	v_rcp_f32_e32 v191, v64
	v_add_f32_e32 v64, 1.0, v71
	v_exp_f32_e32 v77, v77
	v_min_f32_e32 v76, 0x42c80000, v76
	v_max_f32_e32 v75, v75, v75
	v_exp_f32_e32 v68, v190
	v_rcp_f32_e32 v211, v64
	v_add_f32_e32 v64, 1.0, v70
	v_exp_f32_e32 v76, v76
	v_min_f32_e32 v75, 0x42c80000, v75
	v_max_f32_e32 v74, v74, v74
	v_add_f32_e32 v190, 1.0, v67
	v_rcp_f32_e32 v213, v64
	v_add_f32_e32 v64, 1.0, v79
	v_exp_f32_e32 v75, v75
	v_min_f32_e32 v74, 0x42c80000, v74
	v_max_f32_e32 v73, v73, v73
	v_add_f32_e32 v183, 1.0, v207
	v_add_f32_e32 v192, 1.0, v66
	v_rcp_f32_e32 v195, v190
	v_rcp_f32_e32 v190, v64
	v_add_f32_e32 v64, 1.0, v78
	v_exp_f32_e32 v74, v74
	v_min_f32_e32 v73, 0x42c80000, v73
	v_max_f32_e32 v72, v72, v72
	v_add_f32_e32 v194, 1.0, v69
	v_rcp_f32_e32 v193, v183
	v_rcp_f32_e32 v197, v192
	v_rcp_f32_e32 v192, v64
	v_add_f32_e32 v64, 1.0, v77
	v_exp_f32_e32 v73, v73
	v_min_f32_e32 v72, 0x42c80000, v72
	v_add_f32_e32 v196, 1.0, v68
	v_rcp_f32_e32 v199, v194
	v_rcp_f32_e32 v194, v64
	v_add_f32_e32 v64, 1.0, v76
	v_exp_f32_e32 v72, v72
	v_rcp_f32_e32 v209, v196
	v_rcp_f32_e32 v196, v64
	v_add_f32_e32 v64, 1.0, v75
	v_rcp_f32_e32 v198, v64
	v_add_f32_e32 v64, 1.0, v74
	v_rcp_f32_e32 v208, v64
	v_add_f32_e32 v64, 1.0, v73
	v_mul_f32_e32 v214, v190, v192
	v_mul_f32_e32 v215, v191, v193
	v_rcp_f32_e32 v210, v64
	v_add_f32_e32 v64, 1.0, v72
	v_mul_f32_e32 v216, v194, v214
	v_mul_f32_e32 v217, v195, v215
	v_rcp_f32_e32 v212, v64
	v_mul_f32_e32 v218, v196, v216
	v_mul_f32_e32 v219, v197, v217
	v_mov_b32_e32 v230, v213
	v_mul_f32_e32 v220, v198, v218
	v_mul_f32_e32 v221, v199, v219
	v_mov_b32_e32 v231, v211
	v_mul_f32_e32 v222, v208, v220
	v_mul_f32_e32 v223, v209, v221
	v_mul_f32_e32 v70, v70, v230
	v_mul_f32_e32 v71, v71, v231
	v_mul_f32_e32 v224, v210, v222
	v_mul_f32_e32 v225, v211, v223
	v_mov_b32_e32 v231, v223
	v_mul_f32_e32 v226, v212, v224
	v_mul_f32_e32 v227, v213, v225
	ds_bpermute_b32 v228, v181, v226
	ds_bpermute_b32 v229, v181, v227
	v_mov_b32_e32 v230, v225
	v_mul_f32_e32 v70, v70, v230
	v_mul_f32_e32 v71, v71, v231
	v_mov_b32_e32 v230, v209
	v_mov_b32_e32 v231, v199
	v_mul_f32_e32 v68, v68, v230
	v_mul_f32_e32 v69, v69, v231
	v_mov_b32_e32 v230, v221
	v_mov_b32_e32 v231, v219
	v_mul_f32_e32 v68, v68, v230
	v_mul_f32_e32 v69, v69, v231
	v_mov_b32_e32 v230, v197
	v_mov_b32_e32 v231, v195
	s_waitcnt lgkmcnt(1)
	v_cndmask_b32_e64 v183, 1.0, v228, s[4:5]
	s_waitcnt lgkmcnt(0)
	v_mul_f32_e32 v226, v226, v228
	v_mul_f32_e32 v227, v227, v229
	v_mul_f32_e32 v66, v66, v230
	v_mul_f32_e32 v67, v67, v231
	v_mov_b32_e32 v230, v217
	v_mov_b32_e32 v231, v215
	v_mul_f32_e32 v64, v207, v193
	v_mul_f32_e32 v78, v78, v192
	v_mul_f32_e32 v192, v188, v183
	v_mul_f32_e32 v183, v188, v226
	v_cndmask_b32_e64 v193, 1.0, v229, s[4:5]
	v_mul_f32_e32 v66, v66, v230
	v_mul_f32_e32 v67, v67, v231
	v_mov_b32_e32 v230, v191
	v_mul_f32_e32 v228, v193, v183
	v_mul_f32_e32 v64, v230, v64
	v_mul_f32_e32 v65, v230, v65
	v_mov_b32_e32 v213, v210
	v_mul_f32_e32 v70, v70, v228
	v_mul_f32_e32 v71, v71, v228
	v_mul_f32_e32 v68, v68, v228
	v_mul_f32_e32 v69, v69, v228
	v_mul_f32_e32 v66, v66, v228
	v_mul_f32_e32 v67, v67, v228
	v_mul_f32_e32 v229, v65, v228
	v_mul_f32_e32 v228, v64, v228
	v_mul_f32_e32 v64, v72, v212
	v_mul_f32_e32 v65, v73, v213
	v_mov_b32_e32 v225, v222
	v_mul_f32_e32 v64, v64, v224
	v_mul_f32_e32 v65, v65, v225
	v_cvt_pk_bf16_f32 v66, v66, v67
	v_mul_f32_e32 v72, v192, v64
	v_mul_f32_e32 v73, v192, v65
	v_cvt_pk_bf16_f32 v64, v70, v71
	v_cvt_pk_bf16_f32 v65, v68, v69
	v_cvt_pk_bf16_f32 v67, v228, v229
	v_mov_b32_e32 v209, v198
	v_mov_b32_e32 v197, v194
	v_mfma_f32_32x32x16_bf16 v[48:63], v[124:127], v[64:67], v[48:63]
	v_mul_f32_e64 v74, v74, v208
	v_mul_f32_e64 v75, v75, v209
	v_mov_b32_e32 v221, v218
	v_mul_f32_e64 v70, v76, v196
	v_mul_f32_e64 v71, v77, v197
	v_mov_b32_e32 v217, v214
	v_mul_f32_e32 v68, v74, v220
	v_mul_f32_e32 v69, v75, v221
	v_mul_f32_e32 v70, v70, v216
	v_mul_f32_e32 v71, v71, v217
	v_mul_f32_e32 v68, v192, v68
	v_mul_f32_e32 v69, v192, v69
	v_mfma_f32_32x32x16_bf16 v[32:47], v[120:123], v[64:67], v[32:47]
	v_mul_f32_e64 v64, v190, v78
	v_mul_f32_e64 v65, v190, v79
	v_mul_f32_e64 v66, v192, v70
	v_mul_f32_e64 v67, v192, v71
	v_mul_f32_e64 v70, v192, v64
	v_mul_f32_e64 v71, v192, v65
	v_cvt_pk_bf16_f32 v64, v72, v73
	v_cvt_pk_bf16_f32 v65, v68, v69
	v_cvt_pk_bf16_f32 v66, v66, v67
	v_cvt_pk_bf16_f32 v67, v70, v71
	v_mul_f32_e32 v68, v188, v227
	v_mul_f32_e32 v188, v226, v68
	v_mfma_f32_32x32x16_bf16 v[48:63], v[116:119], v[64:67], v[48:63]
	v_mfma_f32_32x32x16_bf16 v[32:47], v[112:115], v[64:67], v[32:47]
; #define MFMA32(a, b, c) __builtin_amdgcn_mfma_f32_32x32x16_bf16((a), (b), (c), 0, 0, 0)
; DI f32x16 qk_mma(const KFrag& f, const bf16x8 (&qf)[4]) {
;     f32x16 st;
; #pragma unroll
;     for (int i = 0; i < 16; ++i) st[i] = 0.f;
; #pragma unroll
;     for (int s = 0; s < 4; ++s) st = MFMA32(f.k[s], qf[s], st);
;     return st;
; }
; template <bool DIAG> DI void sb_tile(const KFrag& kf, const VFrag& vf, const bf16x8 (&qf)[4], float& F, f32x16& o0, f32x16& o1, int r, int hh) {
;     const f32x16 st = qk_mma(kf, qf);
;     f32x16 w; float M[2];
; #pragma unroll
;     for (int run = 0; run < 2; ++run) {
;         float E = 1.f;
; #pragma unroll
;         for (int e = 7; e >= 0; --e) { const int i = 8 * run + e;
;             const float ex = __builtin_amdgcn_exp2f(__builtin_fminf(st[i], 100.f));
;             float sc = __builtin_amdgcn_rcpf(1.0f + ex), beta = ex * sc;
;             if (DIAG) { if (e + 8 * hh + 16 * run >= r) { sc = 1.f; beta = 0.f; } }
;             w[i] = beta * E; E *= sc; }
;         M[run] = E;
;     }
;     const float P0 = __shfl_xor(M[0], 32), P1 = __shfl_xor(M[1], 32);
;     const float off1 = F * (hh == 0 ? P1 : 1.f);
;     const float off0 = F * (M[1] * P1) * (hh == 0 ? P0 : 1.f);
;     F = F * (M[0] * P0) * (M[1] * P1);
; #pragma unroll
;     for (int i = 0; i < 16; ++i) w[i] *= (i < 8 ? off0 : off1);
;     pv_mma(vf, w, o0, o1);
; }
.LBB0_409:
	s_andn2_b64 vcc, exec, s[8:9]
	s_cbranch_vccnz .LBB0_411
	v_mfma_f32_32x32x16_bf16 v[64:79], v[140:143], v[80:83], 0
	v_mfma_f32_32x32x16_bf16 v[64:79], v[136:139], v[84:87], v[64:79]
	v_mfma_f32_32x32x16_bf16 v[64:79], v[132:135], v[88:91], v[64:79]
	v_mfma_f32_32x32x16_bf16 v[64:79], v[128:131], v[92:95], v[64:79]
	s_nop 11
	v_max_f32_e32 v71, v71, v71
	v_max_f32_e32 v65, v65, v65
	v_min_f32_e32 v71, 0x42c80000, v71
	v_max_f32_e32 v70, v70, v70
	v_max_f32_e32 v64, v64, v64
	v_min_f32_e32 v130, 0x42c80000, v65
	v_exp_f32_e32 v65, v71
	v_min_f32_e32 v70, 0x42c80000, v70
	v_min_f32_e32 v64, 0x42c80000, v64
	v_exp_f32_e32 v71, v130
	v_max_f32_e32 v79, v79, v79
	v_max_f32_e32 v69, v69, v69
	v_exp_f32_e32 v183, v70
	v_exp_f32_e32 v70, v64
	v_min_f32_e32 v79, 0x42c80000, v79
	v_max_f32_e32 v78, v78, v78
	v_max_f32_e32 v68, v68, v68
	v_max_f32_e32 v67, v67, v67
	v_max_f32_e32 v66, v66, v66
	v_min_f32_e32 v69, 0x42c80000, v69
	v_exp_f32_e32 v79, v79
	v_min_f32_e32 v78, 0x42c80000, v78
	v_max_f32_e32 v77, v77, v77
	v_min_f32_e32 v68, 0x42c80000, v68
	v_min_f32_e32 v128, 0x42c80000, v67
	v_min_f32_e32 v129, 0x42c80000, v66
	v_exp_f32_e32 v67, v69
	v_add_f32_e32 v64, 1.0, v65
	v_exp_f32_e32 v78, v78
	v_min_f32_e32 v77, 0x42c80000, v77
	v_max_f32_e32 v76, v76, v76
	v_exp_f32_e32 v66, v68
	v_exp_f32_e32 v68, v129
	v_rcp_f32_e32 v129, v64
	v_add_f32_e32 v64, 1.0, v71
	v_exp_f32_e32 v77, v77
	v_min_f32_e32 v76, 0x42c80000, v76
	v_max_f32_e32 v75, v75, v75
	v_exp_f32_e32 v69, v128
	v_rcp_f32_e32 v141, v64
	v_add_f32_e32 v64, 1.0, v70
	v_exp_f32_e32 v76, v76
	v_min_f32_e32 v75, 0x42c80000, v75
	v_max_f32_e32 v74, v74, v74
	v_add_f32_e32 v128, 1.0, v183
	v_rcp_f32_e32 v143, v64
	v_add_f32_e32 v64, 1.0, v79
	v_exp_f32_e32 v75, v75
	v_min_f32_e32 v74, 0x42c80000, v74
	v_max_f32_e32 v73, v73, v73
	v_add_f32_e32 v130, 1.0, v67
	v_rcp_f32_e32 v131, v128
	v_rcp_f32_e32 v128, v64
	v_add_f32_e32 v64, 1.0, v78
	v_exp_f32_e32 v74, v74
	v_min_f32_e32 v73, 0x42c80000, v73
	v_max_f32_e32 v72, v72, v72
	v_add_f32_e32 v132, 1.0, v66
	v_rcp_f32_e32 v133, v130
	v_rcp_f32_e32 v130, v64
	v_add_f32_e32 v64, 1.0, v77
	v_exp_f32_e32 v73, v73
	v_min_f32_e32 v72, 0x42c80000, v72
	v_add_f32_e32 v134, 1.0, v69
	v_rcp_f32_e32 v135, v132
	v_rcp_f32_e32 v132, v64
	v_add_f32_e32 v64, 1.0, v76
	v_exp_f32_e32 v72, v72
	v_add_f32_e32 v136, 1.0, v68
	v_rcp_f32_e32 v137, v134
	v_rcp_f32_e32 v134, v64
	v_add_f32_e32 v64, 1.0, v75
	v_rcp_f32_e32 v139, v136
	v_rcp_f32_e32 v136, v64
	v_add_f32_e32 v64, 1.0, v74
	v_rcp_f32_e32 v138, v64
	v_add_f32_e32 v64, 1.0, v73
	v_mul_f32_e32 v190, v128, v130
	v_mul_f32_e32 v191, v129, v131
	v_rcp_f32_e32 v140, v64
	v_add_f32_e32 v64, 1.0, v72
	v_mul_f32_e32 v192, v132, v190
	v_mul_f32_e32 v193, v133, v191
	v_rcp_f32_e32 v142, v64
	v_mul_f32_e32 v194, v134, v192
	v_mul_f32_e32 v195, v135, v193
	v_mov_b32_e32 v214, v143
	v_mul_f32_e32 v196, v136, v194
	v_mul_f32_e32 v197, v137, v195
	v_mov_b32_e32 v215, v141
	v_mul_f32_e32 v198, v138, v196
	v_mul_f32_e32 v199, v139, v197
	v_mul_f32_e32 v70, v70, v214
	v_mul_f32_e32 v71, v71, v215
	v_mul_f32_e32 v208, v140, v198
	v_mul_f32_e32 v209, v141, v199
	v_mov_b32_e32 v215, v199
	v_mul_f32_e32 v210, v142, v208
	v_mul_f32_e32 v211, v143, v209
	ds_bpermute_b32 v212, v181, v210
	ds_bpermute_b32 v213, v181, v211
	v_mov_b32_e32 v214, v209
	v_mul_f32_e32 v70, v70, v214
	v_mul_f32_e32 v71, v71, v215
	v_mov_b32_e32 v214, v139
	v_mov_b32_e32 v215, v137
	v_mul_f32_e32 v68, v68, v214
	v_mul_f32_e32 v69, v69, v215
	v_mov_b32_e32 v214, v197
	v_mov_b32_e32 v215, v195
	v_mul_f32_e32 v68, v68, v214
	v_mul_f32_e32 v69, v69, v215
	v_mov_b32_e32 v214, v135
	v_mov_b32_e32 v215, v133
	s_waitcnt lgkmcnt(0)
	v_mul_f32_e32 v210, v210, v212
	v_mul_f32_e32 v211, v211, v213
	v_mul_f32_e32 v66, v66, v214
	v_mul_f32_e32 v67, v67, v215
	v_mov_b32_e32 v214, v193
	v_mov_b32_e32 v215, v191
	v_mul_f32_e32 v64, v183, v131
	v_mul_f32_e32 v131, v189, v210
	v_cndmask_b32_e64 v183, 1.0, v213, s[4:5]
	v_mul_f32_e32 v66, v66, v214
	v_mul_f32_e32 v67, v67, v215
	v_mov_b32_e32 v214, v129
	v_mul_f32_e32 v78, v78, v130
	v_cndmask_b32_e64 v130, 1.0, v212, s[4:5]
	v_mul_f32_e32 v212, v183, v131
	v_mul_f32_e32 v64, v214, v64
	v_mul_f32_e32 v65, v214, v65
	v_mov_b32_e32 v143, v140
	v_mul_f32_e32 v70, v70, v212
	v_mul_f32_e32 v71, v71, v212
	v_mul_f32_e32 v68, v68, v212
	v_mul_f32_e32 v69, v69, v212
	v_mul_f32_e32 v66, v66, v212
	v_mul_f32_e32 v67, v67, v212
	v_mul_f32_e32 v213, v65, v212
	v_mul_f32_e32 v212, v64, v212
	v_mul_f32_e32 v64, v72, v142
	v_mul_f32_e32 v65, v73, v143
	v_mov_b32_e32 v209, v198
	v_mul_f32_e32 v130, v189, v130
	v_mul_f32_e32 v64, v64, v208
	v_mul_f32_e32 v65, v65, v209
	v_cvt_pk_bf16_f32 v66, v66, v67
	v_mul_f32_e32 v72, v130, v64
	v_mul_f32_e32 v73, v130, v65
	v_cvt_pk_bf16_f32 v64, v70, v71
	v_cvt_pk_bf16_f32 v65, v68, v69
	v_cvt_pk_bf16_f32 v67, v212, v213
	v_mov_b32_e32 v139, v136
	v_mov_b32_e32 v135, v132
	v_mfma_f32_32x32x16_bf16 v[16:31], v[124:127], v[64:67], v[16:31]
	v_mul_f32_e64 v74, v74, v138
	v_mul_f32_e64 v75, v75, v139
	v_mov_b32_e32 v197, v194
	v_mul_f32_e64 v70, v76, v134
	v_mul_f32_e64 v71, v77, v135
	v_mov_b32_e32 v193, v190
	v_mul_f32_e32 v68, v74, v196
	v_mul_f32_e32 v69, v75, v197
	v_mul_f32_e32 v70, v70, v192
	v_mul_f32_e32 v71, v71, v193
	v_mul_f32_e32 v68, v130, v68
	v_mul_f32_e32 v69, v130, v69
	v_mfma_f32_32x32x16_bf16 v[0:15], v[120:123], v[64:67], v[0:15]
	v_mul_f32_e64 v64, v128, v78
	v_mul_f32_e64 v65, v128, v79
	v_mul_f32_e64 v66, v130, v70
	v_mul_f32_e64 v67, v130, v71
	v_mul_f32_e64 v70, v130, v64
	v_mul_f32_e64 v71, v130, v65
	v_cvt_pk_bf16_f32 v64, v72, v73
	v_cvt_pk_bf16_f32 v65, v68, v69
	v_cvt_pk_bf16_f32 v66, v66, v67
	v_cvt_pk_bf16_f32 v67, v70, v71
	v_mul_f32_e32 v68, v189, v211
	v_mul_f32_e32 v189, v210, v68
	v_mfma_f32_32x32x16_bf16 v[16:31], v[116:119], v[64:67], v[16:31]
	v_mfma_f32_32x32x16_bf16 v[0:15], v[112:115], v[64:67], v[0:15]

; DI unsigned pk_bf16(float lo, float hi) { f32x2 v = {lo, hi}; bf2_t b = __builtin_convertvector(v, bf2_t); return __builtin_bit_cast(unsigned, b); }
; DI float bf_lo(unsigned u) { return __uint_as_float(u << 16); }
; DI float bf_hi(unsigned u) { return __uint_as_float(u & 0xffff0000u); }
; DI float silu(float x) { return x * __builtin_amdgcn_rcpf(1.0f + __builtin_amdgcn_exp2f(-1.4426950408889634f * x)); }
; DI void store_head(const f32x16& o0, const f32x16& o1, float rs, const unsigned char* gl, int tr, int ch0, const float* gs, bf16_t* yp) {
;     u32x2 gt[8]; f32x4 gv[8];
; #pragma unroll
;     for (int q = 0; q < 8; ++q) { const int d = 32 * (q >> 2) + 8 * (q & 3); gt[q] = *(const u32x2*)(gl + gate_off(tr, ch0 + d)); gv[q] = *(const f32x4*)(gs + d); }
; #pragma unroll
;     for (int q = 0; q < 8; ++q) { const int d = 32 * (q >> 2) + 8 * (q & 3), g = q & 3;
;         const f32x16& o = (q >> 2) ? o1 : o0;
;         u32x2 w; w.x = pk_bf16(o[4 * g + 0] * rs * gv[q][0] * silu(bf_lo(gt[q].x)), o[4 * g + 1] * rs * gv[q][1] * silu(bf_hi(gt[q].x)));
;         w.y = pk_bf16(o[4 * g + 2] * rs * gv[q][2] * silu(bf_lo(gt[q].y)), o[4 * g + 3] * rs * gv[q][3] * silu(bf_hi(gt[q].y)));
;         *(u32x2*)(yp + d) = w; }
; DI void mixer_phase(const Params& p, unsigned char* ldsraw, int vid) {
;     ...
;             asm volatile("s_waitcnt vmcnt(0)" ::: "memory");
;             __syncthreads();
;             float totA = 0.f, totB = 0.f;
; #pragma unroll
;             for (int w8 = 0; w8 < 8; ++w8) { totA += lf[w8 * 32 + r]; totB += lf[256 + w8 * 32 + r]; }
;             const float* gs = p.g_sb + 64 * wid + 4 * hh;
;             store_head(oA0, oA1, rsqrtf(totA * (1.0f / 512.0f) + EPS), gl, r, 64 * wid + 4 * hh, gs, Y + (size_t)tqA * 1024 + 64 * wid + 4 * hh);
;             store_head(oB0, oB1, rsqrtf(totB * (1.0f / 512.0f) + EPS), gl, r + 32, 64 * wid + 4 * hh, gs, Y + (size_t)tqB * 1024 + 64 * wid + 4 * hh);
.LBB0_414:
	s_or_b64 exec, exec, s[0:1]
	v_lshlrev_b32_e32 v144, 2, v176
	v_add_u32_e32 v158, s74, v144
	v_add_u32_e32 v70, 16, v158
	v_and_b32_e32 v160, 15, v205
	v_lshlrev_b32_e32 v71, 1, v70
	v_lshrrev_b32_e32 v70, 3, v70
	v_or_b32_e32 v96, s38, v206
	v_lshl_add_u32 v161, v206, 2, 0
	v_bitop3_b32 v70, v70, v160, 63 bitop3:0x6c
	v_add_u32_e32 v64, 0x400, v161
	v_ashrrev_i32_e32 v97, 31, v96
	v_and_b32_e32 v72, 0xfffffc00, v71
	v_lshlrev_b32_e32 v70, 4, v70
	v_and_b32_e32 v138, 8, v71
	v_add_u32_e32 v71, 24, v158
	s_waitcnt vmcnt(0)
	s_waitcnt lgkmcnt(0)
	s_barrier
	ds_read2_b32 v[102:103], v161 offset1:32
	ds_read2_b32 v[110:111], v64 offset1:32
	ds_read2_b32 v[108:109], v161 offset0:64 offset1:96
	ds_read2_b32 v[112:113], v64 offset0:64 offset1:96
	ds_read2_b32 v[106:107], v161 offset0:128 offset1:160
	ds_read2_b32 v[114:115], v64 offset0:128 offset1:160
	ds_read2_b32 v[104:105], v161 offset0:192 offset1:224
	ds_read2_b32 v[116:117], v64 offset0:192 offset1:224
	v_ashrrev_i32_e32 v145, 31, v144
	v_lshlrev_b64 v[64:65], 11, v[96:97]
	v_add3_u32 v139, 0, v70, v72
	v_lshlrev_b32_e32 v72, 1, v71
	v_lshrrev_b32_e32 v71, 3, v71
	v_lshl_add_u64 v[64:65], s[80:81], 0, v[64:65]
	v_lshlrev_b64 v[100:101], 1, v[144:145]
	v_lshrrev_b32_e32 v66, 3, v158
	v_bitop3_b32 v71, v71, v160, 63 bitop3:0x6c
	v_lshl_add_u64 v[140:141], v[64:65], 0, v[100:101]
	v_lshlrev_b32_e32 v64, 1, v158
	v_bitop3_b32 v66, v66, v160, 63 bitop3:0x6c
	v_and_b32_e32 v73, 0xfffffc00, v72
	v_lshlrev_b32_e32 v71, 4, v71
	v_and_b32_e32 v146, 8, v72
	v_add_u32_e32 v72, 32, v158
	v_and_b32_e32 v65, 0xfffffc00, v64
	v_lshlrev_b32_e32 v66, 4, v66
	v_and_b32_e32 v134, 8, v64
	v_add_u32_e32 v64, 8, v158
	v_add3_u32 v147, 0, v71, v73
	v_lshlrev_b32_e32 v73, 1, v72
	v_lshrrev_b32_e32 v72, 3, v72
	v_add_u32_e32 v90, 48, v158
	v_add3_u32 v135, 0, v66, v65
	v_lshlrev_b32_e32 v65, 1, v64
	v_lshrrev_b32_e32 v64, 3, v64
	v_bitop3_b32 v72, v72, v160, 63 bitop3:0x6c
	v_lshlrev_b32_e32 v91, 1, v90
	v_lshrrev_b32_e32 v90, 3, v90
	v_bitop3_b32 v64, v64, v160, 63 bitop3:0x6c
	v_and_b32_e32 v74, 0xfffffc00, v73
	v_lshlrev_b32_e32 v72, 4, v72
	v_bitop3_b32 v90, v90, v160, 63 bitop3:0x6c
	v_lshlrev_b32_e32 v159, 11, v206
	v_and_b32_e32 v66, 0xfffffc00, v65
	v_lshlrev_b32_e32 v64, 4, v64
	v_add3_u32 v149, 0, v72, v74
	v_add_u32_e32 v72, 40, v158
	v_and_b32_e32 v92, 0xfffffc00, v91
	v_lshlrev_b32_e32 v90, 4, v90
	v_and_b32_e32 v152, 8, v91
	v_add_u32_e32 v91, 56, v158
	v_lshl_add_u64 v[98:99], v[144:145], 2, s[56:57]
	v_add3_u32 v68, v135, v159, v134
	v_and_b32_e32 v136, 8, v65
	v_add3_u32 v137, 0, v64, v66
	v_and_b32_e32 v148, 8, v73
	v_lshlrev_b32_e32 v73, 1, v72
	v_lshrrev_b32_e32 v72, 3, v72
	v_add3_u32 v153, 0, v90, v92
	v_lshlrev_b32_e32 v92, 1, v91
	v_lshrrev_b32_e32 v91, 3, v91
	v_add3_u32 v69, v137, v159, v136
	global_load_dwordx4 v[76:79], v[98:99], off
	global_load_dwordx4 v[64:67], v[98:99], off offset:32
	v_add3_u32 v70, v139, v159, v138
	v_add3_u32 v71, v147, v159, v146
	ds_read_b64 v[118:119], v68 offset:4096
	ds_read_b64 v[124:125], v69 offset:4096
	ds_read_b64 v[128:129], v70 offset:4096
	ds_read_b64 v[142:143], v71 offset:4096
	v_bitop3_b32 v72, v72, v160, 63 bitop3:0x6c
	v_bitop3_b32 v91, v91, v160, 63 bitop3:0x6c
	v_and_b32_e32 v74, 0xfffffc00, v73
	v_lshlrev_b32_e32 v72, 4, v72
	v_and_b32_e32 v93, 0xfffffc00, v92
	v_lshlrev_b32_e32 v91, 4, v91
	v_add3_u32 v88, v149, v159, v148
	v_and_b32_e32 v150, 8, v73
	v_add3_u32 v151, 0, v72, v74
	v_and_b32_e32 v154, 8, v92
	v_add3_u32 v155, 0, v91, v93
	s_waitcnt lgkmcnt(3)
	v_lshlrev_b32_e32 v120, 16, v118
	global_load_dwordx4 v[80:83], v[98:99], off offset:64
	global_load_dwordx4 v[68:71], v[98:99], off offset:96
	v_add3_u32 v89, v151, v159, v150
	global_load_dwordx4 v[84:87], v[98:99], off offset:128
	global_load_dwordx4 v[72:75], v[98:99], off offset:160
	v_add3_u32 v90, v153, v159, v152
	v_add3_u32 v91, v155, v159, v154
	ds_read_b64 v[156:157], v88 offset:4096
	ds_read_b64 v[162:163], v89 offset:4096
	ds_read_b64 v[130:131], v90 offset:4096
	ds_read_b64 v[122:123], v91 offset:4096
	v_and_b32_e32 v121, 0xffff0000, v118
	v_mul_f32_e32 v88, 0xbfb8aa3b, v120
	v_exp_f32_e32 v118, v88
	v_mul_f32_e32 v88, 0xbfb8aa3b, v121
	v_exp_f32_e32 v127, v88
	v_lshlrev_b32_e32 v132, 16, v119
	v_add_f32_e32 v118, 1.0, v118
	v_rcp_f32_e32 v126, v118
	v_add_f32_e32 v118, 1.0, v127
	v_rcp_f32_e32 v127, v118
	v_and_b32_e32 v133, 0xffff0000, v119
	v_mul_f32_e32 v118, 0xbfb8aa3b, v132
	v_exp_f32_e32 v164, v118
	v_mul_f32_e32 v118, 0xbfb8aa3b, v133
	v_exp_f32_e32 v165, v118
	v_mul_f32_e32 v118, v126, v120
	v_mul_f32_e32 v119, v127, v121
	s_waitcnt lgkmcnt(6)
	v_lshlrev_b32_e32 v126, 16, v124
	v_and_b32_e32 v127, 0xffff0000, v124
	v_mul_f32_e32 v124, 0xbfb8aa3b, v126
	v_add_f32_e32 v120, 1.0, v164
	v_add_f32_e32 v121, 1.0, v165
	v_exp_f32_e32 v124, v124
	v_mul_f32_e32 v164, 0xbfb8aa3b, v127
	v_rcp_f32_e32 v120, v120
	v_rcp_f32_e32 v121, v121
	v_exp_f32_e32 v164, v164
	v_add_f32_e32 v124, 1.0, v124
	v_and_b32_e32 v165, 0xffff0000, v125
	v_mul_f32_e32 v120, v120, v132
	v_mul_f32_e32 v121, v121, v133
	v_rcp_f32_e32 v132, v124
	v_add_f32_e32 v124, 1.0, v164
	v_lshlrev_b32_e32 v164, 16, v125
	v_rcp_f32_e32 v133, v124
	v_mul_f32_e32 v124, 0xbfb8aa3b, v164
	v_exp_f32_e32 v166, v124
	v_mul_f32_e32 v124, 0xbfb8aa3b, v165
	global_load_dwordx4 v[92:95], v[98:99], off offset:192
	global_load_dwordx4 v[88:91], v[98:99], off offset:224
	v_exp_f32_e32 v167, v124
	v_mul_f32_e32 v124, v132, v126
	v_mul_f32_e32 v125, v133, v127
	s_waitcnt lgkmcnt(5)
; DI unsigned pk_bf16(float lo, float hi) { f32x2 v = {lo, hi}; bf2_t b = __builtin_convertvector(v, bf2_t); return __builtin_bit_cast(unsigned, b); }
; DI float bf_lo(unsigned u) { return __uint_as_float(u << 16); }
; DI float bf_hi(unsigned u) { return __uint_as_float(u & 0xffff0000u); }
; DI float silu(float x) { return x * __builtin_amdgcn_rcpf(1.0f + __builtin_amdgcn_exp2f(-1.4426950408889634f * x)); }
; DI void store_head(const f32x16& o0, const f32x16& o1, float rs, const unsigned char* gl, int tr, int ch0, const float* gs, bf16_t* yp) {
;     u32x2 gt[8]; f32x4 gv[8];
; #pragma unroll
;     for (int q = 0; q < 8; ++q) { const int d = 32 * (q >> 2) + 8 * (q & 3); gt[q] = *(const u32x2*)(gl + gate_off(tr, ch0 + d)); gv[q] = *(const f32x4*)(gs + d); }
; #pragma unroll
;     for (int q = 0; q < 8; ++q) { const int d = 32 * (q >> 2) + 8 * (q & 3), g = q & 3;
;         const f32x16& o = (q >> 2) ? o1 : o0;
;         u32x2 w; w.x = pk_bf16(o[4 * g + 0] * rs * gv[q][0] * silu(bf_lo(gt[q].x)), o[4 * g + 1] * rs * gv[q][1] * silu(bf_hi(gt[q].x)));
;         w.y = pk_bf16(o[4 * g + 2] * rs * gv[q][2] * silu(bf_lo(gt[q].y)), o[4 * g + 3] * rs * gv[q][3] * silu(bf_hi(gt[q].y)));
;         *(u32x2*)(yp + d) = w; }
; DI void mixer_phase(const Params& p, unsigned char* ldsraw, int vid) {
;     ...
;             float totA = 0.f, totB = 0.f;
; #pragma unroll
;             for (int w8 = 0; w8 < 8; ++w8) { totA += lf[w8 * 32 + r]; totB += lf[256 + w8 * 32 + r]; }
;             const float* gs = p.g_sb + 64 * wid + 4 * hh;
;             store_head(oA0, oA1, rsqrtf(totA * (1.0f / 512.0f) + EPS), gl, r, 64 * wid + 4 * hh, gs, Y + (size_t)tqA * 1024 + 64 * wid + 4 * hh);
;             store_head(oB0, oB1, rsqrtf(totB * (1.0f / 512.0f) + EPS), gl, r + 32, 64 * wid + 4 * hh, gs, Y + (size_t)tqB * 1024 + 64 * wid + 4 * hh);
	v_lshlrev_b32_e32 v132, 16, v128
	v_and_b32_e32 v133, 0xffff0000, v128
	v_mul_f32_e32 v128, 0xbfb8aa3b, v132
	v_add_f32_e32 v126, 1.0, v166
	v_add_f32_e32 v127, 1.0, v167
	v_exp_f32_e32 v128, v128
	v_mul_f32_e32 v166, 0xbfb8aa3b, v133
	v_rcp_f32_e32 v126, v126
	v_rcp_f32_e32 v127, v127
	v_exp_f32_e32 v166, v166
	v_add_f32_e32 v128, 1.0, v128
	v_and_b32_e32 v167, 0xffff0000, v129
	v_mul_f32_e32 v126, v126, v164
	v_mul_f32_e32 v127, v127, v165
	v_rcp_f32_e32 v164, v128
	v_add_f32_e32 v128, 1.0, v166
	v_lshlrev_b32_e32 v166, 16, v129
	v_rcp_f32_e32 v165, v128
	v_mul_f32_e32 v128, 0xbfb8aa3b, v166
	v_exp_f32_e32 v168, v128
	v_mul_f32_e32 v128, 0xbfb8aa3b, v167
	v_exp_f32_e32 v169, v128
	v_mul_f32_e32 v128, v164, v132
	v_mul_f32_e32 v129, v165, v133
	s_waitcnt lgkmcnt(4)
	v_lshlrev_b32_e32 v164, 16, v142
	v_and_b32_e32 v165, 0xffff0000, v142
	v_mul_f32_e32 v142, 0xbfb8aa3b, v164
	v_add_f32_e32 v132, 1.0, v168
	v_add_f32_e32 v133, 1.0, v169
	v_exp_f32_e32 v142, v142
	v_mul_f32_e32 v168, 0xbfb8aa3b, v165
	v_rcp_f32_e32 v132, v132
	v_rcp_f32_e32 v133, v133
	v_exp_f32_e32 v168, v168
	v_add_f32_e32 v142, 1.0, v142
	v_mov_b32_e32 v188, v110
	v_mul_f32_e32 v132, v132, v166
	v_mul_f32_e32 v133, v133, v167
	v_rcp_f32_e32 v166, v142
	v_add_f32_e32 v142, 1.0, v168
	v_rcp_f32_e32 v167, v142
	v_lshlrev_b32_e32 v142, 16, v143
	v_and_b32_e32 v143, 0xffff0000, v143
	v_mul_f32_e32 v168, 0xbfb8aa3b, v142
	v_exp_f32_e32 v168, v168
	v_mul_f32_e32 v169, 0xbfb8aa3b, v143
	v_exp_f32_e32 v169, v169
	v_mul_f32_e32 v164, v166, v164
	v_mul_f32_e32 v165, v167, v165
	v_add_f32_e32 v166, 1.0, v168
	s_waitcnt lgkmcnt(3)
	v_lshlrev_b32_e32 v168, 16, v156
	v_add_f32_e32 v167, 1.0, v169
	v_and_b32_e32 v169, 0xffff0000, v156
	v_mul_f32_e32 v156, 0xbfb8aa3b, v168
	v_exp_f32_e32 v156, v156
	v_mul_f32_e32 v170, 0xbfb8aa3b, v169
	v_rcp_f32_e32 v166, v166
	v_rcp_f32_e32 v167, v167
	v_exp_f32_e32 v170, v170
	v_add_f32_e32 v156, 1.0, v156
	v_mov_b32_e32 v189, v102
	v_mul_f32_e32 v142, v166, v142
	v_mul_f32_e32 v143, v167, v143
	v_rcp_f32_e32 v166, v156
	v_add_f32_e32 v156, 1.0, v170
	v_rcp_f32_e32 v167, v156
	v_lshlrev_b32_e32 v156, 16, v157
	v_and_b32_e32 v157, 0xffff0000, v157
	v_mul_f32_e32 v170, 0xbfb8aa3b, v156
	v_exp_f32_e32 v170, v170
	v_mul_f32_e32 v171, 0xbfb8aa3b, v157
	v_exp_f32_e32 v171, v171
	v_mul_f32_e32 v166, v166, v168
	v_mul_f32_e32 v167, v167, v169
	v_add_f32_e32 v168, 1.0, v170
	s_waitcnt lgkmcnt(2)
	v_lshlrev_b32_e32 v170, 16, v162
	v_add_f32_e32 v169, 1.0, v171
	v_and_b32_e32 v171, 0xffff0000, v162
	v_mul_f32_e32 v162, 0xbfb8aa3b, v170
	v_exp_f32_e32 v162, v162
	v_mul_f32_e32 v172, 0xbfb8aa3b, v171
	v_rcp_f32_e32 v168, v168
	v_rcp_f32_e32 v169, v169
	v_exp_f32_e32 v172, v172
	v_add_f32_e32 v162, 1.0, v162
	v_pk_add_f32 v[188:189], v[188:189], 0 op_sel_hi:[1,0]
	v_mul_f32_e32 v156, v168, v156
	v_mul_f32_e32 v157, v169, v157
	v_rcp_f32_e32 v168, v162
	v_add_f32_e32 v162, 1.0, v172
	v_rcp_f32_e32 v169, v162
	v_lshlrev_b32_e32 v162, 16, v163
	v_and_b32_e32 v163, 0xffff0000, v163
	v_mul_f32_e32 v172, 0xbfb8aa3b, v162
	v_exp_f32_e32 v172, v172
	v_mul_f32_e32 v173, 0xbfb8aa3b, v163
	v_exp_f32_e32 v173, v173
	v_mov_b32_e32 v102, v111
	v_add_f32_e32 v102, v188, v102
	v_add_f32_e32 v103, v189, v103
	v_mov_b32_e32 v110, v112
	v_mov_b32_e32 v111, v108
	v_add_f32_e32 v102, v102, v110
	v_add_f32_e32 v103, v103, v111
	v_mov_b32_e32 v108, v113
	v_mul_f32_e32 v168, v168, v170
	v_mul_f32_e32 v169, v169, v171
	v_add_f32_e32 v170, 1.0, v172
	s_waitcnt lgkmcnt(1)
	v_lshlrev_b32_e32 v172, 16, v130
	v_add_f32_e32 v102, v102, v108
	v_add_f32_e32 v103, v103, v109
	v_mov_b32_e32 v108, v114
	v_mov_b32_e32 v109, v106
	v_add_f32_e32 v171, 1.0, v173
	v_and_b32_e32 v173, 0xffff0000, v130
	v_mul_f32_e32 v130, 0xbfb8aa3b, v172
	v_add_f32_e32 v102, v102, v108
	v_add_f32_e32 v103, v103, v109
	v_mov_b32_e32 v106, v115
	v_exp_f32_e32 v130, v130
	v_mul_f32_e32 v174, 0xbfb8aa3b, v173
	v_add_f32_e32 v102, v102, v106
	v_add_f32_e32 v103, v103, v107
	v_mov_b32_e32 v106, v116
	v_mov_b32_e32 v107, v104
	v_rcp_f32_e32 v170, v170
	v_rcp_f32_e32 v171, v171
	v_exp_f32_e32 v174, v174
	v_add_f32_e32 v102, v102, v106
	v_add_f32_e32 v103, v103, v107
	v_mov_b32_e32 v104, v117
	v_add_f32_e32 v102, v102, v104
	v_add_f32_e32 v103, v103, v105
	s_mov_b32 s0, 0x3b000000
	v_fma_f32 v102, v102, s0, v178
	v_fma_f32 v103, v103, s0, v178
	v_add_f32_e32 v130, 1.0, v130
	v_mul_f32_e32 v104, 0x4b800000, v103
	v_cmp_gt_f32_e32 vcc, s98, v103
	v_mul_f32_e32 v162, v170, v162
	v_mul_f32_e32 v163, v171, v163
	v_rcp_f32_e32 v170, v130
	v_add_f32_e32 v130, 1.0, v174
	v_cndmask_b32_e32 v103, v103, v104, vcc
	v_rcp_f32_e32 v171, v130
	v_lshlrev_b32_e32 v130, 16, v131
	v_and_b32_e32 v131, 0xffff0000, v131
	v_rsq_f32_e32 v103, v103
	v_mul_f32_e32 v175, 0xbfb8aa3b, v131
	v_exp_f32_e32 v175, v175
	v_mul_f32_e32 v174, 0xbfb8aa3b, v130
	v_exp_f32_e32 v174, v174
	v_mul_f32_e32 v110, 0x45800000, v103
	v_cndmask_b32_e32 v110, v103, v110, vcc
	v_mul_f32_e32 v170, v170, v172
	v_mul_f32_e32 v171, v171, v173
	v_add_f32_e32 v173, 1.0, v175
	s_waitcnt lgkmcnt(0)
	v_and_b32_e32 v175, 0xffff0000, v122
	v_mul_f32_e32 v48, v48, v110
	v_mul_f32_e32 v49, v49, v110
	v_mul_f32_e32 v50, v50, v110
	v_mul_f32_e32 v51, v51, v110
	v_mul_f32_e32 v32, v32, v110
	v_mul_f32_e32 v33, v33, v110
	v_mul_f32_e32 v34, v34, v110
	v_mul_f32_e32 v35, v35, v110
	v_mul_f32_e32 v176, 0xbfb8aa3b, v175
	v_lshlrev_b32_e32 v184, 16, v123
	s_waitcnt vmcnt(7)
	v_mul_f32_e32 v48, v76, v48
	v_mul_f32_e32 v49, v77, v49
	v_mul_f32_e32 v50, v78, v50
	v_mul_f32_e32 v51, v79, v51
	s_waitcnt vmcnt(3)
; DI unsigned pk_bf16(float lo, float hi) { f32x2 v = {lo, hi}; bf2_t b = __builtin_convertvector(v, bf2_t); return __builtin_bit_cast(unsigned, b); }
; DI float bf_lo(unsigned u) { return __uint_as_float(u << 16); }
; DI float bf_hi(unsigned u) { return __uint_as_float(u & 0xffff0000u); }
; DI float silu(float x) { return x * __builtin_amdgcn_rcpf(1.0f + __builtin_amdgcn_exp2f(-1.4426950408889634f * x)); }
; DI void store_head(const f32x16& o0, const f32x16& o1, float rs, const unsigned char* gl, int tr, int ch0, const float* gs, bf16_t* yp) {
;     u32x2 gt[8]; f32x4 gv[8];
; #pragma unroll
;     for (int q = 0; q < 8; ++q) { const int d = 32 * (q >> 2) + 8 * (q & 3); gt[q] = *(const u32x2*)(gl + gate_off(tr, ch0 + d)); gv[q] = *(const f32x4*)(gs + d); }
; #pragma unroll
;     for (int q = 0; q < 8; ++q) { const int d = 32 * (q >> 2) + 8 * (q & 3), g = q & 3;
;         const f32x16& o = (q >> 2) ? o1 : o0;
;         u32x2 w; w.x = pk_bf16(o[4 * g + 0] * rs * gv[q][0] * silu(bf_lo(gt[q].x)), o[4 * g + 1] * rs * gv[q][1] * silu(bf_hi(gt[q].x)));
;         w.y = pk_bf16(o[4 * g + 2] * rs * gv[q][2] * silu(bf_lo(gt[q].y)), o[4 * g + 3] * rs * gv[q][3] * silu(bf_hi(gt[q].y)));
;         *(u32x2*)(yp + d) = w; }
; DI void mixer_phase(const Params& p, unsigned char* ldsraw, int vid) {
;     ...
;             store_head(oA0, oA1, rsqrtf(totA * (1.0f / 512.0f) + EPS), gl, r, 64 * wid + 4 * hh, gs, Y + (size_t)tqA * 1024 + 64 * wid + 4 * hh);
;             store_head(oB0, oB1, rsqrtf(totB * (1.0f / 512.0f) + EPS), gl, r + 32, 64 * wid + 4 * hh, gs, Y + (size_t)tqB * 1024 + 64 * wid + 4 * hh);
	v_mul_f32_e32 v32, v32, v84
	v_mul_f32_e32 v33, v33, v85
	v_mul_f32_e32 v34, v34, v86
	v_mul_f32_e32 v35, v35, v87
	v_add_f32_e32 v172, 1.0, v174
	v_lshlrev_b32_e32 v174, 16, v122
	v_exp_f32_e32 v176, v176
	v_and_b32_e32 v185, 0xffff0000, v123
	v_mul_f32_e32 v123, 0xbfb8aa3b, v184
	v_mul_f32_e32 v48, v48, v118
	v_mul_f32_e32 v49, v49, v119
	v_mul_f32_e32 v50, v50, v120
	v_mul_f32_e32 v51, v51, v121
	v_mul_f32_e32 v32, v32, v166
	v_mul_f32_e32 v33, v33, v167
	v_mul_f32_e32 v34, v34, v156
	v_mul_f32_e32 v35, v35, v157
	v_mul_f32_e32 v122, 0xbfb8aa3b, v174
	v_exp_f32_e32 v183, v123
	v_mul_f32_e32 v123, 0xbfb8aa3b, v185
	v_cvt_pk_bf16_f32 v236, v48, v49
	v_cvt_pk_bf16_f32 v237, v50, v51
	v_cvt_pk_bf16_f32 v244, v32, v33
	v_cvt_pk_bf16_f32 v245, v34, v35
	v_exp_f32_e32 v122, v122
	v_exp_f32_e32 v187, v123
	v_and_b32_e32 v252, 32, v205
	v_lshrrev_b32_e32 v252, 2, v252
	v_mov_b32_e32 v253, 0
	v_lshl_add_u64 v[254:255], v[140:141], 0, v[252:253]
	v_mul_f32_e32 v48, v52, v110
	v_mul_f32_e32 v49, v53, v110
	v_mul_f32_e32 v50, v54, v110
	v_mul_f32_e32 v51, v55, v110
	v_mul_f32_e32 v32, v36, v110
	v_mul_f32_e32 v33, v37, v110
	v_mul_f32_e32 v34, v38, v110
	v_mul_f32_e32 v35, v39, v110
	v_rcp_f32_e32 v172, v172
	v_rcp_f32_e32 v173, v173
	v_mul_f32_e32 v48, v64, v48
	v_mul_f32_e32 v49, v65, v49
	v_mul_f32_e32 v50, v66, v50
	v_mul_f32_e32 v51, v67, v51
	s_waitcnt vmcnt(2)
	v_mul_f32_e32 v32, v32, v72
	v_mul_f32_e32 v33, v33, v73
	v_mul_f32_e32 v34, v34, v74
	v_mul_f32_e32 v35, v35, v75
	v_add_f32_e32 v176, 1.0, v176
	v_mul_f32_e32 v48, v48, v124
	v_mul_f32_e32 v49, v49, v125
	v_mul_f32_e32 v50, v50, v126
	v_mul_f32_e32 v51, v51, v127
	v_mul_f32_e32 v32, v32, v168
	v_mul_f32_e32 v33, v33, v169
	v_mul_f32_e32 v34, v34, v162
	v_mul_f32_e32 v35, v35, v163
	v_rcp_f32_e32 v123, v176
	v_add_f32_e32 v176, 1.0, v183
	v_cvt_pk_bf16_f32 v238, v48, v49
	v_cvt_pk_bf16_f32 v239, v50, v51
	v_cvt_pk_bf16_f32 v246, v32, v33
	v_cvt_pk_bf16_f32 v247, v34, v35
	v_add_f32_e32 v122, 1.0, v122
	v_rcp_f32_e32 v186, v176
	v_add_f32_e32 v176, 1.0, v187
	s_nop 1
	v_permlane32_swap_b32_e32 v236, v238
	v_permlane32_swap_b32_e32 v237, v239
	global_store_dwordx4 v[254:255], v[236:239], off
	v_mul_f32_e32 v48, v56, v110
	v_mul_f32_e32 v49, v57, v110
	v_mul_f32_e32 v50, v58, v110
	v_mul_f32_e32 v51, v59, v110
	s_nop 1
	v_permlane32_swap_b32_e32 v244, v246
	v_permlane32_swap_b32_e32 v245, v247
	global_store_dwordx4 v[254:255], v[244:247], off offset:64
	v_mul_f32_e32 v32, v40, v110
	v_mul_f32_e32 v33, v41, v110
	v_mul_f32_e32 v34, v42, v110
	v_mul_f32_e32 v35, v43, v110
	v_rcp_f32_e32 v122, v122
	v_rcp_f32_e32 v187, v176
	v_mul_f32_e32 v104, v172, v130
	v_mul_f32_e32 v105, v173, v131
	v_mul_f32_e32 v48, v80, v48
	v_mul_f32_e32 v49, v81, v49
	v_mul_f32_e32 v50, v82, v50
	v_mul_f32_e32 v51, v83, v51
	s_waitcnt vmcnt(3)
	v_mul_f32_e32 v32, v32, v92
	v_mul_f32_e32 v33, v33, v93
	v_mul_f32_e32 v34, v34, v94
	v_mul_f32_e32 v35, v35, v95
	v_mul_f32_e32 v48, v48, v128
	v_mul_f32_e32 v49, v49, v129
	v_mul_f32_e32 v50, v50, v132
	v_mul_f32_e32 v51, v51, v133
	v_mul_f32_e32 v32, v32, v170
	v_mul_f32_e32 v33, v33, v171
	v_mul_f32_e32 v34, v34, v104
	v_mul_f32_e32 v35, v35, v105
	v_cvt_pk_bf16_f32 v240, v48, v49
	v_cvt_pk_bf16_f32 v241, v50, v51
	v_cvt_pk_bf16_f32 v248, v32, v33
	v_cvt_pk_bf16_f32 v249, v34, v35
	v_mul_f32_e32 v48, v60, v110
	v_mul_f32_e32 v49, v61, v110
	v_mul_f32_e32 v50, v62, v110
	v_mul_f32_e32 v51, v63, v110
	v_mul_f32_e32 v32, v44, v110
	v_mul_f32_e32 v33, v45, v110
	v_mul_f32_e32 v34, v46, v110
	v_mul_f32_e32 v35, v47, v110
	v_mul_f32_e32 v106, v122, v174
	v_mul_f32_e32 v107, v123, v175
	v_mul_f32_e32 v108, v186, v184
	v_mul_f32_e32 v109, v187, v185
	v_mul_f32_e32 v48, v48, v68
	v_mul_f32_e32 v49, v49, v69
	v_mul_f32_e32 v50, v50, v70
	v_mul_f32_e32 v51, v51, v71
	s_waitcnt vmcnt(2)
	v_mul_f32_e32 v32, v32, v88
	v_mul_f32_e32 v33, v33, v89
	v_mul_f32_e32 v34, v34, v90
	v_mul_f32_e32 v35, v35, v91
	v_mul_f32_e32 v48, v48, v164
	v_mul_f32_e32 v49, v49, v165
	v_mul_f32_e32 v50, v50, v142
	v_mul_f32_e32 v51, v51, v143
	v_mul_f32_e32 v32, v32, v106
	v_mul_f32_e32 v33, v33, v107
	v_mul_f32_e32 v34, v34, v108
	v_mul_f32_e32 v35, v35, v109
	v_cvt_pk_bf16_f32 v242, v48, v49
	v_cvt_pk_bf16_f32 v243, v50, v51
	v_cvt_pk_bf16_f32 v250, v32, v33
	v_cvt_pk_bf16_f32 v251, v34, v35
	s_nop 1
	v_permlane32_swap_b32_e32 v240, v242
	v_permlane32_swap_b32_e32 v241, v243
	global_store_dwordx4 v[254:255], v[240:243], off offset:32
	s_nop 1
	v_permlane32_swap_b32_e32 v248, v250
	v_permlane32_swap_b32_e32 v249, v251
	global_store_dwordx4 v[254:255], v[248:251], off offset:96
	global_load_dwordx4 v[56:59], v[98:99], off
	global_load_dwordx4 v[60:63], v[98:99], off offset:32
	v_mul_f32_e32 v32, 0x4b800000, v102
	v_cmp_gt_f32_e32 vcc, s98, v102
	v_or_b32_e32 v162, 0x10000, v159
	v_add3_u32 v35, v147, v162, v146
	v_cndmask_b32_e32 v32, v102, v32, vcc
	v_rsq_f32_e32 v33, v32
	v_or_b32_e32 v32, 32, v96
	v_ashrrev_i32_e32 v163, 3, v205
	s_mov_b64 s[0:1], -1
	v_mul_f32_e32 v34, 0x45800000, v33
	v_cndmask_b32_e32 v48, v33, v34, vcc
	v_ashrrev_i32_e32 v33, 31, v32
	v_lshlrev_b64 v[32:33], 11, v[32:33]
	v_lshl_add_u64 v[32:33], s[80:81], 0, v[32:33]
	v_lshl_add_u64 v[142:143], v[32:33], 0, v[100:101]
	v_add3_u32 v32, v135, v162, v134
	v_add3_u32 v33, v137, v162, v136
	v_add3_u32 v34, v139, v162, v138
	ds_read_b64 v[72:73], v32 offset:4096
	ds_read_b64 v[74:75], v33 offset:4096
	ds_read_b64 v[76:77], v34 offset:4096
	ds_read_b64 v[78:79], v35 offset:4096
	global_load_dwordx4 v[64:67], v[98:99], off offset:64
	global_load_dwordx4 v[68:71], v[98:99], off offset:96
	s_waitcnt lgkmcnt(3)
; DI unsigned pk_bf16(float lo, float hi) { f32x2 v = {lo, hi}; bf2_t b = __builtin_convertvector(v, bf2_t); return __builtin_bit_cast(unsigned, b); }
; DI float bf_lo(unsigned u) { return __uint_as_float(u << 16); }
; DI float bf_hi(unsigned u) { return __uint_as_float(u & 0xffff0000u); }
; DI float silu(float x) { return x * __builtin_amdgcn_rcpf(1.0f + __builtin_amdgcn_exp2f(-1.4426950408889634f * x)); }
; DI void store_head(const f32x16& o0, const f32x16& o1, float rs, const unsigned char* gl, int tr, int ch0, const float* gs, bf16_t* yp) {
;     u32x2 gt[8]; f32x4 gv[8];
; #pragma unroll
;     for (int q = 0; q < 8; ++q) { const int d = 32 * (q >> 2) + 8 * (q & 3); gt[q] = *(const u32x2*)(gl + gate_off(tr, ch0 + d)); gv[q] = *(const f32x4*)(gs + d); }
; #pragma unroll
;     for (int q = 0; q < 8; ++q) { const int d = 32 * (q >> 2) + 8 * (q & 3), g = q & 3;
;         const f32x16& o = (q >> 2) ? o1 : o0;
;         u32x2 w; w.x = pk_bf16(o[4 * g + 0] * rs * gv[q][0] * silu(bf_lo(gt[q].x)), o[4 * g + 1] * rs * gv[q][1] * silu(bf_hi(gt[q].x)));
;         w.y = pk_bf16(o[4 * g + 2] * rs * gv[q][2] * silu(bf_lo(gt[q].y)), o[4 * g + 3] * rs * gv[q][3] * silu(bf_hi(gt[q].y)));
;         *(u32x2*)(yp + d) = w; }
; DI void mixer_phase(const Params& p, unsigned char* ldsraw, int vid) {
;     ...
;             store_head(oB0, oB1, rsqrtf(totB * (1.0f / 512.0f) + EPS), gl, r + 32, 64 * wid + 4 * hh, gs, Y + (size_t)tqB * 1024 + 64 * wid + 4 * hh);
	v_lshlrev_b32_e32 v80, 16, v72
	v_and_b32_e32 v81, 0xffff0000, v72
	v_mul_f32_e32 v36, 0xbfb8aa3b, v80
	v_exp_f32_e32 v36, v36
	v_mul_f32_e32 v37, 0xbfb8aa3b, v81
	v_exp_f32_e32 v37, v37
	v_add3_u32 v32, v149, v162, v148
	v_add3_u32 v33, v151, v162, v150
	global_load_dwordx4 v[44:47], v[98:99], off offset:128
	global_load_dwordx4 v[40:43], v[98:99], off offset:160
	v_add3_u32 v34, v153, v162, v152
	v_add3_u32 v35, v155, v162, v154
	ds_read_b64 v[82:83], v32 offset:4096
	ds_read_b64 v[54:55], v33 offset:4096
	ds_read_b64 v[52:53], v34 offset:4096
	ds_read_b64 v[50:51], v35 offset:4096
	v_add_f32_e32 v32, 1.0, v36
	v_rcp_f32_e32 v84, v32
	v_add_f32_e32 v32, 1.0, v37
	v_rcp_f32_e32 v85, v32
	v_lshlrev_b32_e32 v72, 16, v73
	v_mul_f32_e32 v16, v16, v48
	v_mul_f32_e32 v17, v17, v48
	v_and_b32_e32 v73, 0xffff0000, v73
	v_mul_f32_e32 v49, 0xbfb8aa3b, v72
	v_exp_f32_e32 v49, v49
	global_load_dwordx4 v[36:39], v[98:99], off offset:192
	global_load_dwordx4 v[32:35], v[98:99], off offset:224
	s_and_b64 vcc, exec, s[76:77]
	v_add_u32_e32 v146, s38, v163
	v_add_f32_e32 v49, 1.0, v49
	v_lshlrev_b32_e32 v164, 4, v163
	s_waitcnt vmcnt(7)
	v_mul_f32_e32 v16, v16, v56
	v_mul_f32_e32 v17, v17, v57
	v_mul_f32_e32 v56, v84, v80
	v_mul_f32_e32 v57, v85, v81
	v_mul_f32_e32 v80, 0xbfb8aa3b, v73
	v_exp_f32_e32 v80, v80
	v_mul_f32_e32 v16, v16, v56
	v_mul_f32_e32 v17, v17, v57
	v_rcp_f32_e32 v56, v49
	v_cvt_pk_bf16_f32 v236, v16, v17
	v_add_f32_e32 v49, 1.0, v80
	v_rcp_f32_e32 v57, v49
	v_mul_f32_e32 v18, v18, v48
	v_mul_f32_e32 v19, v19, v48
	v_mul_f32_e32 v56, v56, v72
	v_mul_f32_e32 v57, v57, v73
	v_mul_f32_e32 v18, v18, v58
	v_mul_f32_e32 v19, v19, v59
	s_nop 0
	v_mul_f32_e32 v18, v18, v56
	v_mul_f32_e32 v19, v19, v57
	s_waitcnt lgkmcnt(6)
	v_lshlrev_b32_e32 v56, 16, v74
	v_and_b32_e32 v57, 0xffff0000, v74
	v_mul_f32_e32 v17, 0xbfb8aa3b, v56
	v_exp_f32_e32 v49, v17
	v_mul_f32_e32 v17, 0xbfb8aa3b, v57
	v_exp_f32_e32 v58, v17
	v_cvt_pk_bf16_f32 v237, v18, v19
	v_add_f32_e32 v18, 1.0, v49
	v_rcp_f32_e32 v18, v18
	v_add_f32_e32 v19, 1.0, v58
	v_rcp_f32_e32 v19, v19
	v_and_b32_e32 v252, 32, v205
	v_lshrrev_b32_e32 v252, 2, v252
	v_mov_b32_e32 v253, 0
	v_lshl_add_u64 v[254:255], v[142:143], 0, v[252:253]
	v_mul_f32_e32 v16, v20, v48
	v_mul_f32_e32 v17, v21, v48
	v_lshlrev_b32_e32 v20, 16, v75
	v_and_b32_e32 v21, 0xffff0000, v75
	v_mul_f32_e32 v18, v18, v56
	v_mul_f32_e32 v19, v19, v57
	v_mul_f32_e32 v49, 0xbfb8aa3b, v20
	v_mul_f32_e32 v56, 0xbfb8aa3b, v21
	v_exp_f32_e32 v49, v49
	v_exp_f32_e32 v56, v56
	s_waitcnt vmcnt(6)
	v_mul_f32_e32 v16, v16, v60
	v_mul_f32_e32 v17, v17, v61
	v_mul_f32_e32 v22, v22, v48
	v_mul_f32_e32 v23, v23, v48
	v_mul_f32_e32 v16, v16, v18
	v_mul_f32_e32 v17, v17, v19
	v_add_f32_e32 v18, 1.0, v49
	v_add_f32_e32 v19, 1.0, v56
	v_rcp_f32_e32 v18, v18
	v_rcp_f32_e32 v19, v19
	v_cvt_pk_bf16_f32 v238, v16, v17
	v_mul_f32_e32 v22, v22, v62
	v_mul_f32_e32 v23, v23, v63
	v_mul_f32_e32 v0, v0, v48
	v_mul_f32_e32 v1, v1, v48
	v_mul_f32_e32 v18, v18, v20
	v_mul_f32_e32 v19, v19, v21
	s_waitcnt lgkmcnt(5)
	v_lshlrev_b32_e32 v20, 16, v76
	v_and_b32_e32 v21, 0xffff0000, v76
	v_mul_f32_e32 v17, 0xbfb8aa3b, v20
	v_mul_f32_e32 v18, v22, v18
	v_mul_f32_e32 v19, v23, v19
	v_exp_f32_e32 v22, v17
	v_mul_f32_e32 v17, 0xbfb8aa3b, v21
	v_exp_f32_e32 v23, v17
	v_cvt_pk_bf16_f32 v239, v18, v19
	v_add_f32_e32 v18, 1.0, v22
	v_rcp_f32_e32 v18, v18
	v_add_f32_e32 v19, 1.0, v23
	v_rcp_f32_e32 v19, v19
	s_nop 1
	v_permlane32_swap_b32_e32 v236, v238
	v_permlane32_swap_b32_e32 v237, v239
	global_store_dwordx4 v[254:255], v[236:239], off
	v_mul_f32_e32 v16, v24, v48
	v_mul_f32_e32 v17, v25, v48
	s_waitcnt vmcnt(4)
	v_mul_f32_e32 v0, v0, v44
	v_mul_f32_e32 v1, v1, v45
	v_mul_f32_e32 v18, v18, v20
	v_mul_f32_e32 v19, v19, v21
	v_lshlrev_b32_e32 v20, 16, v77
	v_and_b32_e32 v21, 0xffff0000, v77
	v_mul_f32_e32 v22, 0xbfb8aa3b, v20
	v_mul_f32_e32 v23, 0xbfb8aa3b, v21
	v_exp_f32_e32 v22, v22
	v_exp_f32_e32 v23, v23
	v_mul_f32_e32 v16, v16, v64
	v_mul_f32_e32 v17, v17, v65
	v_mul_f32_e32 v2, v2, v48
	v_mul_f32_e32 v3, v3, v48
	v_mul_f32_e32 v16, v16, v18
	v_mul_f32_e32 v17, v17, v19
	v_add_f32_e32 v18, 1.0, v22
	v_add_f32_e32 v19, 1.0, v23
	v_rcp_f32_e32 v18, v18
	v_rcp_f32_e32 v19, v19
	v_mul_f32_e32 v22, v26, v48
	v_mul_f32_e32 v23, v27, v48
	v_cvt_pk_bf16_f32 v240, v16, v17
	v_mul_f32_e32 v22, v22, v66
	v_mul_f32_e32 v23, v23, v67
	v_mul_f32_e32 v18, v18, v20
	v_mul_f32_e32 v19, v19, v21
	s_waitcnt lgkmcnt(4)
	v_lshlrev_b32_e32 v20, 16, v78
	v_and_b32_e32 v21, 0xffff0000, v78
	v_mul_f32_e32 v17, 0xbfb8aa3b, v20
	v_mul_f32_e32 v18, v22, v18
	v_mul_f32_e32 v19, v23, v19
	v_exp_f32_e32 v22, v17
	v_mul_f32_e32 v17, 0xbfb8aa3b, v21
	v_exp_f32_e32 v23, v17
	v_cvt_pk_bf16_f32 v241, v18, v19
	v_add_f32_e32 v18, 1.0, v22
	v_rcp_f32_e32 v18, v18
	v_add_f32_e32 v19, 1.0, v23
	v_rcp_f32_e32 v19, v19
	v_mul_f32_e32 v16, v28, v48
	v_mul_f32_e32 v17, v29, v48
	v_mul_f32_e32 v2, v2, v46
	v_mul_f32_e32 v3, v3, v47
	v_mul_f32_e32 v18, v18, v20
	v_mul_f32_e32 v19, v19, v21
	v_lshlrev_b32_e32 v20, 16, v79
	v_and_b32_e32 v21, 0xffff0000, v79
	v_mul_f32_e32 v22, 0xbfb8aa3b, v20
	v_mul_f32_e32 v23, 0xbfb8aa3b, v21
	v_exp_f32_e32 v22, v22
	v_exp_f32_e32 v23, v23
	v_mul_f32_e32 v16, v16, v68
	v_mul_f32_e32 v17, v17, v69
	v_mul_f32_e32 v6, v6, v48
	v_mul_f32_e32 v7, v7, v48
	v_mul_f32_e32 v16, v16, v18
	v_mul_f32_e32 v17, v17, v19
	v_add_f32_e32 v18, 1.0, v22
	v_add_f32_e32 v19, 1.0, v23
	v_rcp_f32_e32 v18, v18
	v_rcp_f32_e32 v19, v19
	v_mul_f32_e32 v22, v30, v48
	v_mul_f32_e32 v23, v31, v48
	v_cvt_pk_bf16_f32 v242, v16, v17
	v_mul_f32_e32 v22, v22, v70
	v_mul_f32_e32 v23, v23, v71
	v_mul_f32_e32 v18, v18, v20
	v_mul_f32_e32 v19, v19, v21
	s_waitcnt lgkmcnt(3)
; DI unsigned pk_bf16(float lo, float hi) { f32x2 v = {lo, hi}; bf2_t b = __builtin_convertvector(v, bf2_t); return __builtin_bit_cast(unsigned, b); }
; DI float bf_lo(unsigned u) { return __uint_as_float(u << 16); }
; DI float bf_hi(unsigned u) { return __uint_as_float(u & 0xffff0000u); }
; DI float silu(float x) { return x * __builtin_amdgcn_rcpf(1.0f + __builtin_amdgcn_exp2f(-1.4426950408889634f * x)); }
; #define ZERO16(v) do { _Pragma("unroll") for (int _i = 0; _i < 16; ++_i) (v)[_i] = 0.f; } while (0)
; DI void store_head(const f32x16& o0, const f32x16& o1, float rs, const unsigned char* gl, int tr, int ch0, const float* gs, bf16_t* yp) {
;     u32x2 gt[8]; f32x4 gv[8];
; #pragma unroll
;     for (int q = 0; q < 8; ++q) { const int d = 32 * (q >> 2) + 8 * (q & 3); gt[q] = *(const u32x2*)(gl + gate_off(tr, ch0 + d)); gv[q] = *(const f32x4*)(gs + d); }
; #pragma unroll
;     for (int q = 0; q < 8; ++q) { const int d = 32 * (q >> 2) + 8 * (q & 3), g = q & 3;
;         const f32x16& o = (q >> 2) ? o1 : o0;
;         u32x2 w; w.x = pk_bf16(o[4 * g + 0] * rs * gv[q][0] * silu(bf_lo(gt[q].x)), o[4 * g + 1] * rs * gv[q][1] * silu(bf_hi(gt[q].x)));
;         w.y = pk_bf16(o[4 * g + 2] * rs * gv[q][2] * silu(bf_lo(gt[q].y)), o[4 * g + 3] * rs * gv[q][3] * silu(bf_hi(gt[q].y)));
;         *(u32x2*)(yp + d) = w; }
; DI void mixer_phase(const Params& p, unsigned char* ldsraw, int vid) {
;     ...
;             store_head(oB0, oB1, rsqrtf(totB * (1.0f / 512.0f) + EPS), gl, r + 32, 64 * wid + 4 * hh, gs, Y + (size_t)tqB * 1024 + 64 * wid + 4 * hh);
;         }
;         {
;             f32x16 a0, a1, b0, b1; ZERO16(a0); ZERO16(a1); ZERO16(b0); ZERO16(b1);
	v_lshlrev_b32_e32 v20, 16, v82
	v_and_b32_e32 v21, 0xffff0000, v82
	v_mul_f32_e32 v17, 0xbfb8aa3b, v20
	v_mul_f32_e32 v18, v22, v18
	v_mul_f32_e32 v19, v23, v19
	v_exp_f32_e32 v22, v17
	v_mul_f32_e32 v17, 0xbfb8aa3b, v21
	v_exp_f32_e32 v23, v17
	v_cvt_pk_bf16_f32 v243, v18, v19
	v_add_f32_e32 v18, 1.0, v22
	v_rcp_f32_e32 v18, v18
	v_add_f32_e32 v19, 1.0, v23
	v_rcp_f32_e32 v19, v19
	s_nop 1
	v_permlane32_swap_b32_e32 v240, v242
	v_permlane32_swap_b32_e32 v241, v243
	global_store_dwordx4 v[254:255], v[240:243], off offset:32
	s_waitcnt vmcnt(4)
	v_mul_f32_e32 v6, v6, v42
	v_mul_f32_e32 v7, v7, v43
	v_mul_f32_e32 v16, v18, v20
	v_mul_f32_e32 v17, v19, v21
	v_lshlrev_b32_e32 v18, 16, v83
	v_and_b32_e32 v19, 0xffff0000, v83
	v_mul_f32_e32 v20, 0xbfb8aa3b, v18
	v_mul_f32_e32 v21, 0xbfb8aa3b, v19
	v_exp_f32_e32 v20, v20
	v_exp_f32_e32 v21, v21
	v_mul_f32_e32 v0, v0, v16
	v_mul_f32_e32 v1, v1, v17
	v_add_f32_e32 v16, 1.0, v20
	v_add_f32_e32 v17, 1.0, v21
	v_rcp_f32_e32 v16, v16
	v_rcp_f32_e32 v17, v17
	v_cvt_pk_bf16_f32 v244, v0, v1
	v_mul_f32_e32 v16, v16, v18
	v_mul_f32_e32 v17, v17, v19
	s_nop 0
	v_mul_f32_e32 v2, v2, v16
	v_mul_f32_e32 v3, v3, v17
	s_waitcnt lgkmcnt(2)
	v_lshlrev_b32_e32 v16, 16, v54
	v_and_b32_e32 v17, 0xffff0000, v54
	v_mul_f32_e32 v1, 0xbfb8aa3b, v16
	v_exp_f32_e32 v18, v1
	v_mul_f32_e32 v1, 0xbfb8aa3b, v17
	v_exp_f32_e32 v19, v1
	v_cvt_pk_bf16_f32 v245, v2, v3
	v_add_f32_e32 v2, 1.0, v18
	v_rcp_f32_e32 v2, v2
	v_add_f32_e32 v3, 1.0, v19
	v_rcp_f32_e32 v3, v3
	v_mul_f32_e32 v0, v4, v48
	v_mul_f32_e32 v1, v5, v48
	v_lshlrev_b32_e32 v4, 16, v55
	v_and_b32_e32 v5, 0xffff0000, v55
	v_mul_f32_e32 v2, v2, v16
	v_mul_f32_e32 v3, v3, v17
	v_mul_f32_e32 v16, 0xbfb8aa3b, v4
	v_mul_f32_e32 v17, 0xbfb8aa3b, v5
	v_exp_f32_e32 v16, v16
	v_exp_f32_e32 v17, v17
	v_mul_f32_e32 v0, v0, v40
	v_mul_f32_e32 v1, v1, v41
	s_nop 0
	v_mul_f32_e32 v0, v0, v2
	v_mul_f32_e32 v1, v1, v3
	v_add_f32_e32 v2, 1.0, v16
	v_add_f32_e32 v3, 1.0, v17
	v_rcp_f32_e32 v2, v2
	v_rcp_f32_e32 v3, v3
	v_cvt_pk_bf16_f32 v246, v0, v1
	v_mul_f32_e32 v2, v2, v4
	v_mul_f32_e32 v3, v3, v5
	s_waitcnt lgkmcnt(1)
	v_lshlrev_b32_e32 v4, 16, v52
	v_and_b32_e32 v5, 0xffff0000, v52
	v_mul_f32_e32 v1, 0xbfb8aa3b, v4
	v_mul_f32_e32 v2, v6, v2
	v_mul_f32_e32 v3, v7, v3
	v_exp_f32_e32 v6, v1
	v_mul_f32_e32 v1, 0xbfb8aa3b, v5
	v_exp_f32_e32 v7, v1
	v_cvt_pk_bf16_f32 v247, v2, v3
	v_add_f32_e32 v2, 1.0, v6
	v_rcp_f32_e32 v2, v2
	v_add_f32_e32 v3, 1.0, v7
	v_rcp_f32_e32 v3, v3
	s_nop 1
	v_permlane32_swap_b32_e32 v244, v246
	v_permlane32_swap_b32_e32 v245, v247
	global_store_dwordx4 v[254:255], v[244:247], off offset:64
	v_mul_f32_e32 v0, v8, v48
	v_mul_f32_e32 v1, v9, v48
	v_mul_f32_e32 v2, v2, v4
	v_mul_f32_e32 v3, v3, v5
	v_lshlrev_b32_e32 v4, 16, v53
	v_and_b32_e32 v5, 0xffff0000, v53
	v_mul_f32_e32 v6, 0xbfb8aa3b, v4
	v_mul_f32_e32 v7, 0xbfb8aa3b, v5
	v_exp_f32_e32 v6, v6
	v_exp_f32_e32 v7, v7
	s_waitcnt vmcnt(4)
	v_mul_f32_e32 v0, v0, v36
	v_mul_f32_e32 v1, v1, v37
	s_nop 0
	v_mul_f32_e32 v0, v0, v2
	v_mul_f32_e32 v1, v1, v3
	v_add_f32_e32 v2, 1.0, v6
	v_add_f32_e32 v3, 1.0, v7
	v_rcp_f32_e32 v2, v2
	v_rcp_f32_e32 v3, v3
	v_mul_f32_e32 v6, v10, v48
	v_mul_f32_e32 v7, v11, v48
	v_cvt_pk_bf16_f32 v248, v0, v1
	v_mul_f32_e32 v6, v6, v38
	v_mul_f32_e32 v7, v7, v39
	v_mul_f32_e32 v2, v2, v4
	v_mul_f32_e32 v3, v3, v5
	s_waitcnt lgkmcnt(0)
	v_lshlrev_b32_e32 v4, 16, v50
	v_and_b32_e32 v5, 0xffff0000, v50
	v_mul_f32_e32 v1, 0xbfb8aa3b, v4
	v_mul_f32_e32 v2, v6, v2
	v_mul_f32_e32 v3, v7, v3
	v_exp_f32_e32 v6, v1
	v_mul_f32_e32 v1, 0xbfb8aa3b, v5
	v_exp_f32_e32 v7, v1
	v_cvt_pk_bf16_f32 v249, v2, v3
	v_add_f32_e32 v2, 1.0, v6
	v_rcp_f32_e32 v2, v2
	v_add_f32_e32 v3, 1.0, v7
	v_rcp_f32_e32 v3, v3
	v_mul_f32_e32 v0, v12, v48
	v_mul_f32_e32 v1, v13, v48
	v_mul_f32_e32 v2, v2, v4
	v_mul_f32_e32 v3, v3, v5
	v_lshlrev_b32_e32 v4, 16, v51
	v_and_b32_e32 v5, 0xffff0000, v51
	v_mul_f32_e32 v6, 0xbfb8aa3b, v4
	v_mul_f32_e32 v7, 0xbfb8aa3b, v5
	v_exp_f32_e32 v6, v6
	v_exp_f32_e32 v7, v7
	s_waitcnt vmcnt(3)
	v_mul_f32_e32 v0, v0, v32
	v_mul_f32_e32 v1, v1, v33
	s_nop 0
	v_mul_f32_e32 v0, v0, v2
	v_mul_f32_e32 v1, v1, v3
	v_add_f32_e32 v2, 1.0, v6
	v_add_f32_e32 v3, 1.0, v7
	v_rcp_f32_e32 v2, v2
	v_rcp_f32_e32 v3, v3
	v_mul_f32_e32 v6, v14, v48
	v_mul_f32_e32 v7, v15, v48
	v_cvt_pk_bf16_f32 v250, v0, v1
	v_mul_f32_e32 v6, v6, v34
	v_mul_f32_e32 v7, v7, v35
	v_mul_f32_e32 v2, v2, v4
	v_mul_f32_e32 v3, v3, v5
	s_nop 0
	v_mul_f32_e32 v2, v6, v2
	v_mul_f32_e32 v3, v7, v3
	s_nop 0
	v_cvt_pk_bf16_f32 v251, v2, v3
	s_nop 1
	v_permlane32_swap_b32_e32 v248, v250
	v_permlane32_swap_b32_e32 v249, v251
	global_store_dwordx4 v[254:255], v[248:251], off offset:96
	s_cbranch_vccz .LBB0_432
; DI float bf_lo(unsigned u) { return __uint_as_float(u << 16); }
; DI float bf_hi(unsigned u) { return __uint_as_float(u & 0xffff0000u); }
; DI void conv_tok(const ConvW& cw, const bf16_t* RR, int t, int ch, float (&y)[8]) {
;     const int t1 = t >= 1 ? t - 1 : 0, t2 = t >= 2 ? t - 2 : 0;
;     const float k1 = t >= 1 ? 1.f : 0.f, k2 = t >= 2 ? 1.f : 0.f;
;     const bf16_t* rp0 = RR + (size_t)t * 2048 + ch; const bf16_t* rp1 = RR + (size_t)t1 * 2048 + ch; const bf16_t* rp2 = RR + (size_t)t2 * 2048 + ch;
;     const u32x4 u0 = *(const u32x4*)rp0, b0 = *(const u32x4*)(rp0 + 256), c0 = *(const u32x4*)(rp0 + 512);
;     const u32x4 u1 = *(const u32x4*)rp1, c1 = *(const u32x4*)(rp1 + 512), u2 = *(const u32x4*)rp2, c2 = *(const u32x4*)(rp2 + 512);
; #pragma unroll
;     for (int e2 = 0; e2 < 4; ++e2) {
;         const int j = (2 * e2) & 3;
;         const f32x4& w0 = e2 < 2 ? cw.w0a : cw.w0b; const f32x4& w1 = e2 < 2 ? cw.w1a : cw.w1b; const f32x4& w2 = e2 < 2 ? cw.w2a : cw.w2b; const f32x4& bb = e2 < 2 ? cw.ba : cw.bb;
;         y[2 * e2] = bf_lo(b0[e2]) * (w0[j] * (k2 * bf_lo(u2[e2]) * bf_lo(c2[e2])) + w1[j] * (k1 * bf_lo(u1[e2]) * bf_lo(c1[e2])) + w2[j] * (bf_lo(u0[e2]) * bf_lo(c0[e2])) + bb[j]);
;         y[2 * e2 + 1] = bf_hi(b0[e2]) * (w0[j + 1] * (k2 * bf_hi(u2[e2]) * bf_hi(c2[e2])) + w1[j + 1] * (k1 * bf_hi(u1[e2]) * bf_hi(c1[e2])) + w2[j + 1] * (bf_hi(u0[e2]) * bf_hi(c0[e2])) + bb[j + 1]);
;     }
; DI void mixer_phase(const Params& p, unsigned char* ldsraw, int vid) {
;     ...
;                 const int cgp = wid - 4, chunk = ln & 7, trow = ln >> 3, ch = 64 * cgp + 8 * chunk;
;                 ConvW cw; { const float* wp = p.conv_w + ch; const float* bp = p.conv_b + ch;
;                     cw.w0a = *(const f32x4*)wp; cw.w0b = *(const f32x4*)(wp + 4); cw.w1a = *(const f32x4*)(wp + 256); cw.w1b = *(const f32x4*)(wp + 260);
;                     cw.w2a = *(const f32x4*)(wp + 512); cw.w2b = *(const f32x4*)(wp + 516); cw.ba = *(const f32x4*)bp; cw.bb = *(const f32x4*)(bp + 4); }
	v_and_b32_e32 v69, 7, v205
	v_max_i32_e32 v0, 2, v146
	v_lshl_or_b32 v176, v69, 3, s93
	v_add_u32_e32 v0, -2, v0
	v_ashrrev_i32_e32 v147, 31, v146
	v_mov_b32_e32 v1, v177
	v_lshl_add_u64 v[32:33], v[176:177], 1, s[44:45]
	v_lshlrev_b64 v[2:3], 12, v[146:147]
	v_lshlrev_b64 v[0:1], 12, v[0:1]
	v_lshl_add_u64 v[2:3], v[32:33], 0, v[2:3]
	v_lshl_add_u64 v[0:1], v[32:33], 0, v[0:1]
	global_load_dwordx4 v[36:39], v[2:3], off offset:512
	global_load_dwordx4 v[40:43], v[0:1], off offset:1024
	global_load_dwordx4 v[44:47], v[2:3], off
	global_load_dwordx4 v[52:55], v[2:3], off offset:1024
	global_load_dwordx4 v[56:59], v[0:1], off
	v_max_i32_e32 v2, 1, v146
	v_lshlrev_b64 v[0:1], 2, v[176:177]
	v_add_u32_e32 v176, -1, v2
	v_lshlrev_b64 v[2:3], 12, v[176:177]
	v_lshl_add_u64 v[2:3], v[32:33], 0, v[2:3]
	global_load_dwordx4 v[60:63], v[2:3], off
	global_load_dwordx4 v[64:67], v[2:3], off offset:1024
	v_lshl_add_u64 v[2:3], s[48:49], 0, v[0:1]
	global_load_dwordx4 v[28:31], v[2:3], off
	global_load_dwordx4 v[24:27], v[2:3], off offset:1024
	global_load_dwordx4 v[16:19], v[2:3], off offset:2048
	v_lshl_add_u64 v[4:5], s[50:51], 0, v[0:1]
	global_load_dwordx4 v[20:23], v[4:5], off
	global_load_dwordx4 v[12:15], v[2:3], off offset:16
	global_load_dwordx4 v[8:11], v[2:3], off offset:1040
	s_nop 0
	global_load_dwordx4 v[0:3], v[2:3], off offset:2064
	s_nop 0
	global_load_dwordx4 v[4:7], v[4:5], off offset:16
	v_cmp_lt_i32_e32 vcc, 0, v146
	v_xor_b32_e32 v34, 1, v202
	s_waitcnt vmcnt(13)
	v_lshlrev_b32_e32 v50, 16, v40
	v_cndmask_b32_e64 v68, 0, 1.0, vcc
	v_cmp_lt_i32_e32 vcc, 1, v146
	s_waitcnt vmcnt(10)
	v_lshlrev_b32_e32 v78, 16, v56
	v_and_b32_e32 v79, 0xffff0000, v56
	v_cndmask_b32_e64 v70, 0, 1.0, vcc
	v_lshlrev_b32_e32 v56, 16, v57
	v_and_b32_e32 v57, 0xffff0000, v57
	v_and_b32_e32 v51, 0xffff0000, v40
	v_lshlrev_b32_e32 v72, 16, v44
	v_and_b32_e32 v73, 0xffff0000, v44
	v_lshlrev_b32_e32 v74, 16, v52
	v_and_b32_e32 v75, 0xffff0000, v52
	v_lshlrev_b32_e32 v40, 16, v41
	v_and_b32_e32 v41, 0xffff0000, v41
	v_lshlrev_b32_e32 v44, 16, v45
	v_and_b32_e32 v45, 0xffff0000, v45
	v_lshlrev_b32_e32 v52, 16, v53
	v_and_b32_e32 v53, 0xffff0000, v53
	s_waitcnt vmcnt(9)
	v_lshlrev_b32_e32 v82, 16, v60
	v_and_b32_e32 v83, 0xffff0000, v60
	v_lshlrev_b32_e32 v60, 16, v61
	v_and_b32_e32 v61, 0xffff0000, v61
	v_mul_f32_e32 v56, v70, v56
	v_mul_f32_e32 v57, v70, v57
	s_waitcnt vmcnt(8)
	v_lshlrev_b32_e32 v84, 16, v64
	v_and_b32_e32 v85, 0xffff0000, v64
	v_lshlrev_b32_e32 v64, 16, v65
	v_and_b32_e32 v65, 0xffff0000, v65
	v_mul_f32_e32 v44, v44, v52
	v_mul_f32_e32 v45, v45, v53
	v_mul_f32_e32 v52, v70, v78
	v_mul_f32_e32 v53, v70, v79
	v_mul_f32_e32 v60, v68, v60
	v_mul_f32_e32 v61, v68, v61
	v_mul_f32_e32 v40, v56, v40
	v_mul_f32_e32 v41, v57, v41
	v_mul_f32_e32 v72, v72, v74
	v_mul_f32_e32 v73, v73, v75
	v_mul_f32_e32 v74, v68, v82
	v_mul_f32_e32 v75, v68, v83
	v_mul_f32_e32 v50, v52, v50
	v_mul_f32_e32 v51, v53, v51
	v_mul_f32_e32 v56, v60, v64
	v_mul_f32_e32 v57, v61, v65
	s_waitcnt vmcnt(7)
	v_mul_f32_e32 v40, v30, v40
	v_mul_f32_e32 v41, v31, v41
	v_mul_f32_e32 v52, v74, v84
	v_mul_f32_e32 v53, v75, v85
	v_mul_f32_e32 v50, v28, v50
	v_mul_f32_e32 v51, v29, v51
	s_waitcnt vmcnt(6)
	v_fma_f32 v40, v26, v56, v40
	v_fma_f32 v41, v27, v57, v41
	v_fma_f32 v50, v24, v52, v50
	v_fma_f32 v51, v25, v53, v51
	s_waitcnt vmcnt(5)
	v_fma_f32 v40, v18, v44, v40
	v_fma_f32 v41, v19, v45, v41
	v_lshlrev_b32_e32 v48, 16, v36
	v_and_b32_e32 v49, 0xffff0000, v36
	v_lshlrev_b32_e32 v36, 16, v37
	v_and_b32_e32 v37, 0xffff0000, v37
	v_lshlrev_b32_e32 v80, 16, v58
	v_and_b32_e32 v81, 0xffff0000, v58
	v_fma_f32 v50, v16, v72, v50
	v_fma_f32 v51, v17, v73, v51
	s_waitcnt vmcnt(4)
	v_add_f32_e32 v40, v22, v40
	v_add_f32_e32 v41, v23, v41
	v_add_f32_e32 v44, v20, v50
	v_add_f32_e32 v45, v21, v51
	v_mul_f32_e32 v50, v40, v36
	v_mul_f32_e32 v51, v41, v37
	v_mul_f32_e32 v36, v70, v80
	v_mul_f32_e32 v37, v70, v81
	v_lshlrev_b32_e32 v40, 16, v42
	v_and_b32_e32 v41, 0xffff0000, v42
	v_mul_f32_e32 v36, v36, v40
	v_mul_f32_e32 v37, v37, v41
	v_lshlrev_b32_e32 v40, 16, v62
	v_and_b32_e32 v41, 0xffff0000, v62
	v_mul_f32_e32 v48, v44, v48
	v_mul_f32_e32 v49, v45, v49
	v_mul_f32_e32 v40, v68, v40
	v_mul_f32_e32 v41, v68, v41
	v_lshlrev_b32_e32 v44, 16, v66
	v_and_b32_e32 v45, 0xffff0000, v66
	s_waitcnt vmcnt(3)
	v_mul_f32_e32 v36, v12, v36
	v_mul_f32_e32 v37, v13, v37
	v_mul_f32_e32 v40, v40, v44
	v_mul_f32_e32 v41, v41, v45
	v_lshlrev_b32_e32 v44, 16, v54
	s_waitcnt vmcnt(2)
	v_fma_f32 v36, v8, v40, v36
	v_fma_f32 v37, v9, v41, v37
	v_lshlrev_b32_e32 v40, 16, v46
	v_and_b32_e32 v41, 0xffff0000, v46
	v_and_b32_e32 v45, 0xffff0000, v54
	v_mul_f32_e32 v40, v40, v44
	v_mul_f32_e32 v41, v41, v45
	v_lshlrev_b32_e32 v76, 16, v38
	s_waitcnt vmcnt(1)
	v_fma_f32 v36, v0, v40, v36
	v_fma_f32 v37, v1, v41, v37
	v_and_b32_e32 v77, 0xffff0000, v38
	s_waitcnt vmcnt(0)
; DI float bf_lo(unsigned u) { return __uint_as_float(u << 16); }
; DI float bf_hi(unsigned u) { return __uint_as_float(u & 0xffff0000u); }
; DI void conv_tok(const ConvW& cw, const bf16_t* RR, int t, int ch, float (&y)[8]) {
;     const int t1 = t >= 1 ? t - 1 : 0, t2 = t >= 2 ? t - 2 : 0;
;     const float k1 = t >= 1 ? 1.f : 0.f, k2 = t >= 2 ? 1.f : 0.f;
;     const bf16_t* rp0 = RR + (size_t)t * 2048 + ch; const bf16_t* rp1 = RR + (size_t)t1 * 2048 + ch; const bf16_t* rp2 = RR + (size_t)t2 * 2048 + ch;
;     const u32x4 u0 = *(const u32x4*)rp0, b0 = *(const u32x4*)(rp0 + 256), c0 = *(const u32x4*)(rp0 + 512);
;     const u32x4 u1 = *(const u32x4*)rp1, c1 = *(const u32x4*)(rp1 + 512), u2 = *(const u32x4*)rp2, c2 = *(const u32x4*)(rp2 + 512);
; #pragma unroll
;     for (int e2 = 0; e2 < 4; ++e2) {
;         const int j = (2 * e2) & 3;
;         const f32x4& w0 = e2 < 2 ? cw.w0a : cw.w0b; const f32x4& w1 = e2 < 2 ? cw.w1a : cw.w1b; const f32x4& w2 = e2 < 2 ? cw.w2a : cw.w2b; const f32x4& bb = e2 < 2 ? cw.ba : cw.bb;
;         y[2 * e2] = bf_lo(b0[e2]) * (w0[j] * (k2 * bf_lo(u2[e2]) * bf_lo(c2[e2])) + w1[j] * (k1 * bf_lo(u1[e2]) * bf_lo(c1[e2])) + w2[j] * (bf_lo(u0[e2]) * bf_lo(c0[e2])) + bb[j]);
;         y[2 * e2 + 1] = bf_hi(b0[e2]) * (w0[j + 1] * (k2 * bf_hi(u2[e2]) * bf_hi(c2[e2])) + w1[j + 1] * (k1 * bf_hi(u1[e2]) * bf_hi(c1[e2])) + w2[j + 1] * (bf_hi(u0[e2]) * bf_hi(c0[e2])) + bb[j + 1]);
;     }
; DI void mixer_phase(const Params& p, unsigned char* ldsraw, int vid) {
;     ...
;                 for (int j = 0; j < 8; ++j) {
;                     float y[8]; conv_tok(cw, RR, t0 + trow + 8 * j, ch, y);
;                     float ss = 0.f;
; #pragma unroll
;                     for (int e = 0; e < 8; ++e) ss += y[e] * y[e];
;                     ss += __shfl_xor(ss, 1); ss += __shfl_xor(ss, 2); ss += __shfl_xor(ss, 4);
;                     const int tk = trow + 8 * j;
;                     if (chunk == 0) lf[768 + 128 * (tk >> 5) + cgp * 32 + (tk & 31)] = ss;
	v_add_f32_e32 v36, v4, v36
	v_add_f32_e32 v37, v5, v37
	v_lshlrev_b32_e32 v38, 16, v59
	v_mul_f32_e32 v52, v36, v76
	v_mul_f32_e32 v53, v37, v77
	v_lshlrev_b32_e32 v36, 16, v39
	v_and_b32_e32 v37, 0xffff0000, v39
	v_and_b32_e32 v39, 0xffff0000, v59
	v_mul_f32_e32 v38, v70, v38
	v_mul_f32_e32 v39, v70, v39
	v_lshlrev_b32_e32 v40, 16, v43
	v_and_b32_e32 v41, 0xffff0000, v43
	v_mul_f32_e32 v38, v38, v40
	v_mul_f32_e32 v39, v39, v41
	v_lshlrev_b32_e32 v40, 16, v63
	v_and_b32_e32 v41, 0xffff0000, v63
	v_mul_f32_e32 v40, v68, v40
	v_mul_f32_e32 v41, v68, v41
	v_lshlrev_b32_e32 v42, 16, v67
	v_and_b32_e32 v43, 0xffff0000, v67
	v_mul_f32_e32 v38, v14, v38
	v_mul_f32_e32 v39, v15, v39
	v_mul_f32_e32 v40, v40, v42
	v_mul_f32_e32 v41, v41, v43
	v_lshlrev_b32_e32 v42, 16, v55
	v_fma_f32 v38, v10, v40, v38
	v_fma_f32 v39, v11, v41, v39
	v_lshlrev_b32_e32 v40, 16, v47
	v_and_b32_e32 v41, 0xffff0000, v47
	v_and_b32_e32 v43, 0xffff0000, v55
	v_mul_f32_e32 v40, v40, v42
	v_mul_f32_e32 v41, v41, v43
	v_cmp_lt_i32_e32 vcc, v34, v204
	v_fma_f32 v38, v2, v40, v38
	v_fma_f32 v39, v3, v41, v39
	v_mul_f32_e32 v40, v52, v52
	v_mul_f32_e32 v41, v53, v53
	v_add_f32_e32 v38, v6, v38
	v_add_f32_e32 v39, v7, v39
	v_cndmask_b32_e32 v34, v202, v34, vcc
	v_mul_f32_e32 v54, v38, v36
	v_mul_f32_e32 v55, v39, v37
	v_mul_f32_e32 v36, v48, v48
	v_mul_f32_e32 v37, v49, v49
	v_mul_f32_e32 v38, v50, v50
	v_mul_f32_e32 v39, v51, v51
	v_add_f32_e32 v35, v36, v37
	v_add_f32_e32 v35, v38, v35
	v_add_f32_e32 v35, v39, v35
	v_add_f32_e32 v35, v40, v35
	v_mul_f32_e32 v42, v54, v54
	v_mul_f32_e32 v43, v55, v55
	v_add_f32_e32 v35, v41, v35
	v_add_f32_e32 v35, v42, v35
	v_lshlrev_b32_e32 v34, 2, v34
	v_add_f32_e32 v36, v43, v35
	ds_bpermute_b32 v37, v34, v36
	v_xor_b32_e32 v35, 2, v202
	v_cmp_lt_i32_e32 vcc, v35, v204
	s_waitcnt lgkmcnt(0)
	v_add_f32_e32 v37, v36, v37
	v_cndmask_b32_e32 v35, v202, v35, vcc
	v_lshlrev_b32_e32 v35, 2, v35
	ds_bpermute_b32 v38, v35, v37
	v_xor_b32_e32 v36, 4, v202
	v_cmp_lt_i32_e32 vcc, v36, v204
	s_waitcnt lgkmcnt(0)
	v_add_f32_e32 v38, v37, v38
	v_cndmask_b32_e32 v36, v202, v36, vcc
	v_lshlrev_b32_e32 v36, 2, v36
	ds_bpermute_b32 v39, v36, v38
	v_cmp_eq_u32_e32 vcc, 0, v69
	v_and_b32_e32 v37, 0xfffffe00, v164
	s_and_saveexec_b64 s[0:1], vcc
	s_cbranch_execz .LBB0_417
	v_lshrrev_b32_e32 v40, 1, v205
	v_and_b32_e32 v40, 0x7c, v40
	v_add3_u32 v40, s75, v37, v40
	s_waitcnt lgkmcnt(0)
	v_add_f32_e32 v38, v38, v39
	ds_write_b32 v40, v38 offset:3072
.LBB0_417:
	s_or_b64 exec, exec, s[0:1]
	v_add_u32_e32 v38, 8, v146
	s_waitcnt lgkmcnt(0)
	v_ashrrev_i32_e32 v39, 31, v38
	v_lshlrev_b64 v[40:41], 12, v[38:39]
	v_lshl_add_u64 v[40:41], v[32:33], 0, v[40:41]
	global_load_dwordx4 v[42:45], v[40:41], off offset:512
	global_load_dwordx4 v[56:59], v[40:41], off
	global_load_dwordx4 v[60:63], v[40:41], off offset:1024
	v_max_i32_e32 v40, 1, v38
	v_max_i32_e32 v38, 2, v38
	v_mov_b32_e32 v39, v177
	v_add_u32_e32 v38, -2, v38
	v_lshlrev_b64 v[38:39], 12, v[38:39]
	v_add_u32_e32 v176, -1, v40
	v_lshl_add_u64 v[38:39], v[32:33], 0, v[38:39]
	global_load_dwordx4 v[64:67], v[38:39], off
	global_load_dwordx4 v[68:71], v[38:39], off offset:1024
	v_lshlrev_b64 v[40:41], 12, v[176:177]
	v_lshl_add_u64 v[38:39], v[32:33], 0, v[40:41]
	global_load_dwordx4 v[72:75], v[38:39], off
	global_load_dwordx4 v[76:79], v[38:39], off offset:1024
	v_cmp_lt_i32_e64 s[0:1], -8, v146
	s_waitcnt vmcnt(6)
	v_lshlrev_b32_e32 v40, 16, v42
	v_cndmask_b32_e64 v38, 0, 1.0, s[0:1]
	v_cmp_lt_i32_e64 s[0:1], -7, v146
	s_waitcnt vmcnt(5)
	v_lshlrev_b32_e32 v86, 16, v58
	v_and_b32_e32 v87, 0xffff0000, v58
	v_cndmask_b32_e64 v46, 0, 1.0, s[0:1]
	s_waitcnt vmcnt(4)
	v_lshlrev_b32_e32 v88, 16, v62
	v_and_b32_e32 v89, 0xffff0000, v62
	v_lshlrev_b32_e32 v80, 16, v56
	v_and_b32_e32 v81, 0xffff0000, v56
	s_waitcnt vmcnt(3)
	v_lshlrev_b32_e32 v90, 16, v64
	v_and_b32_e32 v91, 0xffff0000, v64
	v_lshlrev_b32_e32 v64, 16, v65
	v_and_b32_e32 v65, 0xffff0000, v65
	v_lshlrev_b32_e32 v82, 16, v60
	v_and_b32_e32 v83, 0xffff0000, v60
	v_lshlrev_b32_e32 v56, 16, v57
	v_and_b32_e32 v57, 0xffff0000, v57
	v_lshlrev_b32_e32 v60, 16, v61
	v_and_b32_e32 v61, 0xffff0000, v61
	s_waitcnt vmcnt(2)
	v_lshlrev_b32_e32 v92, 16, v68
	v_and_b32_e32 v93, 0xffff0000, v68
	s_waitcnt vmcnt(1)
	v_lshlrev_b32_e32 v94, 16, v72
	v_and_b32_e32 v95, 0xffff0000, v72
	v_lshlrev_b32_e32 v68, 16, v69
	v_and_b32_e32 v69, 0xffff0000, v69
	v_lshlrev_b32_e32 v72, 16, v73
	v_and_b32_e32 v73, 0xffff0000, v73
	v_mul_f32_e32 v86, v86, v88
	v_mul_f32_e32 v87, v87, v89
	v_mul_f32_e32 v88, v46, v90
	v_mul_f32_e32 v89, v46, v91
	v_mul_f32_e32 v64, v46, v64
	v_mul_f32_e32 v65, v46, v65
	s_waitcnt vmcnt(0)
; DI float bf_lo(unsigned u) { return __uint_as_float(u << 16); }
; DI float bf_hi(unsigned u) { return __uint_as_float(u & 0xffff0000u); }
; DI void conv_tok(const ConvW& cw, const bf16_t* RR, int t, int ch, float (&y)[8]) {
;     const int t1 = t >= 1 ? t - 1 : 0, t2 = t >= 2 ? t - 2 : 0;
;     const float k1 = t >= 1 ? 1.f : 0.f, k2 = t >= 2 ? 1.f : 0.f;
;     const bf16_t* rp0 = RR + (size_t)t * 2048 + ch; const bf16_t* rp1 = RR + (size_t)t1 * 2048 + ch; const bf16_t* rp2 = RR + (size_t)t2 * 2048 + ch;
;     const u32x4 u0 = *(const u32x4*)rp0, b0 = *(const u32x4*)(rp0 + 256), c0 = *(const u32x4*)(rp0 + 512);
;     const u32x4 u1 = *(const u32x4*)rp1, c1 = *(const u32x4*)(rp1 + 512), u2 = *(const u32x4*)rp2, c2 = *(const u32x4*)(rp2 + 512);
; #pragma unroll
;     for (int e2 = 0; e2 < 4; ++e2) {
;         const int j = (2 * e2) & 3;
;         const f32x4& w0 = e2 < 2 ? cw.w0a : cw.w0b; const f32x4& w1 = e2 < 2 ? cw.w1a : cw.w1b; const f32x4& w2 = e2 < 2 ? cw.w2a : cw.w2b; const f32x4& bb = e2 < 2 ? cw.ba : cw.bb;
;         y[2 * e2] = bf_lo(b0[e2]) * (w0[j] * (k2 * bf_lo(u2[e2]) * bf_lo(c2[e2])) + w1[j] * (k1 * bf_lo(u1[e2]) * bf_lo(c1[e2])) + w2[j] * (bf_lo(u0[e2]) * bf_lo(c0[e2])) + bb[j]);
;         y[2 * e2 + 1] = bf_hi(b0[e2]) * (w0[j + 1] * (k2 * bf_hi(u2[e2]) * bf_hi(c2[e2])) + w1[j + 1] * (k1 * bf_hi(u1[e2]) * bf_hi(c1[e2])) + w2[j + 1] * (bf_hi(u0[e2]) * bf_hi(c0[e2])) + bb[j + 1]);
;     }
; DI void mixer_phase(const Params& p, unsigned char* ldsraw, int vid) {
;     ...
;                 for (int j = 0; j < 8; ++j) {
;                     float y[8]; conv_tok(cw, RR, t0 + trow + 8 * j, ch, y);
;                     float ss = 0.f;
; #pragma unroll
;                     for (int e = 0; e < 8; ++e) ss += y[e] * y[e];
;                     ss += __shfl_xor(ss, 1); ss += __shfl_xor(ss, 2); ss += __shfl_xor(ss, 4);
;                     const int tk = trow + 8 * j;
;                     if (chunk == 0) lf[768 + 128 * (tk >> 5) + cgp * 32 + (tk & 31)] = ss;
	v_lshlrev_b32_e32 v98, 16, v76
	v_and_b32_e32 v99, 0xffff0000, v76
	v_lshlrev_b32_e32 v76, 16, v77
	v_and_b32_e32 v77, 0xffff0000, v77
	v_mul_f32_e32 v56, v56, v60
	v_mul_f32_e32 v57, v57, v61
	v_lshlrev_b32_e32 v60, 16, v66
	v_and_b32_e32 v61, 0xffff0000, v66
	v_mul_f32_e32 v90, v38, v94
	v_mul_f32_e32 v91, v38, v95
	v_mul_f32_e32 v72, v38, v72
	v_mul_f32_e32 v73, v38, v73
	v_mul_f32_e32 v88, v88, v92
	v_mul_f32_e32 v89, v89, v93
	v_mul_f32_e32 v64, v64, v68
	v_mul_f32_e32 v65, v65, v69
	v_mul_f32_e32 v80, v80, v82
	v_mul_f32_e32 v81, v81, v83
	v_lshlrev_b32_e32 v82, 16, v70
	v_and_b32_e32 v83, 0xffff0000, v70
	v_lshlrev_b32_e32 v100, 16, v74
	v_and_b32_e32 v101, 0xffff0000, v74
	v_mul_f32_e32 v60, v46, v60
	v_mul_f32_e32 v61, v46, v61
	v_mul_f32_e32 v90, v90, v98
	v_mul_f32_e32 v91, v91, v99
	v_mul_f32_e32 v68, v72, v76
	v_mul_f32_e32 v69, v73, v77
	v_mul_f32_e32 v76, v28, v88
	v_mul_f32_e32 v77, v29, v89
	v_mul_f32_e32 v64, v30, v64
	v_mul_f32_e32 v65, v31, v65
	v_lshlrev_b32_e32 v102, 16, v78
	v_and_b32_e32 v103, 0xffff0000, v78
	v_mul_f32_e32 v94, v38, v100
	v_mul_f32_e32 v95, v38, v101
	v_mul_f32_e32 v60, v60, v82
	v_mul_f32_e32 v61, v61, v83
	v_fma_f32 v76, v24, v90, v76
	v_fma_f32 v77, v25, v91, v77
	v_fma_f32 v64, v26, v68, v64
	v_fma_f32 v65, v27, v69, v65
	v_mul_f32_e32 v72, v94, v102
	v_mul_f32_e32 v73, v95, v103
	v_mul_f32_e32 v60, v12, v60
	v_mul_f32_e32 v61, v13, v61
	v_fma_f32 v68, v16, v80, v76
	v_fma_f32 v69, v17, v81, v77
	v_fma_f32 v56, v18, v56, v64
	v_fma_f32 v57, v19, v57, v65
	v_and_b32_e32 v41, 0xffff0000, v42
	v_lshlrev_b32_e32 v42, 16, v43
	v_and_b32_e32 v43, 0xffff0000, v43
	v_fma_f32 v60, v8, v72, v60
	v_fma_f32 v61, v9, v73, v61
	v_add_f32_e32 v64, v20, v68
	v_add_f32_e32 v65, v21, v69
	v_add_f32_e32 v68, v22, v56
	v_add_f32_e32 v69, v23, v57
	v_mul_f32_e32 v56, v64, v40
	v_mul_f32_e32 v57, v65, v41
	v_mul_f32_e32 v40, v68, v42
	v_mul_f32_e32 v41, v69, v43
	v_fma_f32 v42, v0, v86, v60
	v_fma_f32 v43, v1, v87, v61
	v_lshlrev_b32_e32 v60, 16, v67
	v_and_b32_e32 v61, 0xffff0000, v67
	v_mul_f32_e32 v47, v46, v61
	v_mul_f32_e32 v46, v46, v60
	v_lshlrev_b32_e32 v60, 16, v71
	v_and_b32_e32 v61, 0xffff0000, v71
	v_mul_f32_e32 v46, v46, v60
	v_mul_f32_e32 v47, v47, v61
	v_lshlrev_b32_e32 v60, 16, v75
	v_and_b32_e32 v61, 0xffff0000, v75
	v_mul_f32_e32 v39, v38, v61
	v_mul_f32_e32 v38, v38, v60
	v_lshlrev_b32_e32 v60, 16, v79
	v_and_b32_e32 v61, 0xffff0000, v79
	v_mul_f32_e32 v46, v14, v46
	v_mul_f32_e32 v47, v15, v47
	v_mul_f32_e32 v38, v38, v60
	v_mul_f32_e32 v39, v39, v61
	v_lshlrev_b32_e32 v58, 16, v63
	v_fma_f32 v38, v10, v38, v46
	v_fma_f32 v39, v11, v39, v47
	v_lshlrev_b32_e32 v46, 16, v59
	v_and_b32_e32 v47, 0xffff0000, v59
	v_and_b32_e32 v59, 0xffff0000, v63
	v_mul_f32_e32 v46, v46, v58
	v_mul_f32_e32 v47, v47, v59
	v_lshlrev_b32_e32 v84, 16, v44
	v_fma_f32 v38, v2, v46, v38
	v_fma_f32 v39, v3, v47, v39
	v_and_b32_e32 v85, 0xffff0000, v44
	v_lshlrev_b32_e32 v44, 16, v45
	v_and_b32_e32 v45, 0xffff0000, v45
	v_add_f32_e32 v38, v6, v38
	v_add_f32_e32 v39, v7, v39
	v_add_f32_e32 v42, v4, v42
	v_add_f32_e32 v43, v5, v43
	v_mul_f32_e32 v44, v38, v44
	v_mul_f32_e32 v45, v39, v45
	v_mul_f32_e32 v38, v56, v56
	v_mul_f32_e32 v39, v57, v57
	v_mul_f32_e32 v46, v40, v40
	v_mul_f32_e32 v47, v41, v41
	v_add_f32_e32 v38, v38, v39
	v_mul_f32_e32 v42, v42, v84
	v_mul_f32_e32 v43, v43, v85
	v_add_f32_e32 v38, v46, v38
	v_mul_f32_e32 v58, v42, v42
	v_mul_f32_e32 v59, v43, v43
	v_add_f32_e32 v38, v47, v38
	v_add_f32_e32 v38, v58, v38
	v_mul_f32_e32 v60, v44, v44
	v_mul_f32_e32 v61, v45, v45
	v_add_f32_e32 v38, v59, v38
	v_add_f32_e32 v38, v60, v38
	v_add_f32_e32 v38, v61, v38
	ds_bpermute_b32 v39, v34, v38
	s_waitcnt lgkmcnt(0)
	v_add_f32_e32 v38, v38, v39
	ds_bpermute_b32 v39, v35, v38
	s_waitcnt lgkmcnt(0)
	v_add_f32_e32 v38, v38, v39
	ds_bpermute_b32 v39, v36, v38
	s_and_saveexec_b64 s[0:1], vcc
	s_cbranch_execz .LBB0_419
	v_add_u32_e32 v46, 8, v163
	s_waitcnt lgkmcnt(0)
	v_add_f32_e32 v38, v38, v39
	v_and_b32_e32 v39, 31, v46
	v_lshlrev_b32_e32 v46, 4, v46
	v_and_b32_e32 v46, 0xfffffe00, v46
	v_lshlrev_b32_e32 v39, 2, v39
	v_add3_u32 v39, s75, v46, v39
	ds_write_b32 v39, v38 offset:3072
.LBB0_419:
	s_or_b64 exec, exec, s[0:1]
	v_add_u32_e32 v38, 16, v146
	s_waitcnt lgkmcnt(0)
	v_ashrrev_i32_e32 v39, 31, v38
	v_lshlrev_b64 v[46:47], 12, v[38:39]
	v_lshl_add_u64 v[46:47], v[32:33], 0, v[46:47]
	global_load_dwordx4 v[58:61], v[46:47], off offset:512
	global_load_dwordx4 v[68:71], v[46:47], off
	global_load_dwordx4 v[72:75], v[46:47], off offset:1024
	v_max_i32_e32 v46, 1, v38
	v_max_i32_e32 v38, 2, v38
	v_mov_b32_e32 v39, v177
	v_add_u32_e32 v38, -2, v38
	v_lshlrev_b64 v[38:39], 12, v[38:39]
	v_add_u32_e32 v176, -1, v46
	v_lshl_add_u64 v[38:39], v[32:33], 0, v[38:39]
	global_load_dwordx4 v[76:79], v[38:39], off
	global_load_dwordx4 v[80:83], v[38:39], off offset:1024
	v_lshlrev_b64 v[46:47], 12, v[176:177]
	v_lshl_add_u64 v[38:39], v[32:33], 0, v[46:47]
	global_load_dwordx4 v[84:87], v[38:39], off
	global_load_dwordx4 v[88:91], v[38:39], off offset:1024
	v_cmp_lt_i32_e64 s[0:1], -16, v146
	s_waitcnt vmcnt(6)
	v_lshlrev_b32_e32 v62, 16, v58
	v_cndmask_b32_e64 v38, 0, 1.0, s[0:1]
	v_cmp_lt_i32_e64 s[0:1], -15, v146
	s_waitcnt vmcnt(5)
	v_lshlrev_b32_e32 v64, 16, v68
	v_and_b32_e32 v65, 0xffff0000, v68
	s_waitcnt vmcnt(4)
	v_lshlrev_b32_e32 v66, 16, v72
	v_and_b32_e32 v67, 0xffff0000, v72
	v_cndmask_b32_e64 v46, 0, 1.0, s[0:1]
	v_mul_f32_e32 v64, v64, v66
	v_mul_f32_e32 v65, v65, v67
	v_lshlrev_b32_e32 v68, 16, v69
	s_waitcnt vmcnt(3)
; DI float bf_lo(unsigned u) { return __uint_as_float(u << 16); }
; DI float bf_hi(unsigned u) { return __uint_as_float(u & 0xffff0000u); }
; DI void conv_tok(const ConvW& cw, const bf16_t* RR, int t, int ch, float (&y)[8]) {
;     const int t1 = t >= 1 ? t - 1 : 0, t2 = t >= 2 ? t - 2 : 0;
;     const float k1 = t >= 1 ? 1.f : 0.f, k2 = t >= 2 ? 1.f : 0.f;
;     const bf16_t* rp0 = RR + (size_t)t * 2048 + ch; const bf16_t* rp1 = RR + (size_t)t1 * 2048 + ch; const bf16_t* rp2 = RR + (size_t)t2 * 2048 + ch;
;     const u32x4 u0 = *(const u32x4*)rp0, b0 = *(const u32x4*)(rp0 + 256), c0 = *(const u32x4*)(rp0 + 512);
;     const u32x4 u1 = *(const u32x4*)rp1, c1 = *(const u32x4*)(rp1 + 512), u2 = *(const u32x4*)rp2, c2 = *(const u32x4*)(rp2 + 512);
; #pragma unroll
;     for (int e2 = 0; e2 < 4; ++e2) {
;         const int j = (2 * e2) & 3;
;         const f32x4& w0 = e2 < 2 ? cw.w0a : cw.w0b; const f32x4& w1 = e2 < 2 ? cw.w1a : cw.w1b; const f32x4& w2 = e2 < 2 ? cw.w2a : cw.w2b; const f32x4& bb = e2 < 2 ? cw.ba : cw.bb;
;         y[2 * e2] = bf_lo(b0[e2]) * (w0[j] * (k2 * bf_lo(u2[e2]) * bf_lo(c2[e2])) + w1[j] * (k1 * bf_lo(u1[e2]) * bf_lo(c1[e2])) + w2[j] * (bf_lo(u0[e2]) * bf_lo(c0[e2])) + bb[j]);
;         y[2 * e2 + 1] = bf_hi(b0[e2]) * (w0[j + 1] * (k2 * bf_hi(u2[e2]) * bf_hi(c2[e2])) + w1[j + 1] * (k1 * bf_hi(u1[e2]) * bf_hi(c1[e2])) + w2[j + 1] * (bf_hi(u0[e2]) * bf_hi(c0[e2])) + bb[j + 1]);
;     }
; DI void mixer_phase(const Params& p, unsigned char* ldsraw, int vid) {
;     ...
;                 for (int j = 0; j < 8; ++j) {
;                     float y[8]; conv_tok(cw, RR, t0 + trow + 8 * j, ch, y);
;                     float ss = 0.f;
; #pragma unroll
;                     for (int e = 0; e < 8; ++e) ss += y[e] * y[e];
;                     ss += __shfl_xor(ss, 1); ss += __shfl_xor(ss, 2); ss += __shfl_xor(ss, 4);
;                     const int tk = trow + 8 * j;
;                     if (chunk == 0) lf[768 + 128 * (tk >> 5) + cgp * 32 + (tk & 31)] = ss;
	v_lshlrev_b32_e32 v66, 16, v77
	v_and_b32_e32 v67, 0xffff0000, v77
	v_and_b32_e32 v69, 0xffff0000, v69
	v_lshlrev_b32_e32 v72, 16, v73
	v_and_b32_e32 v73, 0xffff0000, v73
	v_lshlrev_b32_e32 v100, 16, v76
	v_and_b32_e32 v101, 0xffff0000, v76
	s_waitcnt vmcnt(2)
	v_lshlrev_b32_e32 v102, 16, v80
	v_and_b32_e32 v103, 0xffff0000, v80
	v_lshlrev_b32_e32 v76, 16, v81
	v_and_b32_e32 v77, 0xffff0000, v81
	s_waitcnt vmcnt(1)
	v_lshlrev_b32_e32 v80, 16, v85
	v_and_b32_e32 v81, 0xffff0000, v85
	v_mul_f32_e32 v66, v46, v66
	v_mul_f32_e32 v67, v46, v67
	v_lshlrev_b32_e32 v104, 16, v84
	v_and_b32_e32 v105, 0xffff0000, v84
	s_waitcnt vmcnt(0)
	v_lshlrev_b32_e32 v84, 16, v89
	v_and_b32_e32 v85, 0xffff0000, v89
	v_mul_f32_e32 v68, v68, v72
	v_mul_f32_e32 v69, v69, v73
	v_lshlrev_b32_e32 v72, 16, v78
	v_and_b32_e32 v73, 0xffff0000, v78
	v_mul_f32_e32 v80, v38, v80
	v_mul_f32_e32 v81, v38, v81
	v_mul_f32_e32 v66, v66, v76
	v_mul_f32_e32 v67, v67, v77
	v_lshlrev_b32_e32 v94, 16, v70
	v_and_b32_e32 v95, 0xffff0000, v70
	v_lshlrev_b32_e32 v98, 16, v74
	v_and_b32_e32 v99, 0xffff0000, v74
	v_lshlrev_b32_e32 v106, 16, v88
	v_and_b32_e32 v107, 0xffff0000, v88
	v_lshlrev_b32_e32 v88, 16, v82
	v_and_b32_e32 v89, 0xffff0000, v82
	v_lshlrev_b32_e32 v108, 16, v86
	v_and_b32_e32 v109, 0xffff0000, v86
	v_mul_f32_e32 v72, v46, v72
	v_mul_f32_e32 v73, v46, v73
	v_mul_f32_e32 v76, v80, v84
	v_mul_f32_e32 v77, v81, v85
	v_mul_f32_e32 v66, v30, v66
	v_mul_f32_e32 v67, v31, v67
	v_lshlrev_b32_e32 v110, 16, v90
	v_and_b32_e32 v111, 0xffff0000, v90
	v_mul_f32_e32 v94, v94, v98
	v_mul_f32_e32 v95, v95, v99
	v_mul_f32_e32 v98, v46, v100
	v_mul_f32_e32 v99, v46, v101
	v_mul_f32_e32 v100, v38, v104
	v_mul_f32_e32 v101, v38, v105
	v_mul_f32_e32 v104, v38, v108
	v_mul_f32_e32 v105, v38, v109
	v_mul_f32_e32 v72, v72, v88
	v_mul_f32_e32 v73, v73, v89
	v_fma_f32 v66, v26, v76, v66
	v_fma_f32 v67, v27, v77, v67
	v_mul_f32_e32 v80, v104, v110
	v_mul_f32_e32 v81, v105, v111
	v_mul_f32_e32 v72, v12, v72
	v_mul_f32_e32 v73, v13, v73
	v_fma_f32 v66, v18, v68, v66
	v_fma_f32 v67, v19, v69, v67
	v_and_b32_e32 v63, 0xffff0000, v58
	v_lshlrev_b32_e32 v58, 16, v59
	v_and_b32_e32 v59, 0xffff0000, v59
	v_fma_f32 v72, v8, v80, v72
	v_fma_f32 v73, v9, v81, v73
	v_add_f32_e32 v66, v22, v66
	v_add_f32_e32 v67, v23, v67
	v_lshlrev_b32_e32 v92, 16, v60
	v_mul_f32_e32 v66, v66, v58
	v_mul_f32_e32 v67, v67, v59
	v_fma_f32 v58, v0, v94, v72
	v_fma_f32 v59, v1, v95, v73
	v_and_b32_e32 v93, 0xffff0000, v60
	v_add_f32_e32 v58, v4, v58
	v_add_f32_e32 v59, v5, v59
	v_lshlrev_b32_e32 v60, 16, v79
	v_mul_f32_e32 v68, v58, v92
	v_mul_f32_e32 v69, v59, v93
	v_lshlrev_b32_e32 v58, 16, v61
	v_and_b32_e32 v59, 0xffff0000, v61
	v_and_b32_e32 v61, 0xffff0000, v79
	v_mul_f32_e32 v47, v46, v61
	v_mul_f32_e32 v46, v46, v60
	v_lshlrev_b32_e32 v60, 16, v83
	v_and_b32_e32 v61, 0xffff0000, v83
	v_mul_f32_e32 v46, v46, v60
	v_mul_f32_e32 v47, v47, v61
	v_lshlrev_b32_e32 v60, 16, v87
	v_and_b32_e32 v61, 0xffff0000, v87
	v_mul_f32_e32 v98, v98, v102
	v_mul_f32_e32 v99, v99, v103
	v_mul_f32_e32 v39, v38, v61
	v_mul_f32_e32 v38, v38, v60
	v_lshlrev_b32_e32 v60, 16, v91
	v_and_b32_e32 v61, 0xffff0000, v91
	v_mul_f32_e32 v100, v100, v106
	v_mul_f32_e32 v101, v101, v107
	v_mul_f32_e32 v84, v28, v98
	v_mul_f32_e32 v85, v29, v99
	v_mul_f32_e32 v46, v14, v46
	v_mul_f32_e32 v47, v15, v47
	v_mul_f32_e32 v38, v38, v60
	v_mul_f32_e32 v39, v39, v61
	v_fma_f32 v84, v24, v100, v84
	v_fma_f32 v85, v25, v101, v85
	v_fma_f32 v38, v10, v38, v46
	v_fma_f32 v39, v11, v39, v47
	v_lshlrev_b32_e32 v46, 16, v71
	v_and_b32_e32 v47, 0xffff0000, v71
	v_lshlrev_b32_e32 v60, 16, v75
	v_and_b32_e32 v61, 0xffff0000, v75
	v_fma_f32 v64, v16, v64, v84
	v_fma_f32 v65, v17, v65, v85
	v_mul_f32_e32 v46, v46, v60
	v_mul_f32_e32 v47, v47, v61
	v_add_f32_e32 v64, v20, v64
	v_add_f32_e32 v65, v21, v65
	v_fma_f32 v38, v2, v46, v38
	v_fma_f32 v39, v3, v47, v39
	v_mul_f32_e32 v64, v64, v62
	v_mul_f32_e32 v65, v65, v63
	v_add_f32_e32 v38, v6, v38
	v_add_f32_e32 v39, v7, v39
	v_mul_f32_e32 v46, v66, v66
	v_mul_f32_e32 v47, v67, v67
	v_mul_f32_e32 v70, v38, v58
	v_mul_f32_e32 v71, v39, v59
	v_mul_f32_e32 v38, v64, v64
	v_mul_f32_e32 v39, v65, v65
	v_mul_f32_e32 v58, v68, v68
	v_mul_f32_e32 v59, v69, v69
	v_add_f32_e32 v38, v38, v39
	v_add_f32_e32 v38, v46, v38
	v_add_f32_e32 v38, v47, v38
	v_add_f32_e32 v38, v58, v38
	v_mul_f32_e32 v60, v70, v70
	v_mul_f32_e32 v61, v71, v71
	v_add_f32_e32 v38, v59, v38
	v_add_f32_e32 v38, v60, v38
	v_add_f32_e32 v38, v61, v38
	ds_bpermute_b32 v39, v34, v38
	s_waitcnt lgkmcnt(0)
	v_add_f32_e32 v38, v38, v39
	ds_bpermute_b32 v39, v35, v38
	s_waitcnt lgkmcnt(0)
	v_add_f32_e32 v38, v38, v39
	ds_bpermute_b32 v39, v36, v38
	s_and_saveexec_b64 s[0:1], vcc
	s_cbranch_execz .LBB0_421
	v_add_u32_e32 v46, 16, v163
	s_waitcnt lgkmcnt(0)
	v_add_f32_e32 v38, v38, v39
	v_and_b32_e32 v39, 31, v46
	v_lshlrev_b32_e32 v46, 4, v46
	v_and_b32_e32 v46, 0xfffffe00, v46
	v_lshlrev_b32_e32 v39, 2, v39
	v_add3_u32 v39, s75, v46, v39
	ds_write_b32 v39, v38 offset:3072
; DI float bf_lo(unsigned u) { return __uint_as_float(u << 16); }
; DI float bf_hi(unsigned u) { return __uint_as_float(u & 0xffff0000u); }
; DI void conv_tok(const ConvW& cw, const bf16_t* RR, int t, int ch, float (&y)[8]) {
;     const int t1 = t >= 1 ? t - 1 : 0, t2 = t >= 2 ? t - 2 : 0;
;     const float k1 = t >= 1 ? 1.f : 0.f, k2 = t >= 2 ? 1.f : 0.f;
;     const bf16_t* rp0 = RR + (size_t)t * 2048 + ch; const bf16_t* rp1 = RR + (size_t)t1 * 2048 + ch; const bf16_t* rp2 = RR + (size_t)t2 * 2048 + ch;
;     const u32x4 u0 = *(const u32x4*)rp0, b0 = *(const u32x4*)(rp0 + 256), c0 = *(const u32x4*)(rp0 + 512);
;     const u32x4 u1 = *(const u32x4*)rp1, c1 = *(const u32x4*)(rp1 + 512), u2 = *(const u32x4*)rp2, c2 = *(const u32x4*)(rp2 + 512);
; #pragma unroll
;     for (int e2 = 0; e2 < 4; ++e2) {
;         const int j = (2 * e2) & 3;
;         const f32x4& w0 = e2 < 2 ? cw.w0a : cw.w0b; const f32x4& w1 = e2 < 2 ? cw.w1a : cw.w1b; const f32x4& w2 = e2 < 2 ? cw.w2a : cw.w2b; const f32x4& bb = e2 < 2 ? cw.ba : cw.bb;
;         y[2 * e2] = bf_lo(b0[e2]) * (w0[j] * (k2 * bf_lo(u2[e2]) * bf_lo(c2[e2])) + w1[j] * (k1 * bf_lo(u1[e2]) * bf_lo(c1[e2])) + w2[j] * (bf_lo(u0[e2]) * bf_lo(c0[e2])) + bb[j]);
;         y[2 * e2 + 1] = bf_hi(b0[e2]) * (w0[j + 1] * (k2 * bf_hi(u2[e2]) * bf_hi(c2[e2])) + w1[j + 1] * (k1 * bf_hi(u1[e2]) * bf_hi(c1[e2])) + w2[j + 1] * (bf_hi(u0[e2]) * bf_hi(c0[e2])) + bb[j + 1]);
;     }
; DI void mixer_phase(const Params& p, unsigned char* ldsraw, int vid) {
;     ...
;                 for (int j = 0; j < 8; ++j) {
;                     float y[8]; conv_tok(cw, RR, t0 + trow + 8 * j, ch, y);
;                     float ss = 0.f;
; #pragma unroll
;                     for (int e = 0; e < 8; ++e) ss += y[e] * y[e];
;                     ss += __shfl_xor(ss, 1); ss += __shfl_xor(ss, 2); ss += __shfl_xor(ss, 4);
;                     const int tk = trow + 8 * j;
;                     if (chunk == 0) lf[768 + 128 * (tk >> 5) + cgp * 32 + (tk & 31)] = ss;
.LBB0_421:
	s_or_b64 exec, exec, s[0:1]
	v_add_u32_e32 v38, 24, v146
	s_waitcnt lgkmcnt(0)
	v_ashrrev_i32_e32 v39, 31, v38
	v_lshlrev_b64 v[46:47], 12, v[38:39]
	v_lshl_add_u64 v[46:47], v[32:33], 0, v[46:47]
	global_load_dwordx4 v[60:63], v[46:47], off offset:512
	global_load_dwordx4 v[72:75], v[46:47], off
	global_load_dwordx4 v[76:79], v[46:47], off offset:1024
	v_max_i32_e32 v46, 1, v38
	v_max_i32_e32 v38, 2, v38
	v_mov_b32_e32 v39, v177
	v_add_u32_e32 v38, -2, v38
	v_lshlrev_b64 v[38:39], 12, v[38:39]
	v_add_u32_e32 v176, -1, v46
	v_lshl_add_u64 v[38:39], v[32:33], 0, v[38:39]
	global_load_dwordx4 v[80:83], v[38:39], off
	global_load_dwordx4 v[84:87], v[38:39], off offset:1024
	v_lshlrev_b64 v[46:47], 12, v[176:177]
	v_lshl_add_u64 v[38:39], v[32:33], 0, v[46:47]
	global_load_dwordx4 v[88:91], v[38:39], off
	global_load_dwordx4 v[92:95], v[38:39], off offset:1024
	s_movk_i32 s0, 0xffe8
	s_movk_i32 s8, 0xffe9
	v_cmp_lt_i32_e64 s[0:1], s0, v146
	s_waitcnt vmcnt(6)
	v_lshlrev_b32_e32 v58, 16, v60
	v_cndmask_b32_e64 v38, 0, 1.0, s[0:1]
	v_cmp_lt_i32_e64 s[0:1], s8, v146
	s_waitcnt vmcnt(5)
	v_lshlrev_b32_e32 v104, 16, v74
	v_and_b32_e32 v105, 0xffff0000, v74
	v_cndmask_b32_e64 v46, 0, 1.0, s[0:1]
	s_waitcnt vmcnt(4)
	v_lshlrev_b32_e32 v106, 16, v78
	v_and_b32_e32 v107, 0xffff0000, v78
	v_lshlrev_b32_e32 v98, 16, v72
	v_and_b32_e32 v99, 0xffff0000, v72
	s_waitcnt vmcnt(3)
	v_lshlrev_b32_e32 v108, 16, v80
	v_and_b32_e32 v109, 0xffff0000, v80
	v_lshlrev_b32_e32 v80, 16, v81
	v_and_b32_e32 v81, 0xffff0000, v81
	v_lshlrev_b32_e32 v100, 16, v76
	v_and_b32_e32 v101, 0xffff0000, v76
	v_lshlrev_b32_e32 v72, 16, v73
	v_and_b32_e32 v73, 0xffff0000, v73
	v_lshlrev_b32_e32 v76, 16, v77
	v_and_b32_e32 v77, 0xffff0000, v77
	s_waitcnt vmcnt(2)
	v_lshlrev_b32_e32 v110, 16, v84
	v_and_b32_e32 v111, 0xffff0000, v84
	s_waitcnt vmcnt(1)
	v_lshlrev_b32_e32 v112, 16, v88
	v_and_b32_e32 v113, 0xffff0000, v88
	v_lshlrev_b32_e32 v84, 16, v85
	v_and_b32_e32 v85, 0xffff0000, v85
	v_lshlrev_b32_e32 v88, 16, v89
	v_and_b32_e32 v89, 0xffff0000, v89
	v_mul_f32_e32 v104, v104, v106
	v_mul_f32_e32 v105, v105, v107
	v_mul_f32_e32 v106, v46, v108
	v_mul_f32_e32 v107, v46, v109
	v_mul_f32_e32 v80, v46, v80
	v_mul_f32_e32 v81, v46, v81
	s_waitcnt vmcnt(0)
	v_lshlrev_b32_e32 v114, 16, v92
	v_and_b32_e32 v115, 0xffff0000, v92
	v_lshlrev_b32_e32 v92, 16, v93
	v_and_b32_e32 v93, 0xffff0000, v93
	v_mul_f32_e32 v72, v72, v76
	v_mul_f32_e32 v73, v73, v77
	v_lshlrev_b32_e32 v76, 16, v82
	v_and_b32_e32 v77, 0xffff0000, v82
	v_mul_f32_e32 v108, v38, v112
	v_mul_f32_e32 v109, v38, v113
	v_mul_f32_e32 v88, v38, v88
	v_mul_f32_e32 v89, v38, v89
	v_mul_f32_e32 v106, v106, v110
	v_mul_f32_e32 v107, v107, v111
	v_mul_f32_e32 v80, v80, v84
	v_mul_f32_e32 v81, v81, v85
	v_mul_f32_e32 v98, v98, v100
	v_mul_f32_e32 v99, v99, v101
	v_lshlrev_b32_e32 v100, 16, v86
	v_and_b32_e32 v101, 0xffff0000, v86
	v_lshlrev_b32_e32 v116, 16, v90
	v_and_b32_e32 v117, 0xffff0000, v90
	v_mul_f32_e32 v76, v46, v76
	v_mul_f32_e32 v77, v46, v77
	v_mul_f32_e32 v108, v108, v114
	v_mul_f32_e32 v109, v109, v115
	v_mul_f32_e32 v84, v88, v92
	v_mul_f32_e32 v85, v89, v93
	v_mul_f32_e32 v92, v28, v106
	v_mul_f32_e32 v93, v29, v107
	v_mul_f32_e32 v80, v30, v80
	v_mul_f32_e32 v81, v31, v81
	v_lshlrev_b32_e32 v118, 16, v94
	v_and_b32_e32 v119, 0xffff0000, v94
	v_mul_f32_e32 v112, v38, v116
	v_mul_f32_e32 v113, v38, v117
	v_mul_f32_e32 v76, v76, v100
	v_mul_f32_e32 v77, v77, v101
	v_fma_f32 v92, v24, v108, v92
	v_fma_f32 v93, v25, v109, v93
	v_fma_f32 v80, v26, v84, v80
	v_fma_f32 v81, v27, v85, v81
	v_mul_f32_e32 v88, v112, v118
	v_mul_f32_e32 v89, v113, v119
	v_mul_f32_e32 v76, v12, v76
	v_mul_f32_e32 v77, v13, v77
	v_fma_f32 v84, v16, v98, v92
	v_fma_f32 v85, v17, v99, v93
	v_fma_f32 v72, v18, v72, v80
	v_fma_f32 v73, v19, v73, v81
	v_and_b32_e32 v59, 0xffff0000, v60
	v_lshlrev_b32_e32 v60, 16, v61
	v_and_b32_e32 v61, 0xffff0000, v61
	v_fma_f32 v76, v8, v88, v76
	v_fma_f32 v77, v9, v89, v77
	v_add_f32_e32 v80, v20, v84
	v_add_f32_e32 v81, v21, v85
	v_add_f32_e32 v84, v22, v72
	v_add_f32_e32 v85, v23, v73
	v_mul_f32_e32 v72, v80, v58
	v_mul_f32_e32 v73, v81, v59
	v_mul_f32_e32 v58, v84, v60
	v_mul_f32_e32 v59, v85, v61
	v_fma_f32 v60, v0, v104, v76
	v_fma_f32 v61, v1, v105, v77
	v_lshlrev_b32_e32 v76, 16, v83
	v_and_b32_e32 v77, 0xffff0000, v83
	v_mul_f32_e32 v47, v46, v77
	v_mul_f32_e32 v46, v46, v76
	v_lshlrev_b32_e32 v76, 16, v87
	v_and_b32_e32 v77, 0xffff0000, v87
	v_mul_f32_e32 v46, v46, v76
	v_mul_f32_e32 v47, v47, v77
	v_lshlrev_b32_e32 v76, 16, v91
	v_and_b32_e32 v77, 0xffff0000, v91
	v_mul_f32_e32 v39, v38, v77
	v_mul_f32_e32 v38, v38, v76
	v_lshlrev_b32_e32 v76, 16, v95
	v_and_b32_e32 v77, 0xffff0000, v95
	v_mul_f32_e32 v46, v14, v46
	v_mul_f32_e32 v47, v15, v47
	v_mul_f32_e32 v38, v38, v76
	v_mul_f32_e32 v39, v39, v77
	v_lshlrev_b32_e32 v74, 16, v79
	v_fma_f32 v38, v10, v38, v46
	v_fma_f32 v39, v11, v39, v47
	v_lshlrev_b32_e32 v46, 16, v75
	v_and_b32_e32 v47, 0xffff0000, v75
	v_and_b32_e32 v75, 0xffff0000, v79
	v_mul_f32_e32 v46, v46, v74
	v_mul_f32_e32 v47, v47, v75
	v_lshlrev_b32_e32 v102, 16, v62
	v_fma_f32 v38, v2, v46, v38
	v_fma_f32 v39, v3, v47, v39
	v_and_b32_e32 v103, 0xffff0000, v62
	v_lshlrev_b32_e32 v62, 16, v63
	v_and_b32_e32 v63, 0xffff0000, v63
	v_add_f32_e32 v38, v6, v38
	v_add_f32_e32 v39, v7, v39
	v_add_f32_e32 v60, v4, v60
	v_add_f32_e32 v61, v5, v61
	v_mul_f32_e32 v46, v38, v62
	v_mul_f32_e32 v47, v39, v63
	v_mul_f32_e32 v38, v72, v72
	v_mul_f32_e32 v39, v73, v73
	v_mul_f32_e32 v62, v58, v58
	v_mul_f32_e32 v63, v59, v59
	v_add_f32_e32 v38, v38, v39
	v_mul_f32_e32 v60, v60, v102
	v_mul_f32_e32 v61, v61, v103
	v_add_f32_e32 v38, v62, v38
	v_mul_f32_e32 v74, v60, v60
	v_mul_f32_e32 v75, v61, v61
	v_add_f32_e32 v38, v63, v38
	v_add_f32_e32 v38, v74, v38
	v_mul_f32_e32 v76, v46, v46
	v_mul_f32_e32 v77, v47, v47
	v_add_f32_e32 v38, v75, v38
	v_add_f32_e32 v38, v76, v38
	v_add_f32_e32 v38, v77, v38
	ds_bpermute_b32 v39, v34, v38
	s_waitcnt lgkmcnt(0)
	v_add_f32_e32 v38, v38, v39
	ds_bpermute_b32 v39, v35, v38
	s_waitcnt lgkmcnt(0)
	v_add_f32_e32 v38, v38, v39
	ds_bpermute_b32 v39, v36, v38
	s_and_saveexec_b64 s[0:1], vcc
	s_cbranch_execz .LBB0_423
	v_add_u32_e32 v62, 24, v163
	s_waitcnt lgkmcnt(0)
	v_add_f32_e32 v38, v38, v39
	v_and_b32_e32 v39, 31, v62
	v_lshlrev_b32_e32 v62, 4, v62
	v_and_b32_e32 v62, 0xfffffe00, v62
	v_lshlrev_b32_e32 v39, 2, v39
	v_add3_u32 v39, s75, v62, v39
	ds_write_b32 v39, v38 offset:3072
; DI float bf_lo(unsigned u) { return __uint_as_float(u << 16); }
; DI float bf_hi(unsigned u) { return __uint_as_float(u & 0xffff0000u); }
; DI void conv_tok(const ConvW& cw, const bf16_t* RR, int t, int ch, float (&y)[8]) {
;     const int t1 = t >= 1 ? t - 1 : 0, t2 = t >= 2 ? t - 2 : 0;
;     const float k1 = t >= 1 ? 1.f : 0.f, k2 = t >= 2 ? 1.f : 0.f;
;     const bf16_t* rp0 = RR + (size_t)t * 2048 + ch; const bf16_t* rp1 = RR + (size_t)t1 * 2048 + ch; const bf16_t* rp2 = RR + (size_t)t2 * 2048 + ch;
;     const u32x4 u0 = *(const u32x4*)rp0, b0 = *(const u32x4*)(rp0 + 256), c0 = *(const u32x4*)(rp0 + 512);
;     const u32x4 u1 = *(const u32x4*)rp1, c1 = *(const u32x4*)(rp1 + 512), u2 = *(const u32x4*)rp2, c2 = *(const u32x4*)(rp2 + 512);
; #pragma unroll
;     for (int e2 = 0; e2 < 4; ++e2) {
;         const int j = (2 * e2) & 3;
;         const f32x4& w0 = e2 < 2 ? cw.w0a : cw.w0b; const f32x4& w1 = e2 < 2 ? cw.w1a : cw.w1b; const f32x4& w2 = e2 < 2 ? cw.w2a : cw.w2b; const f32x4& bb = e2 < 2 ? cw.ba : cw.bb;
;         y[2 * e2] = bf_lo(b0[e2]) * (w0[j] * (k2 * bf_lo(u2[e2]) * bf_lo(c2[e2])) + w1[j] * (k1 * bf_lo(u1[e2]) * bf_lo(c1[e2])) + w2[j] * (bf_lo(u0[e2]) * bf_lo(c0[e2])) + bb[j]);
;         y[2 * e2 + 1] = bf_hi(b0[e2]) * (w0[j + 1] * (k2 * bf_hi(u2[e2]) * bf_hi(c2[e2])) + w1[j + 1] * (k1 * bf_hi(u1[e2]) * bf_hi(c1[e2])) + w2[j + 1] * (bf_hi(u0[e2]) * bf_hi(c0[e2])) + bb[j + 1]);
;     }
; DI void mixer_phase(const Params& p, unsigned char* ldsraw, int vid) {
;     ...
;                 for (int j = 0; j < 8; ++j) {
;                     float y[8]; conv_tok(cw, RR, t0 + trow + 8 * j, ch, y);
;                     float ss = 0.f;
; #pragma unroll
;                     for (int e = 0; e < 8; ++e) ss += y[e] * y[e];
;                     ss += __shfl_xor(ss, 1); ss += __shfl_xor(ss, 2); ss += __shfl_xor(ss, 4);
;                     const int tk = trow + 8 * j;
;                     if (chunk == 0) lf[768 + 128 * (tk >> 5) + cgp * 32 + (tk & 31)] = ss;
.LBB0_423:
	s_or_b64 exec, exec, s[0:1]
	v_add_u32_e32 v38, 32, v146
	s_waitcnt lgkmcnt(0)
	v_ashrrev_i32_e32 v39, 31, v38
	v_lshlrev_b64 v[62:63], 12, v[38:39]
	v_lshl_add_u64 v[62:63], v[32:33], 0, v[62:63]
	global_load_dwordx4 v[76:79], v[62:63], off offset:512
	global_load_dwordx4 v[80:83], v[62:63], off
	global_load_dwordx4 v[84:87], v[62:63], off offset:1024
	v_max_i32_e32 v62, 1, v38
	v_max_i32_e32 v38, 2, v38
	v_mov_b32_e32 v39, v177
	v_add_u32_e32 v38, -2, v38
	v_lshlrev_b64 v[38:39], 12, v[38:39]
	v_add_u32_e32 v176, -1, v62
	v_lshl_add_u64 v[38:39], v[32:33], 0, v[38:39]
	global_load_dwordx4 v[88:91], v[38:39], off
	global_load_dwordx4 v[92:95], v[38:39], off offset:1024
	v_lshlrev_b64 v[62:63], 12, v[176:177]
	v_lshl_add_u64 v[38:39], v[32:33], 0, v[62:63]
	global_load_dwordx4 v[98:101], v[38:39], off
	global_load_dwordx4 v[102:105], v[38:39], off offset:1024
	s_movk_i32 s0, 0xffe0
	s_movk_i32 s8, 0xffe1
	v_cmp_lt_i32_e64 s[0:1], s0, v146
	s_waitcnt vmcnt(6)
	v_lshlrev_b32_e32 v74, 16, v76
	v_cndmask_b32_e64 v38, 0, 1.0, s[0:1]
	v_cmp_lt_i32_e64 s[0:1], s8, v146
	s_waitcnt vmcnt(5)
	v_lshlrev_b32_e32 v112, 16, v82
	v_and_b32_e32 v113, 0xffff0000, v82
	v_cndmask_b32_e64 v62, 0, 1.0, s[0:1]
	s_waitcnt vmcnt(4)
	v_lshlrev_b32_e32 v114, 16, v86
	v_and_b32_e32 v115, 0xffff0000, v86
	v_lshlrev_b32_e32 v106, 16, v80
	v_and_b32_e32 v107, 0xffff0000, v80
	s_waitcnt vmcnt(3)
	v_lshlrev_b32_e32 v116, 16, v88
	v_and_b32_e32 v117, 0xffff0000, v88
	v_lshlrev_b32_e32 v108, 16, v84
	v_and_b32_e32 v109, 0xffff0000, v84
	v_lshlrev_b32_e32 v80, 16, v81
	v_and_b32_e32 v81, 0xffff0000, v81
	v_lshlrev_b32_e32 v84, 16, v85
	v_and_b32_e32 v85, 0xffff0000, v85
	s_waitcnt vmcnt(2)
	v_lshlrev_b32_e32 v118, 16, v92
	v_and_b32_e32 v119, 0xffff0000, v92
	s_waitcnt vmcnt(1)
	v_lshlrev_b32_e32 v120, 16, v98
	v_and_b32_e32 v121, 0xffff0000, v98
	v_lshlrev_b32_e32 v88, 16, v89
	v_and_b32_e32 v89, 0xffff0000, v89
	v_lshlrev_b32_e32 v98, 16, v99
	v_and_b32_e32 v99, 0xffff0000, v99
	v_mul_f32_e32 v112, v112, v114
	v_mul_f32_e32 v113, v113, v115
	v_mul_f32_e32 v114, v62, v116
	v_mul_f32_e32 v115, v62, v117
	s_waitcnt vmcnt(0)
	v_lshlrev_b32_e32 v122, 16, v102
	v_and_b32_e32 v123, 0xffff0000, v102
	v_lshlrev_b32_e32 v92, 16, v93
	v_and_b32_e32 v93, 0xffff0000, v93
	v_lshlrev_b32_e32 v102, 16, v103
	v_and_b32_e32 v103, 0xffff0000, v103
	v_mul_f32_e32 v80, v80, v84
	v_mul_f32_e32 v81, v81, v85
	v_lshlrev_b32_e32 v84, 16, v90
	v_and_b32_e32 v85, 0xffff0000, v90
	v_mul_f32_e32 v116, v38, v120
	v_mul_f32_e32 v117, v38, v121
	v_mul_f32_e32 v88, v62, v88
	v_mul_f32_e32 v89, v62, v89
	v_mul_f32_e32 v98, v38, v98
	v_mul_f32_e32 v99, v38, v99
	v_mul_f32_e32 v114, v114, v118
	v_mul_f32_e32 v115, v115, v119
	v_mul_f32_e32 v106, v106, v108
	v_mul_f32_e32 v107, v107, v109
	v_lshlrev_b32_e32 v108, 16, v94
	v_and_b32_e32 v109, 0xffff0000, v94
	v_lshlrev_b32_e32 v124, 16, v100
	v_and_b32_e32 v125, 0xffff0000, v100
	v_mul_f32_e32 v84, v62, v84
	v_mul_f32_e32 v85, v62, v85
	v_mul_f32_e32 v116, v116, v122
	v_mul_f32_e32 v117, v117, v123
	v_mul_f32_e32 v88, v88, v92
	v_mul_f32_e32 v89, v89, v93
	v_mul_f32_e32 v92, v98, v102
	v_mul_f32_e32 v93, v99, v103
	v_mul_f32_e32 v102, v28, v114
	v_mul_f32_e32 v103, v29, v115
	v_lshlrev_b32_e32 v126, 16, v104
	v_and_b32_e32 v127, 0xffff0000, v104
	v_mul_f32_e32 v120, v38, v124
	v_mul_f32_e32 v121, v38, v125
	v_mul_f32_e32 v84, v84, v108
	v_mul_f32_e32 v85, v85, v109
	v_mul_f32_e32 v88, v30, v88
	v_mul_f32_e32 v89, v31, v89
	v_fma_f32 v102, v24, v116, v102
	v_fma_f32 v103, v25, v117, v103
	v_mul_f32_e32 v98, v120, v126
	v_mul_f32_e32 v99, v121, v127
	v_mul_f32_e32 v84, v12, v84
	v_mul_f32_e32 v85, v13, v85
	v_fma_f32 v88, v26, v92, v88
	v_fma_f32 v89, v27, v93, v89
	v_fma_f32 v92, v16, v106, v102
	v_fma_f32 v93, v17, v107, v103
	v_and_b32_e32 v75, 0xffff0000, v76
	v_fma_f32 v84, v8, v98, v84
	v_fma_f32 v85, v9, v99, v85
	v_fma_f32 v80, v18, v80, v88
	v_fma_f32 v81, v19, v81, v89
	v_add_f32_e32 v88, v20, v92
	v_add_f32_e32 v89, v21, v93
	v_add_f32_e32 v92, v22, v80
	v_add_f32_e32 v93, v23, v81
	v_mul_f32_e32 v80, v88, v74
	v_mul_f32_e32 v81, v89, v75
	v_fma_f32 v74, v0, v112, v84
	v_fma_f32 v75, v1, v113, v85
	v_lshlrev_b32_e32 v84, 16, v91
	v_and_b32_e32 v85, 0xffff0000, v91
	v_mul_f32_e32 v63, v62, v85
	v_mul_f32_e32 v62, v62, v84
	v_lshlrev_b32_e32 v84, 16, v95
	v_and_b32_e32 v85, 0xffff0000, v95
	v_mul_f32_e32 v62, v62, v84
	v_mul_f32_e32 v63, v63, v85
	v_lshlrev_b32_e32 v84, 16, v101
	v_and_b32_e32 v85, 0xffff0000, v101
	v_mul_f32_e32 v39, v38, v85
	v_mul_f32_e32 v38, v38, v84
	v_lshlrev_b32_e32 v84, 16, v105
	v_and_b32_e32 v85, 0xffff0000, v105
	v_mul_f32_e32 v62, v14, v62
	v_mul_f32_e32 v63, v15, v63
	v_mul_f32_e32 v38, v38, v84
	v_mul_f32_e32 v39, v39, v85
	v_lshlrev_b32_e32 v82, 16, v87
	v_fma_f32 v38, v10, v38, v62
	v_fma_f32 v39, v11, v39, v63
	v_lshlrev_b32_e32 v62, 16, v83
	v_and_b32_e32 v63, 0xffff0000, v83
	v_and_b32_e32 v83, 0xffff0000, v87
	v_mul_f32_e32 v62, v62, v82
	v_mul_f32_e32 v63, v63, v83
	v_lshlrev_b32_e32 v76, 16, v77
	v_fma_f32 v38, v2, v62, v38
	v_fma_f32 v39, v3, v63, v39
	v_and_b32_e32 v77, 0xffff0000, v77
	v_lshlrev_b32_e32 v110, 16, v78
	v_and_b32_e32 v111, 0xffff0000, v78
	v_lshlrev_b32_e32 v78, 16, v79
	v_and_b32_e32 v79, 0xffff0000, v79
	v_add_f32_e32 v38, v6, v38
	v_add_f32_e32 v39, v7, v39
	v_mul_f32_e32 v76, v92, v76
	v_mul_f32_e32 v77, v93, v77
	v_mul_f32_e32 v78, v38, v78
	v_mul_f32_e32 v79, v39, v79
	v_mul_f32_e32 v38, v80, v80
	v_mul_f32_e32 v39, v81, v81
	v_add_f32_e32 v74, v4, v74
	v_add_f32_e32 v75, v5, v75
	v_mul_f32_e32 v62, v76, v76
	v_mul_f32_e32 v63, v77, v77
	v_add_f32_e32 v38, v38, v39
	v_mul_f32_e32 v74, v74, v110
	v_mul_f32_e32 v75, v75, v111
	v_add_f32_e32 v38, v62, v38
	v_mul_f32_e32 v82, v74, v74
	v_mul_f32_e32 v83, v75, v75
	v_add_f32_e32 v38, v63, v38
	v_add_f32_e32 v38, v82, v38
	v_mul_f32_e32 v84, v78, v78
	v_mul_f32_e32 v85, v79, v79
	v_add_f32_e32 v38, v83, v38
	v_add_f32_e32 v38, v84, v38
	v_add_f32_e32 v38, v85, v38
	ds_bpermute_b32 v39, v34, v38
	s_waitcnt lgkmcnt(0)
	v_add_f32_e32 v38, v38, v39
	ds_bpermute_b32 v39, v35, v38
	s_waitcnt lgkmcnt(0)
	v_add_f32_e32 v38, v38, v39
	ds_bpermute_b32 v39, v36, v38
	s_and_saveexec_b64 s[0:1], vcc
	s_cbranch_execz .LBB0_425
	v_lshrrev_b32_e32 v62, 1, v205
	v_and_b32_e32 v62, 0x7c, v62
	v_add3_u32 v37, s75, v37, v62
	s_waitcnt lgkmcnt(0)
	v_add_f32_e32 v38, v38, v39
	ds_write_b32 v37, v38 offset:3584
; DI float bf_lo(unsigned u) { return __uint_as_float(u << 16); }
; DI float bf_hi(unsigned u) { return __uint_as_float(u & 0xffff0000u); }
; DI void conv_tok(const ConvW& cw, const bf16_t* RR, int t, int ch, float (&y)[8]) {
;     const int t1 = t >= 1 ? t - 1 : 0, t2 = t >= 2 ? t - 2 : 0;
;     const float k1 = t >= 1 ? 1.f : 0.f, k2 = t >= 2 ? 1.f : 0.f;
;     const bf16_t* rp0 = RR + (size_t)t * 2048 + ch; const bf16_t* rp1 = RR + (size_t)t1 * 2048 + ch; const bf16_t* rp2 = RR + (size_t)t2 * 2048 + ch;
;     const u32x4 u0 = *(const u32x4*)rp0, b0 = *(const u32x4*)(rp0 + 256), c0 = *(const u32x4*)(rp0 + 512);
;     const u32x4 u1 = *(const u32x4*)rp1, c1 = *(const u32x4*)(rp1 + 512), u2 = *(const u32x4*)rp2, c2 = *(const u32x4*)(rp2 + 512);
; #pragma unroll
;     for (int e2 = 0; e2 < 4; ++e2) {
;         const int j = (2 * e2) & 3;
;         const f32x4& w0 = e2 < 2 ? cw.w0a : cw.w0b; const f32x4& w1 = e2 < 2 ? cw.w1a : cw.w1b; const f32x4& w2 = e2 < 2 ? cw.w2a : cw.w2b; const f32x4& bb = e2 < 2 ? cw.ba : cw.bb;
;         y[2 * e2] = bf_lo(b0[e2]) * (w0[j] * (k2 * bf_lo(u2[e2]) * bf_lo(c2[e2])) + w1[j] * (k1 * bf_lo(u1[e2]) * bf_lo(c1[e2])) + w2[j] * (bf_lo(u0[e2]) * bf_lo(c0[e2])) + bb[j]);
;         y[2 * e2 + 1] = bf_hi(b0[e2]) * (w0[j + 1] * (k2 * bf_hi(u2[e2]) * bf_hi(c2[e2])) + w1[j + 1] * (k1 * bf_hi(u1[e2]) * bf_hi(c1[e2])) + w2[j + 1] * (bf_hi(u0[e2]) * bf_hi(c0[e2])) + bb[j + 1]);
;     }
; DI void mixer_phase(const Params& p, unsigned char* ldsraw, int vid) {
;     ...
;                 for (int j = 0; j < 8; ++j) {
;                     float y[8]; conv_tok(cw, RR, t0 + trow + 8 * j, ch, y);
;                     float ss = 0.f;
; #pragma unroll
;                     for (int e = 0; e < 8; ++e) ss += y[e] * y[e];
;                     ss += __shfl_xor(ss, 1); ss += __shfl_xor(ss, 2); ss += __shfl_xor(ss, 4);
;                     const int tk = trow + 8 * j;
;                     if (chunk == 0) lf[768 + 128 * (tk >> 5) + cgp * 32 + (tk & 31)] = ss;
.LBB0_425:
	s_or_b64 exec, exec, s[0:1]
	v_add_u32_e32 v38, 40, v146
	s_waitcnt lgkmcnt(0)
	v_ashrrev_i32_e32 v39, 31, v38
	v_lshlrev_b64 v[62:63], 12, v[38:39]
	v_max_i32_e32 v37, 1, v38
	v_max_i32_e32 v38, 2, v38
	v_mov_b32_e32 v39, v177
	v_add_u32_e32 v38, -2, v38
	v_lshlrev_b64 v[38:39], 12, v[38:39]
	v_lshl_add_u64 v[62:63], v[32:33], 0, v[62:63]
	v_add_u32_e32 v176, -1, v37
	v_lshl_add_u64 v[38:39], v[32:33], 0, v[38:39]
	global_load_dwordx4 v[86:89], v[62:63], off offset:512
	global_load_dwordx4 v[90:93], v[62:63], off
	global_load_dwordx4 v[98:101], v[62:63], off offset:1024
	global_load_dwordx4 v[102:105], v[38:39], off
	global_load_dwordx4 v[106:109], v[38:39], off offset:1024
	v_lshlrev_b64 v[62:63], 12, v[176:177]
	v_lshl_add_u64 v[38:39], v[32:33], 0, v[62:63]
	global_load_dwordx4 v[110:113], v[38:39], off
	global_load_dwordx4 v[114:117], v[38:39], off offset:1024
	s_movk_i32 s0, 0xffd8
	s_movk_i32 s8, 0xffd9
	v_cmp_lt_i32_e64 s[0:1], s0, v146
	s_waitcnt vmcnt(6)
	v_lshlrev_b32_e32 v82, 16, v86
	v_cndmask_b32_e64 v38, 0, 1.0, s[0:1]
	v_cmp_lt_i32_e64 s[0:1], s8, v146
	s_waitcnt vmcnt(5)
	v_lshlrev_b32_e32 v84, 16, v90
	v_and_b32_e32 v85, 0xffff0000, v90
	v_cndmask_b32_e64 v62, 0, 1.0, s[0:1]
	s_waitcnt vmcnt(4)
	v_lshlrev_b32_e32 v94, 16, v98
	v_and_b32_e32 v95, 0xffff0000, v98
	v_lshlrev_b32_e32 v120, 16, v92
	v_and_b32_e32 v121, 0xffff0000, v92
	v_lshlrev_b32_e32 v122, 16, v100
	v_and_b32_e32 v123, 0xffff0000, v100
	s_waitcnt vmcnt(3)
	v_lshlrev_b32_e32 v124, 16, v102
	v_and_b32_e32 v125, 0xffff0000, v102
	v_and_b32_e32 v83, 0xffff0000, v86
	v_lshlrev_b32_e32 v118, 16, v87
	v_and_b32_e32 v119, 0xffff0000, v87
	v_lshlrev_b32_e32 v86, 16, v91
	v_and_b32_e32 v87, 0xffff0000, v91
	v_lshlrev_b32_e32 v90, 16, v99
	v_and_b32_e32 v91, 0xffff0000, v99
	s_waitcnt vmcnt(2)
	v_lshlrev_b32_e32 v126, 16, v106
	v_and_b32_e32 v127, 0xffff0000, v106
	s_waitcnt vmcnt(1)
	v_lshlrev_b32_e32 v128, 16, v110
	v_and_b32_e32 v129, 0xffff0000, v110
	v_mul_f32_e32 v84, v84, v94
	v_mul_f32_e32 v85, v85, v95
	v_lshlrev_b32_e32 v94, 16, v103
	v_and_b32_e32 v95, 0xffff0000, v103
	v_lshlrev_b32_e32 v102, 16, v107
	v_and_b32_e32 v103, 0xffff0000, v107
	v_lshlrev_b32_e32 v106, 16, v111
	v_and_b32_e32 v107, 0xffff0000, v111
	v_mul_f32_e32 v120, v120, v122
	v_mul_f32_e32 v121, v121, v123
	v_mul_f32_e32 v122, v62, v124
	v_mul_f32_e32 v123, v62, v125
	s_waitcnt vmcnt(0)
	v_lshlrev_b32_e32 v130, 16, v114
	v_and_b32_e32 v131, 0xffff0000, v114
	v_lshlrev_b32_e32 v110, 16, v115
	v_and_b32_e32 v111, 0xffff0000, v115
	v_mul_f32_e32 v86, v86, v90
	v_mul_f32_e32 v87, v87, v91
	v_lshlrev_b32_e32 v90, 16, v104
	v_and_b32_e32 v91, 0xffff0000, v104
	v_mul_f32_e32 v124, v38, v128
	v_mul_f32_e32 v125, v38, v129
	v_mul_f32_e32 v94, v62, v94
	v_mul_f32_e32 v95, v62, v95
	v_mul_f32_e32 v106, v38, v106
	v_mul_f32_e32 v107, v38, v107
	v_mul_f32_e32 v122, v122, v126
	v_mul_f32_e32 v123, v123, v127
	v_lshlrev_b32_e32 v114, 16, v108
	v_and_b32_e32 v115, 0xffff0000, v108
	v_lshlrev_b32_e32 v132, 16, v112
	v_and_b32_e32 v133, 0xffff0000, v112
	v_mul_f32_e32 v90, v62, v90
	v_mul_f32_e32 v91, v62, v91
	v_mul_f32_e32 v124, v124, v130
	v_mul_f32_e32 v125, v125, v131
	v_mul_f32_e32 v94, v94, v102
	v_mul_f32_e32 v95, v95, v103
	v_mul_f32_e32 v102, v106, v110
	v_mul_f32_e32 v103, v107, v111
	v_mul_f32_e32 v110, v28, v122
	v_mul_f32_e32 v111, v29, v123
	v_lshlrev_b32_e32 v134, 16, v116
	v_and_b32_e32 v135, 0xffff0000, v116
	v_mul_f32_e32 v128, v38, v132
	v_mul_f32_e32 v129, v38, v133
	v_mul_f32_e32 v90, v90, v114
	v_mul_f32_e32 v91, v91, v115
	v_mul_f32_e32 v94, v30, v94
	v_mul_f32_e32 v95, v31, v95
	v_fma_f32 v110, v24, v124, v110
	v_fma_f32 v111, v25, v125, v111
	v_mul_f32_e32 v106, v128, v134
	v_mul_f32_e32 v107, v129, v135
	v_mul_f32_e32 v90, v12, v90
	v_mul_f32_e32 v91, v13, v91
	v_fma_f32 v94, v26, v102, v94
	v_fma_f32 v95, v27, v103, v95
	v_fma_f32 v84, v16, v84, v110
	v_fma_f32 v85, v17, v85, v111
	v_fma_f32 v90, v8, v106, v90
	v_fma_f32 v91, v9, v107, v91
	v_fma_f32 v86, v18, v86, v94
	v_fma_f32 v87, v19, v87, v95
	v_add_f32_e32 v84, v20, v84
	v_add_f32_e32 v85, v21, v85
	v_add_f32_e32 v94, v22, v86
	v_add_f32_e32 v95, v23, v87
	v_mul_f32_e32 v86, v84, v82
	v_mul_f32_e32 v87, v85, v83
	v_fma_f32 v82, v0, v120, v90
	v_fma_f32 v83, v1, v121, v91
	v_lshlrev_b32_e32 v90, 16, v105
	v_and_b32_e32 v91, 0xffff0000, v105
	v_mul_f32_e32 v63, v62, v91
	v_mul_f32_e32 v62, v62, v90
	v_lshlrev_b32_e32 v90, 16, v109
	v_and_b32_e32 v91, 0xffff0000, v109
	v_mul_f32_e32 v62, v62, v90
	v_mul_f32_e32 v63, v63, v91
	v_lshlrev_b32_e32 v90, 16, v113
	v_and_b32_e32 v91, 0xffff0000, v113
	v_mul_f32_e32 v39, v38, v91
	v_mul_f32_e32 v38, v38, v90
	v_lshlrev_b32_e32 v90, 16, v117
	v_and_b32_e32 v91, 0xffff0000, v117
	v_mul_f32_e32 v62, v14, v62
	v_mul_f32_e32 v63, v15, v63
	v_mul_f32_e32 v38, v38, v90
	v_mul_f32_e32 v39, v39, v91
	v_lshlrev_b32_e32 v90, 16, v101
	v_fma_f32 v38, v10, v38, v62
	v_fma_f32 v39, v11, v39, v63
	v_lshlrev_b32_e32 v62, 16, v93
	v_and_b32_e32 v63, 0xffff0000, v93
	v_and_b32_e32 v91, 0xffff0000, v101
	v_mul_f32_e32 v62, v62, v90
	v_mul_f32_e32 v63, v63, v91
	v_lshlrev_b32_e32 v98, 16, v88
	v_fma_f32 v38, v2, v62, v38
	v_fma_f32 v39, v3, v63, v39
	v_and_b32_e32 v99, 0xffff0000, v88
	v_lshlrev_b32_e32 v88, 16, v89
	v_and_b32_e32 v89, 0xffff0000, v89
	v_add_f32_e32 v38, v6, v38
	v_add_f32_e32 v39, v7, v39
	v_mul_f32_e32 v84, v94, v118
	v_mul_f32_e32 v85, v95, v119
	v_mul_f32_e32 v62, v38, v88
	v_mul_f32_e32 v63, v39, v89
	v_mul_f32_e32 v38, v86, v86
	v_mul_f32_e32 v39, v87, v87
	v_add_f32_e32 v82, v4, v82
	v_add_f32_e32 v83, v5, v83
	v_mul_f32_e32 v88, v84, v84
	v_mul_f32_e32 v89, v85, v85
	v_add_f32_e32 v37, v38, v39
	v_mul_f32_e32 v82, v82, v98
	v_mul_f32_e32 v83, v83, v99
	v_add_f32_e32 v37, v88, v37
	v_mul_f32_e32 v90, v82, v82
	v_mul_f32_e32 v91, v83, v83
	v_add_f32_e32 v37, v89, v37
	v_add_f32_e32 v37, v90, v37
	v_mul_f32_e32 v92, v62, v62
	v_mul_f32_e32 v93, v63, v63
	v_add_f32_e32 v37, v91, v37
	v_add_f32_e32 v37, v92, v37
	v_add_f32_e32 v37, v93, v37
	ds_bpermute_b32 v38, v34, v37
	s_waitcnt lgkmcnt(0)
	v_add_f32_e32 v37, v37, v38
	ds_bpermute_b32 v38, v35, v37
	s_waitcnt lgkmcnt(0)
	v_add_f32_e32 v37, v37, v38
	ds_bpermute_b32 v38, v36, v37
	s_and_saveexec_b64 s[0:1], vcc
	s_cbranch_execz .LBB0_427
	v_add_u32_e32 v39, 40, v163
	s_waitcnt lgkmcnt(0)
	v_add_f32_e32 v37, v37, v38
	v_and_b32_e32 v38, 31, v39
	v_lshlrev_b32_e32 v39, 4, v39
	v_and_b32_e32 v39, 0xfffffe00, v39
	v_lshlrev_b32_e32 v38, 2, v38
	v_add3_u32 v38, s75, v39, v38
	ds_write_b32 v38, v37 offset:3072
; DI float bf_lo(unsigned u) { return __uint_as_float(u << 16); }
; DI float bf_hi(unsigned u) { return __uint_as_float(u & 0xffff0000u); }
; DI void conv_tok(const ConvW& cw, const bf16_t* RR, int t, int ch, float (&y)[8]) {
;     const int t1 = t >= 1 ? t - 1 : 0, t2 = t >= 2 ? t - 2 : 0;
;     const float k1 = t >= 1 ? 1.f : 0.f, k2 = t >= 2 ? 1.f : 0.f;
;     const bf16_t* rp0 = RR + (size_t)t * 2048 + ch; const bf16_t* rp1 = RR + (size_t)t1 * 2048 + ch; const bf16_t* rp2 = RR + (size_t)t2 * 2048 + ch;
;     const u32x4 u0 = *(const u32x4*)rp0, b0 = *(const u32x4*)(rp0 + 256), c0 = *(const u32x4*)(rp0 + 512);
;     const u32x4 u1 = *(const u32x4*)rp1, c1 = *(const u32x4*)(rp1 + 512), u2 = *(const u32x4*)rp2, c2 = *(const u32x4*)(rp2 + 512);
; #pragma unroll
;     for (int e2 = 0; e2 < 4; ++e2) {
;         const int j = (2 * e2) & 3;
;         const f32x4& w0 = e2 < 2 ? cw.w0a : cw.w0b; const f32x4& w1 = e2 < 2 ? cw.w1a : cw.w1b; const f32x4& w2 = e2 < 2 ? cw.w2a : cw.w2b; const f32x4& bb = e2 < 2 ? cw.ba : cw.bb;
;         y[2 * e2] = bf_lo(b0[e2]) * (w0[j] * (k2 * bf_lo(u2[e2]) * bf_lo(c2[e2])) + w1[j] * (k1 * bf_lo(u1[e2]) * bf_lo(c1[e2])) + w2[j] * (bf_lo(u0[e2]) * bf_lo(c0[e2])) + bb[j]);
;         y[2 * e2 + 1] = bf_hi(b0[e2]) * (w0[j + 1] * (k2 * bf_hi(u2[e2]) * bf_hi(c2[e2])) + w1[j + 1] * (k1 * bf_hi(u1[e2]) * bf_hi(c1[e2])) + w2[j + 1] * (bf_hi(u0[e2]) * bf_hi(c0[e2])) + bb[j + 1]);
;     }
; DI void mixer_phase(const Params& p, unsigned char* ldsraw, int vid) {
;     ...
;                 for (int j = 0; j < 8; ++j) {
;                     float y[8]; conv_tok(cw, RR, t0 + trow + 8 * j, ch, y);
;                     float ss = 0.f;
; #pragma unroll
;                     for (int e = 0; e < 8; ++e) ss += y[e] * y[e];
;                     ss += __shfl_xor(ss, 1); ss += __shfl_xor(ss, 2); ss += __shfl_xor(ss, 4);
;                     const int tk = trow + 8 * j;
;                     if (chunk == 0) lf[768 + 128 * (tk >> 5) + cgp * 32 + (tk & 31)] = ss;
.LBB0_427:
	s_or_b64 exec, exec, s[0:1]
	s_waitcnt lgkmcnt(0)
	v_add_u32_e32 v38, 48, v146
	v_ashrrev_i32_e32 v39, 31, v38
	v_lshlrev_b64 v[88:89], 12, v[38:39]
	v_max_i32_e32 v37, 1, v38
	v_max_i32_e32 v38, 2, v38
	v_mov_b32_e32 v39, v177
	v_add_u32_e32 v38, -2, v38
	v_lshlrev_b64 v[38:39], 12, v[38:39]
	v_lshl_add_u64 v[88:89], v[32:33], 0, v[88:89]
	v_add_u32_e32 v176, -1, v37
	v_lshl_add_u64 v[38:39], v[32:33], 0, v[38:39]
	global_load_dwordx4 v[90:93], v[88:89], off offset:512
	global_load_dwordx4 v[98:101], v[88:89], off
	global_load_dwordx4 v[102:105], v[88:89], off offset:1024
	global_load_dwordx4 v[106:109], v[38:39], off
	global_load_dwordx4 v[110:113], v[38:39], off offset:1024
	v_lshlrev_b64 v[88:89], 12, v[176:177]
	v_lshl_add_u64 v[38:39], v[32:33], 0, v[88:89]
	global_load_dwordx4 v[114:117], v[38:39], off
	global_load_dwordx4 v[118:121], v[38:39], off offset:1024
	s_movk_i32 s0, 0xffd0
	s_movk_i32 s8, 0xffd1
	v_cmp_lt_i32_e64 s[0:1], s0, v146
	s_waitcnt vmcnt(6)
	v_lshlrev_b32_e32 v88, 16, v90
	v_cndmask_b32_e64 v38, 0, 1.0, s[0:1]
	v_cmp_lt_i32_e64 s[0:1], s8, v146
	s_waitcnt vmcnt(3)
	v_lshlrev_b32_e32 v132, 16, v106
	v_and_b32_e32 v133, 0xffff0000, v106
	v_cndmask_b32_e64 v122, 0, 1.0, s[0:1]
	v_lshlrev_b32_e32 v106, 16, v107
	v_and_b32_e32 v107, 0xffff0000, v107
	v_lshlrev_b32_e32 v128, 16, v100
	v_and_b32_e32 v129, 0xffff0000, v100
	v_lshlrev_b32_e32 v130, 16, v104
	v_and_b32_e32 v131, 0xffff0000, v104
	s_waitcnt vmcnt(2)
	v_lshlrev_b32_e32 v134, 16, v110
	v_and_b32_e32 v135, 0xffff0000, v110
	s_waitcnt vmcnt(1)
	v_lshlrev_b32_e32 v136, 16, v114
	v_and_b32_e32 v137, 0xffff0000, v114
	v_lshlrev_b32_e32 v110, 16, v111
	v_and_b32_e32 v111, 0xffff0000, v111
	v_lshlrev_b32_e32 v114, 16, v115
	v_and_b32_e32 v115, 0xffff0000, v115
	v_mul_f32_e32 v106, v122, v106
	v_mul_f32_e32 v107, v122, v107
	v_lshlrev_b32_e32 v94, 16, v98
	v_and_b32_e32 v95, 0xffff0000, v98
	v_lshlrev_b32_e32 v124, 16, v102
	v_and_b32_e32 v125, 0xffff0000, v102
	v_lshlrev_b32_e32 v98, 16, v99
	v_and_b32_e32 v99, 0xffff0000, v99
	v_lshlrev_b32_e32 v102, 16, v103
	v_and_b32_e32 v103, 0xffff0000, v103
	s_waitcnt vmcnt(0)
	v_lshlrev_b32_e32 v138, 16, v118
	v_and_b32_e32 v139, 0xffff0000, v118
	v_lshlrev_b32_e32 v118, 16, v119
	v_and_b32_e32 v119, 0xffff0000, v119
	v_mul_f32_e32 v128, v128, v130
	v_mul_f32_e32 v129, v129, v131
	v_mul_f32_e32 v130, v122, v132
	v_mul_f32_e32 v131, v122, v133
	v_mul_f32_e32 v114, v38, v114
	v_mul_f32_e32 v115, v38, v115
	v_mul_f32_e32 v106, v106, v110
	v_mul_f32_e32 v107, v107, v111
	v_mul_f32_e32 v98, v98, v102
	v_mul_f32_e32 v99, v99, v103
	v_lshlrev_b32_e32 v102, 16, v108
	v_and_b32_e32 v103, 0xffff0000, v108
	v_mul_f32_e32 v132, v38, v136
	v_mul_f32_e32 v133, v38, v137
	v_mul_f32_e32 v130, v130, v134
	v_mul_f32_e32 v131, v131, v135
	v_mul_f32_e32 v110, v114, v118
	v_mul_f32_e32 v111, v115, v119
	v_mul_f32_e32 v106, v30, v106
	v_mul_f32_e32 v107, v31, v107
	v_mul_f32_e32 v94, v94, v124
	v_mul_f32_e32 v95, v95, v125
	v_lshlrev_b32_e32 v124, 16, v112
	v_and_b32_e32 v125, 0xffff0000, v112
	v_lshlrev_b32_e32 v148, 16, v116
	v_and_b32_e32 v149, 0xffff0000, v116
	v_mul_f32_e32 v102, v122, v102
	v_mul_f32_e32 v103, v122, v103
	v_mul_f32_e32 v132, v132, v138
	v_mul_f32_e32 v133, v133, v139
	v_mul_f32_e32 v118, v28, v130
	v_mul_f32_e32 v119, v29, v131
	v_fma_f32 v106, v26, v110, v106
	v_fma_f32 v107, v27, v111, v107
	v_lshlrev_b32_e32 v150, 16, v120
	v_and_b32_e32 v151, 0xffff0000, v120
	v_mul_f32_e32 v136, v38, v148
	v_mul_f32_e32 v137, v38, v149
	v_mul_f32_e32 v102, v102, v124
	v_mul_f32_e32 v103, v103, v125
	v_fma_f32 v118, v24, v132, v118
	v_fma_f32 v119, v25, v133, v119
	v_fma_f32 v98, v18, v98, v106
	v_fma_f32 v99, v19, v99, v107
	v_and_b32_e32 v89, 0xffff0000, v90
	v_lshlrev_b32_e32 v90, 16, v91
	v_and_b32_e32 v91, 0xffff0000, v91
	v_mul_f32_e32 v114, v136, v150
	v_mul_f32_e32 v115, v137, v151
	v_mul_f32_e32 v102, v12, v102
	v_mul_f32_e32 v103, v13, v103
	v_fma_f32 v94, v16, v94, v118
	v_fma_f32 v95, v17, v95, v119
	v_add_f32_e32 v98, v22, v98
	v_add_f32_e32 v99, v23, v99
	v_fma_f32 v102, v8, v114, v102
	v_fma_f32 v103, v9, v115, v103
	v_add_f32_e32 v94, v20, v94
	v_add_f32_e32 v95, v21, v95
	v_mul_f32_e32 v90, v98, v90
	v_mul_f32_e32 v91, v99, v91
	v_lshlrev_b32_e32 v98, 16, v109
	v_and_b32_e32 v99, 0xffff0000, v109
	v_mul_f32_e32 v94, v94, v88
	v_mul_f32_e32 v95, v95, v89
	v_fma_f32 v88, v0, v128, v102
	v_fma_f32 v89, v1, v129, v103
	v_mul_f32_e32 v98, v122, v98
	v_mul_f32_e32 v99, v122, v99
	v_lshlrev_b32_e32 v102, 16, v113
	v_and_b32_e32 v103, 0xffff0000, v113
	v_mul_f32_e32 v98, v98, v102
	v_mul_f32_e32 v99, v99, v103
	v_lshlrev_b32_e32 v102, 16, v117
	v_and_b32_e32 v103, 0xffff0000, v117
	v_mul_f32_e32 v39, v38, v103
	v_mul_f32_e32 v38, v38, v102
	v_lshlrev_b32_e32 v102, 16, v121
	v_and_b32_e32 v103, 0xffff0000, v121
	v_mul_f32_e32 v98, v14, v98
	v_mul_f32_e32 v99, v15, v99
	v_mul_f32_e32 v38, v38, v102
	v_mul_f32_e32 v39, v39, v103
	v_lshlrev_b32_e32 v100, 16, v105
	v_fma_f32 v38, v10, v38, v98
	v_fma_f32 v39, v11, v39, v99
	v_lshlrev_b32_e32 v98, 16, v101
	v_and_b32_e32 v99, 0xffff0000, v101
	v_and_b32_e32 v101, 0xffff0000, v105
	v_mul_f32_e32 v98, v98, v100
	v_mul_f32_e32 v99, v99, v101
	v_lshlrev_b32_e32 v126, 16, v92
	v_fma_f32 v38, v2, v98, v38
	v_fma_f32 v39, v3, v99, v39
	v_and_b32_e32 v127, 0xffff0000, v92
	v_lshlrev_b32_e32 v92, 16, v93
	v_and_b32_e32 v93, 0xffff0000, v93
	v_add_f32_e32 v38, v6, v38
	v_add_f32_e32 v39, v7, v39
	v_add_f32_e32 v88, v4, v88
	v_add_f32_e32 v89, v5, v89
	v_mul_f32_e32 v92, v38, v92
	v_mul_f32_e32 v93, v39, v93
	v_mul_f32_e32 v38, v94, v94
	v_mul_f32_e32 v39, v95, v95
	v_mul_f32_e32 v98, v90, v90
	v_mul_f32_e32 v99, v91, v91
	v_add_f32_e32 v37, v38, v39
	v_mul_f32_e32 v88, v88, v126
	v_mul_f32_e32 v89, v89, v127
	v_add_f32_e32 v37, v98, v37
	v_mul_f32_e32 v100, v88, v88
	v_mul_f32_e32 v101, v89, v89
	v_add_f32_e32 v37, v99, v37
	v_add_f32_e32 v37, v100, v37
	v_mul_f32_e32 v102, v92, v92
	v_mul_f32_e32 v103, v93, v93
	v_add_f32_e32 v37, v101, v37
	v_add_f32_e32 v37, v102, v37
	v_add_f32_e32 v37, v103, v37
	ds_bpermute_b32 v38, v34, v37
	s_waitcnt lgkmcnt(0)
	v_add_f32_e32 v37, v37, v38
	ds_bpermute_b32 v38, v35, v37
	s_waitcnt lgkmcnt(0)
	v_add_f32_e32 v37, v37, v38
	ds_bpermute_b32 v38, v36, v37
	s_and_saveexec_b64 s[0:1], vcc
	s_cbranch_execz .LBB0_429
	v_add_u32_e32 v39, 48, v163
	s_waitcnt lgkmcnt(0)
	v_add_f32_e32 v37, v37, v38
	v_and_b32_e32 v38, 31, v39
	v_lshlrev_b32_e32 v39, 4, v39
	v_and_b32_e32 v39, 0xfffffe00, v39
	v_lshlrev_b32_e32 v38, 2, v38
	v_add3_u32 v38, s75, v39, v38
	ds_write_b32 v38, v37 offset:3072
; DI float bf_lo(unsigned u) { return __uint_as_float(u << 16); }
; DI float bf_hi(unsigned u) { return __uint_as_float(u & 0xffff0000u); }
; DI void conv_tok(const ConvW& cw, const bf16_t* RR, int t, int ch, float (&y)[8]) {
;     const int t1 = t >= 1 ? t - 1 : 0, t2 = t >= 2 ? t - 2 : 0;
;     const float k1 = t >= 1 ? 1.f : 0.f, k2 = t >= 2 ? 1.f : 0.f;
;     const bf16_t* rp0 = RR + (size_t)t * 2048 + ch; const bf16_t* rp1 = RR + (size_t)t1 * 2048 + ch; const bf16_t* rp2 = RR + (size_t)t2 * 2048 + ch;
;     const u32x4 u0 = *(const u32x4*)rp0, b0 = *(const u32x4*)(rp0 + 256), c0 = *(const u32x4*)(rp0 + 512);
;     const u32x4 u1 = *(const u32x4*)rp1, c1 = *(const u32x4*)(rp1 + 512), u2 = *(const u32x4*)rp2, c2 = *(const u32x4*)(rp2 + 512);
; #pragma unroll
;     for (int e2 = 0; e2 < 4; ++e2) {
;         const int j = (2 * e2) & 3;
;         const f32x4& w0 = e2 < 2 ? cw.w0a : cw.w0b; const f32x4& w1 = e2 < 2 ? cw.w1a : cw.w1b; const f32x4& w2 = e2 < 2 ? cw.w2a : cw.w2b; const f32x4& bb = e2 < 2 ? cw.ba : cw.bb;
;         y[2 * e2] = bf_lo(b0[e2]) * (w0[j] * (k2 * bf_lo(u2[e2]) * bf_lo(c2[e2])) + w1[j] * (k1 * bf_lo(u1[e2]) * bf_lo(c1[e2])) + w2[j] * (bf_lo(u0[e2]) * bf_lo(c0[e2])) + bb[j]);
;         y[2 * e2 + 1] = bf_hi(b0[e2]) * (w0[j + 1] * (k2 * bf_hi(u2[e2]) * bf_hi(c2[e2])) + w1[j + 1] * (k1 * bf_hi(u1[e2]) * bf_hi(c1[e2])) + w2[j + 1] * (bf_hi(u0[e2]) * bf_hi(c0[e2])) + bb[j + 1]);
;     }
; DI void mixer_phase(const Params& p, unsigned char* ldsraw, int vid) {
;     ...
;                 for (int j = 0; j < 8; ++j) {
;                     float y[8]; conv_tok(cw, RR, t0 + trow + 8 * j, ch, y);
;                     float ss = 0.f;
; #pragma unroll
;                     for (int e = 0; e < 8; ++e) ss += y[e] * y[e];
;                     ss += __shfl_xor(ss, 1); ss += __shfl_xor(ss, 2); ss += __shfl_xor(ss, 4);
;                     const int tk = trow + 8 * j;
;                     if (chunk == 0) lf[768 + 128 * (tk >> 5) + cgp * 32 + (tk & 31)] = ss;
.LBB0_429:
	s_or_b64 exec, exec, s[0:1]
	s_waitcnt lgkmcnt(0)
	v_add_u32_e32 v38, 56, v146
	v_ashrrev_i32_e32 v39, 31, v38
	v_lshlrev_b64 v[98:99], 12, v[38:39]
	v_max_i32_e32 v37, 1, v38
	v_max_i32_e32 v38, 2, v38
	v_mov_b32_e32 v39, v177
	v_add_u32_e32 v38, -2, v38
	v_lshl_add_u64 v[98:99], v[32:33], 0, v[98:99]
	v_lshlrev_b64 v[38:39], 12, v[38:39]
	global_load_dwordx4 v[102:105], v[98:99], off offset:512
	global_load_dwordx4 v[106:109], v[98:99], off
	global_load_dwordx4 v[110:113], v[98:99], off offset:1024
	v_add_u32_e32 v176, -1, v37
	v_lshl_add_u64 v[38:39], v[32:33], 0, v[38:39]
	global_load_dwordx4 v[114:117], v[38:39], off
	global_load_dwordx4 v[118:121], v[38:39], off offset:1024
	v_lshlrev_b64 v[98:99], 12, v[176:177]
	v_lshl_add_u64 v[32:33], v[32:33], 0, v[98:99]
	global_load_dwordx4 v[122:125], v[32:33], off
	global_load_dwordx4 v[126:129], v[32:33], off offset:1024
	s_movk_i32 s0, 0xffc8
	s_movk_i32 s8, 0xffc9
	v_cmp_lt_i32_e64 s[0:1], s0, v146
	s_waitcnt vmcnt(6)
	v_lshlrev_b32_e32 v98, 16, v102
	v_cndmask_b32_e64 v32, 0, 1.0, s[0:1]
	v_cmp_lt_i32_e64 s[0:1], s8, v146
	v_and_b32_e32 v99, 0xffff0000, v102
	s_waitcnt vmcnt(5)
	v_lshlrev_b32_e32 v100, 16, v106
	v_and_b32_e32 v101, 0xffff0000, v106
	v_lshlrev_b32_e32 v132, 16, v103
	v_and_b32_e32 v133, 0xffff0000, v103
	v_lshlrev_b32_e32 v102, 16, v107
	v_and_b32_e32 v103, 0xffff0000, v107
	s_waitcnt vmcnt(4)
	v_lshlrev_b32_e32 v106, 16, v111
	v_and_b32_e32 v107, 0xffff0000, v111
	v_cndmask_b32_e64 v38, 0, 1.0, s[0:1]
	v_lshlrev_b32_e32 v130, 16, v110
	v_and_b32_e32 v131, 0xffff0000, v110
	v_mul_f32_e32 v102, v102, v106
	v_mul_f32_e32 v103, v103, v107
	s_waitcnt vmcnt(3)
	v_lshlrev_b32_e32 v106, 16, v116
	v_and_b32_e32 v107, 0xffff0000, v116
	v_lshlrev_b32_e32 v134, 16, v108
	v_and_b32_e32 v135, 0xffff0000, v108
	v_lshlrev_b32_e32 v136, 16, v112
	v_and_b32_e32 v137, 0xffff0000, v112
	v_lshlrev_b32_e32 v138, 16, v114
	v_and_b32_e32 v139, 0xffff0000, v114
	s_waitcnt vmcnt(1)
	v_lshlrev_b32_e32 v150, 16, v122
	v_and_b32_e32 v151, 0xffff0000, v122
	v_mul_f32_e32 v100, v100, v130
	v_mul_f32_e32 v101, v101, v131
	v_lshlrev_b32_e32 v114, 16, v115
	v_and_b32_e32 v115, 0xffff0000, v115
	v_lshlrev_b32_e32 v122, 16, v123
	v_and_b32_e32 v123, 0xffff0000, v123
	v_lshlrev_b32_e32 v130, 16, v120
	v_and_b32_e32 v131, 0xffff0000, v120
	v_lshlrev_b32_e32 v154, 16, v124
	v_and_b32_e32 v155, 0xffff0000, v124
	v_mul_f32_e32 v106, v38, v106
	v_mul_f32_e32 v107, v38, v107
	v_lshlrev_b32_e32 v148, 16, v118
	v_and_b32_e32 v149, 0xffff0000, v118
	s_waitcnt vmcnt(0)
	v_lshlrev_b32_e32 v152, 16, v126
	v_and_b32_e32 v153, 0xffff0000, v126
	v_lshlrev_b32_e32 v118, 16, v119
	v_and_b32_e32 v119, 0xffff0000, v119
	v_lshlrev_b32_e32 v126, 16, v127
	v_and_b32_e32 v127, 0xffff0000, v127
	v_lshlrev_b32_e32 v156, 16, v128
	v_and_b32_e32 v157, 0xffff0000, v128
	v_mul_f32_e32 v134, v134, v136
	v_mul_f32_e32 v135, v135, v137
	v_mul_f32_e32 v136, v38, v138
	v_mul_f32_e32 v137, v38, v139
	v_mul_f32_e32 v138, v32, v150
	v_mul_f32_e32 v139, v32, v151
	v_mul_f32_e32 v114, v38, v114
	v_mul_f32_e32 v115, v38, v115
	v_mul_f32_e32 v122, v32, v122
	v_mul_f32_e32 v123, v32, v123
	v_mul_f32_e32 v150, v32, v154
	v_mul_f32_e32 v151, v32, v155
	v_mul_f32_e32 v106, v106, v130
	v_mul_f32_e32 v107, v107, v131
	v_mul_f32_e32 v114, v114, v118
	v_mul_f32_e32 v115, v115, v119
	v_mul_f32_e32 v118, v122, v126
	v_mul_f32_e32 v119, v123, v127
	v_mul_f32_e32 v122, v150, v156
	v_mul_f32_e32 v123, v151, v157
	v_mul_f32_e32 v12, v12, v106
	v_mul_f32_e32 v13, v13, v107
	v_mul_f32_e32 v136, v136, v148
	v_mul_f32_e32 v137, v137, v149
	v_fma_f32 v8, v8, v122, v12
	v_fma_f32 v9, v9, v123, v13
	v_mul_f32_e32 v138, v138, v152
	v_mul_f32_e32 v139, v139, v153
	v_mul_f32_e32 v28, v28, v136
	v_mul_f32_e32 v29, v29, v137
	v_fma_f32 v0, v0, v134, v8
	v_fma_f32 v1, v1, v135, v9
	v_fma_f32 v24, v24, v138, v28
	v_fma_f32 v25, v25, v139, v29
	v_add_f32_e32 v0, v4, v0
	v_add_f32_e32 v1, v5, v1
	v_lshlrev_b32_e32 v4, 16, v117
	v_and_b32_e32 v5, 0xffff0000, v117
	v_mul_f32_e32 v30, v30, v114
	v_mul_f32_e32 v31, v31, v115
	v_fma_f32 v12, v16, v100, v24
	v_fma_f32 v13, v17, v101, v25
	v_mul_f32_e32 v4, v38, v4
	v_mul_f32_e32 v5, v38, v5
	v_lshlrev_b32_e32 v8, 16, v121
	v_and_b32_e32 v9, 0xffff0000, v121
	v_fma_f32 v26, v26, v118, v30
	v_fma_f32 v27, v27, v119, v31
	v_add_f32_e32 v12, v20, v12
	v_add_f32_e32 v13, v21, v13
	v_mul_f32_e32 v4, v4, v8
	v_mul_f32_e32 v5, v5, v9
	v_lshlrev_b32_e32 v8, 16, v125
	v_and_b32_e32 v9, 0xffff0000, v125
	v_fma_f32 v16, v18, v102, v26
	v_fma_f32 v17, v19, v103, v27
	v_mul_f32_e32 v102, v12, v98
	v_mul_f32_e32 v103, v13, v99
	v_mul_f32_e32 v8, v32, v8
	v_mul_f32_e32 v9, v32, v9
	v_lshlrev_b32_e32 v12, 16, v129
	v_and_b32_e32 v13, 0xffff0000, v129
	v_mul_f32_e32 v4, v14, v4
	v_mul_f32_e32 v5, v15, v5
	v_mul_f32_e32 v8, v8, v12
	v_mul_f32_e32 v9, v9, v13
	v_lshlrev_b32_e32 v110, 16, v104
	v_fma_f32 v4, v10, v8, v4
	v_fma_f32 v5, v11, v9, v5
	v_lshlrev_b32_e32 v8, 16, v109
	v_and_b32_e32 v9, 0xffff0000, v109
	v_lshlrev_b32_e32 v10, 16, v113
	v_and_b32_e32 v11, 0xffff0000, v113
	v_mul_f32_e32 v8, v8, v10
	v_mul_f32_e32 v9, v9, v11
	v_and_b32_e32 v111, 0xffff0000, v104
	v_fma_f32 v2, v2, v8, v4
	v_fma_f32 v3, v3, v9, v5
	v_add_f32_e32 v16, v22, v16
	v_add_f32_e32 v17, v23, v17
	v_mul_f32_e32 v98, v0, v110
	v_mul_f32_e32 v99, v1, v111
	v_lshlrev_b32_e32 v0, 16, v105
	v_and_b32_e32 v1, 0xffff0000, v105
	v_add_f32_e32 v2, v6, v2
	v_add_f32_e32 v3, v7, v3
	v_mul_f32_e32 v100, v16, v132
	v_mul_f32_e32 v101, v17, v133
	v_mul_f32_e32 v104, v2, v0
	v_mul_f32_e32 v105, v3, v1
	v_mul_f32_e32 v0, v102, v102
	v_mul_f32_e32 v1, v103, v103
	v_mul_f32_e32 v2, v100, v100
	v_mul_f32_e32 v3, v101, v101
	v_add_f32_e32 v0, v0, v1
	v_add_f32_e32 v0, v2, v0
	v_mul_f32_e32 v4, v98, v98
	v_mul_f32_e32 v5, v99, v99
	v_add_f32_e32 v0, v3, v0
	v_add_f32_e32 v0, v4, v0
	v_mul_f32_e32 v6, v104, v104
	v_mul_f32_e32 v7, v105, v105
	v_add_f32_e32 v0, v5, v0
	v_add_f32_e32 v0, v6, v0
	v_add_f32_e32 v0, v7, v0
	ds_bpermute_b32 v1, v34, v0
	s_waitcnt lgkmcnt(0)
	v_add_f32_e32 v0, v0, v1
	ds_bpermute_b32 v1, v35, v0
	s_waitcnt lgkmcnt(0)
	v_add_f32_e32 v0, v0, v1
	ds_bpermute_b32 v1, v36, v0
	s_and_saveexec_b64 s[0:1], vcc
	s_cbranch_execz .LBB0_431
	v_add_u32_e32 v2, 56, v163
	s_waitcnt lgkmcnt(0)
	v_add_f32_e32 v0, v0, v1
	v_and_b32_e32 v1, 31, v2
	v_lshlrev_b32_e32 v2, 4, v2
	v_and_b32_e32 v2, 0xfffffe00, v2
	v_lshlrev_b32_e32 v1, 2, v1
	v_add3_u32 v1, s75, v2, v1
	ds_write_b32 v1, v0 offset:3072

; DI void mem_tile(const KFrag& kf, const VFrag& vf, const bf16x8 (&qf)[4], float& mx, float& lsum, f32x16& m0, f32x16& m1) {
;     const f32x16 st = qk_mma(kf, qf);
;     float tm = st[0];
; #pragma unroll
;     for (int i = 1; i < 16; ++i) tm = __builtin_fmaxf(tm, st[i]);
;     tm = __builtin_fmaxf(tm, __shfl_xor(tm, 32));
;     const float nm = __builtin_fmaxf(mx, tm), alpha = __builtin_amdgcn_exp2f(mx - nm); mx = nm;
;     f32x16 w; float ps = 0.f;
; #pragma unroll
;     for (int i = 0; i < 16; ++i) { w[i] = __builtin_amdgcn_exp2f(st[i] - nm); ps += w[i]; }
;     lsum = lsum * alpha + ps;
; #pragma unroll
;     for (int i = 0; i < 16; ++i) { m0[i] *= alpha; m1[i] *= alpha; }
;     pv_mma(vf, w, m0, m1);
; }
; DI void mixer_phase(const Params& p, unsigned char* ldsraw, int vid) {
;     ...
;                 for (int mt = 0; mt < 8; ++mt) {
;                     const int nx = mt < 7 ? mt + 1 : 7;
;                     load_k(kn, kb + (size_t)(32 * nx) * 256); load_v(vn, vb + 32 * nx, 256);
;                     mem_tile(kc, vc, qfA, mxA, lsA, a0, a1);
;                     mem_tile(kc, vc, qfB, mxB, lsB, b0, b1);
;                     kc = kn; vc = vn;
;                 }
.LBB0_434:
	global_load_dwordx4 v[64:67], v[156:157], off
	global_load_dwordx4 v[128:131], v[156:157], off offset:32
	global_load_dwordx4 v[132:135], v[156:157], off offset:64
	global_load_dwordx4 v[136:139], v[156:157], off offset:96
	s_movk_i32 s1, 0x4000
	s_cmpk_lg_i32 s0, 0x100
	s_cselect_b32 s72, s0, 0xe0
	s_add_i32 s0, s0, 32
	s_lshl_b64 s[8:9], s[72:73], 9
	v_lshl_add_u64 v[156:157], v[148:149], 0, s[8:9]
	s_cmpk_eq_i32 s0, 0x120
	s_waitcnt vmcnt(3)
	v_mfma_f32_32x32x16_bf16 v[80:95], v[64:67], v[96:99], 0
	v_mfma_f32_32x32x16_bf16 v[64:79], v[64:67], v[104:107], 0
	s_waitcnt vmcnt(2)
	v_mfma_f32_32x32x16_bf16 v[80:95], v[128:131], v[100:103], v[80:95]
	v_mfma_f32_32x32x16_bf16 v[64:79], v[128:131], v[108:111], v[64:79]
	global_load_dwordx4 v[128:131], v[154:155], off offset:32
	s_waitcnt vmcnt(2)
	v_mfma_f32_32x32x16_bf16 v[80:95], v[132:135], v[112:115], v[80:95]
	v_mfma_f32_32x32x16_bf16 v[64:79], v[132:135], v[120:123], v[64:79]
	global_load_dwordx4 v[132:135], v[154:155], off
	v_add_co_u32_e32 v154, vcc, s1, v154
	s_nop 1
	v_addc_co_u32_e32 v155, vcc, 0, v155, vcc
	global_load_dwordx4 v[166:169], v[154:155], off offset:32
	global_load_dwordx4 v[170:173], v[154:155], off
	s_waitcnt vmcnt(4)
	v_mfma_f32_32x32x16_bf16 v[80:95], v[136:139], v[116:119], v[80:95]
	v_lshl_add_u64 v[154:155], s[72:73], 1, v[150:151]
	v_mfma_f32_32x32x16_bf16 v[64:79], v[136:139], v[124:127], v[64:79]
	s_nop 9
	v_max_f32_e32 v136, v81, v81
	v_max_f32_e32 v137, v80, v80
	v_max_f32_e32 v136, v137, v136
	v_max3_f32 v136, v136, v82, v83
	v_max3_f32 v136, v136, v84, v85
	v_max3_f32 v136, v136, v86, v87
	v_max3_f32 v136, v136, v88, v89
	v_max_f32_e32 v138, v65, v65
	v_max_f32_e32 v139, v64, v64
	v_max_f32_e32 v137, v139, v138
	v_max3_f32 v137, v137, v66, v67
	v_max3_f32 v137, v137, v68, v69
	v_max3_f32 v137, v137, v70, v71
	v_max3_f32 v137, v137, v72, v73
	v_max3_f32 v136, v136, v90, v91
	v_max3_f32 v137, v137, v74, v75
	v_max3_f32 v136, v136, v92, v93
	v_max3_f32 v137, v137, v76, v77
	v_max3_f32 v136, v136, v94, v95
	v_max3_f32 v137, v137, v78, v79
	ds_bpermute_b32 v138, v181, v136
	ds_bpermute_b32 v139, v181, v137
	s_waitcnt lgkmcnt(1)
	v_max3_f32 v136, v165, v136, v138
	s_waitcnt lgkmcnt(0)
	v_max3_f32 v137, v147, v137, v139
	v_sub_f32_e32 v139, v165, v136
	v_sub_f32_e32 v80, v80, v136
	v_sub_f32_e32 v81, v81, v136
	v_sub_f32_e32 v82, v82, v136
	v_sub_f32_e32 v83, v83, v136
	v_sub_f32_e32 v84, v84, v136
	v_sub_f32_e32 v85, v85, v136
	v_sub_f32_e32 v86, v86, v136
	v_sub_f32_e32 v87, v87, v136
	v_sub_f32_e32 v174, v92, v136
	v_sub_f32_e32 v175, v147, v137
	v_sub_f32_e32 v88, v88, v136
	v_sub_f32_e32 v89, v89, v136
	v_sub_f32_e32 v138, v90, v136
	v_sub_f32_e32 v91, v91, v136
	v_sub_f32_e32 v93, v93, v136
	v_sub_f32_e32 v182, v94, v136
	v_sub_f32_e32 v95, v95, v136
	v_sub_f32_e32 v64, v64, v137
	v_sub_f32_e32 v65, v65, v137
	v_sub_f32_e32 v66, v66, v137
	v_sub_f32_e32 v67, v67, v137
	v_sub_f32_e32 v68, v68, v137
	v_sub_f32_e32 v69, v69, v137
	v_sub_f32_e32 v70, v70, v137
	v_sub_f32_e32 v71, v71, v137
	v_sub_f32_e32 v183, v72, v137
	v_sub_f32_e32 v185, v74, v137
	v_sub_f32_e32 v187, v76, v137
	v_sub_f32_e32 v189, v78, v137
	v_mov_b32_e32 v165, v136
	v_exp_f32_e32 v72, v80
	v_exp_f32_e32 v74, v81
	v_exp_f32_e32 v76, v82
	v_exp_f32_e32 v78, v83
	v_exp_f32_e32 v80, v84
	v_exp_f32_e32 v82, v85
	v_exp_f32_e32 v84, v86
	v_exp_f32_e32 v86, v87
	v_exp_f32_e32 v136, v174
	v_exp_f32_e32 v174, v139
	v_exp_f32_e32 v175, v175
	v_sub_f32_e32 v184, v73, v137
	v_sub_f32_e32 v186, v75, v137
	v_sub_f32_e32 v188, v77, v137
	v_sub_f32_e32 v190, v79, v137
	v_exp_f32_e32 v73, v64
	v_exp_f32_e32 v75, v65
	v_exp_f32_e32 v77, v66
	v_exp_f32_e32 v79, v67
	v_exp_f32_e32 v81, v68
	v_exp_f32_e32 v83, v69
	v_exp_f32_e32 v85, v70
	v_exp_f32_e32 v87, v71
	v_cvt_pk_bf16_f32 v64, v72, v74
	v_cvt_pk_bf16_f32 v65, v76, v78
	v_cvt_pk_bf16_f32 v66, v80, v82
	v_mul_f32_e32 v62, v62, v174
	v_mul_f32_e32 v63, v63, v174
	v_mul_f32_e32 v60, v60, v174
	v_mul_f32_e32 v61, v61, v174
	v_mul_f32_e32 v58, v58, v174
	v_mul_f32_e32 v59, v59, v174
	v_mul_f32_e32 v56, v56, v174
	v_mul_f32_e32 v57, v57, v174
	v_mul_f32_e32 v54, v54, v174
	v_mul_f32_e32 v55, v55, v174
	v_mul_f32_e32 v52, v52, v174
	v_mul_f32_e32 v53, v53, v174
	v_mul_f32_e32 v50, v50, v174
	v_mul_f32_e32 v51, v51, v174
	v_mul_f32_e32 v48, v48, v174
	v_mul_f32_e32 v49, v49, v174
	v_mul_f32_e32 v46, v46, v174
	v_mul_f32_e32 v47, v47, v174
	v_mul_f32_e32 v44, v44, v174
	v_mul_f32_e32 v45, v45, v174
	v_mul_f32_e32 v42, v42, v174
	v_mul_f32_e32 v43, v43, v174
	v_mul_f32_e32 v40, v40, v174
	v_mul_f32_e32 v41, v41, v174
	v_mul_f32_e32 v38, v38, v174
	v_mul_f32_e32 v39, v39, v174
	v_mul_f32_e32 v36, v36, v174
	v_mul_f32_e32 v37, v37, v174
	v_cvt_pk_bf16_f32 v67, v84, v86
	v_mul_f32_e32 v34, v34, v174
	v_mul_f32_e32 v35, v35, v174
	v_mul_f32_e32 v32, v32, v174
	v_mul_f32_e32 v33, v33, v174
	v_mov_b32_e32 v176, v175
	s_waitcnt vmcnt(2)
	v_mfma_f32_32x32x16_bf16 v[48:63], v[132:135], v[64:67], v[48:63]
	v_cvt_pk_bf16_f32 v68, v73, v75
	v_cvt_pk_bf16_f32 v69, v77, v79
	v_cvt_pk_bf16_f32 v70, v81, v83
	v_cvt_pk_bf16_f32 v71, v85, v87
	v_mul_f32_e64 v30, v30, v176
	v_mul_f32_e64 v31, v31, v176
	v_mul_f32_e32 v28, v28, v176
	v_mul_f32_e32 v29, v29, v176
	v_mul_f32_e32 v26, v26, v176
	v_mul_f32_e32 v27, v27, v176
	s_waitcnt vmcnt(0)
; DI void mem_tile(const KFrag& kf, const VFrag& vf, const bf16x8 (&qf)[4], float& mx, float& lsum, f32x16& m0, f32x16& m1) {
;     ...
;     const float nm = __builtin_fmaxf(mx, tm), alpha = __builtin_amdgcn_exp2f(mx - nm); mx = nm;
;     f32x16 w; float ps = 0.f;
; #pragma unroll
;     for (int i = 0; i < 16; ++i) { w[i] = __builtin_amdgcn_exp2f(st[i] - nm); ps += w[i]; }
;     lsum = lsum * alpha + ps;
; #pragma unroll
;     for (int i = 0; i < 16; ++i) { m0[i] *= alpha; m1[i] *= alpha; }
;     pv_mma(vf, w, m0, m1);
	v_mfma_f32_32x32x16_bf16 v[32:47], v[170:173], v[64:67], v[32:47]
	v_mul_f32_e64 v24, v24, v176
	v_mul_f32_e64 v25, v25, v176
	v_mul_f32_e64 v22, v22, v176
	v_mul_f32_e64 v23, v23, v176
	v_mul_f32_e64 v20, v20, v176
	v_mul_f32_e64 v21, v21, v176
	v_mul_f32_e32 v18, v18, v176
	v_mul_f32_e32 v19, v19, v176
	v_mul_f32_e32 v16, v16, v176
	v_mul_f32_e32 v17, v17, v176
	v_mul_f32_e32 v14, v14, v176
	v_mul_f32_e32 v15, v15, v176
	v_mul_f32_e32 v12, v12, v176
	v_mul_f32_e32 v13, v13, v176
	v_mul_f32_e32 v10, v10, v176
	v_mul_f32_e32 v11, v11, v176
	v_mul_f32_e32 v8, v8, v176
	v_mul_f32_e32 v9, v9, v176
	v_mul_f32_e32 v6, v6, v176
	v_mul_f32_e32 v7, v7, v176
	v_mul_f32_e32 v4, v4, v176
	v_mul_f32_e32 v5, v5, v176
	v_mul_f32_e32 v2, v2, v176
	v_mul_f32_e32 v3, v3, v176
	v_mul_f32_e32 v0, v0, v176
	v_mul_f32_e32 v1, v1, v176
	v_pk_add_f32 v[72:73], v[72:73], 0 op_sel_hi:[1,0]
	v_mfma_f32_32x32x16_bf16 v[16:31], v[132:135], v[68:71], v[16:31]
	v_add_f32_e64 v72, v74, v72
	v_add_f32_e64 v73, v75, v73
	v_exp_f32_e32 v88, v88
	v_add_f32_e32 v72, v76, v72
	v_add_f32_e32 v73, v77, v73
	v_exp_f32_e32 v90, v89
	v_exp_f32_e32 v92, v138
	v_exp_f32_e32 v94, v91
	v_exp_f32_e32 v138, v93
	v_mfma_f32_32x32x16_bf16 v[0:15], v[170:173], v[68:71], v[0:15]
	v_exp_f32_e32 v68, v182
	v_exp_f32_e32 v70, v95
	v_add_f32_e32 v72, v78, v72
	v_add_f32_e32 v73, v79, v73
	v_mov_b32_e32 v147, v137
	v_exp_f32_e32 v89, v183
	v_exp_f32_e32 v91, v184
	v_exp_f32_e32 v93, v185
	v_exp_f32_e32 v95, v186
	v_exp_f32_e32 v137, v187
	v_exp_f32_e32 v139, v188
	v_exp_f32_e32 v69, v189
	v_exp_f32_e32 v71, v190
	v_add_f32_e32 v72, v80, v72
	v_add_f32_e32 v73, v81, v73
	v_cvt_pk_bf16_f32 v64, v88, v90
	v_add_f32_e32 v72, v82, v72
	v_add_f32_e32 v73, v83, v73
	v_cvt_pk_bf16_f32 v65, v92, v94
	v_add_f32_e32 v72, v84, v72
	v_add_f32_e32 v73, v85, v73
	v_cvt_pk_bf16_f32 v66, v136, v138
	v_cvt_pk_bf16_f32 v67, v68, v70
	v_add_f32_e32 v72, v86, v72
	v_add_f32_e32 v73, v87, v73
	s_nop 0
	v_mfma_f32_32x32x16_bf16 v[48:63], v[128:131], v[64:67], v[48:63]
	v_add_f32_e64 v72, v88, v72
	v_add_f32_e64 v73, v89, v73
	v_add_f32_e64 v72, v90, v72
	v_add_f32_e64 v73, v91, v73
	v_mfma_f32_32x32x16_bf16 v[32:47], v[166:169], v[64:67], v[32:47]
	v_cvt_pk_bf16_f32 v64, v89, v91
	v_cvt_pk_bf16_f32 v65, v93, v95
	v_cvt_pk_bf16_f32 v66, v137, v139
	v_cvt_pk_bf16_f32 v67, v69, v71
	s_nop 1
	v_mfma_f32_32x32x16_bf16 v[16:31], v[128:131], v[64:67], v[16:31]
	v_mfma_f32_32x32x16_bf16 v[0:15], v[166:169], v[64:67], v[0:15]
	v_add_f32_e64 v64, v92, v72
	v_add_f32_e64 v65, v93, v73
	v_add_f32_e64 v64, v94, v64
	v_add_f32_e64 v65, v95, v65
	v_add_f32_e64 v64, v136, v64
	v_add_f32_e64 v65, v137, v65
	v_add_f32_e32 v64, v138, v64
	v_add_f32_e32 v65, v139, v65
	s_nop 0
	v_add_f32_e32 v64, v68, v64
	v_add_f32_e32 v65, v69, v65
	s_nop 0
	v_add_f32_e32 v64, v70, v64
	v_add_f32_e32 v65, v71, v65
	s_nop 0
	v_fma_f32 v152, v152, v174, v64
	v_fma_f32 v153, v153, v175, v65
	s_cbranch_scc0 .LBB0_434
; DI float ssq32(const f32x16& a, const f32x16& b) {
;     float ss = 0.f;
; #pragma unroll
;     for (int i = 0; i < 16; ++i) ss += a[i] * a[i] + b[i] * b[i];
;     return ss + __shfl_xor(ss, 32);
; }
; DI void mixer_phase(const Params& p, unsigned char* ldsraw, int vid) {
;     ...
;                 lsA += __shfl_xor(lsA, 32); lsB += __shfl_xor(lsB, 32);
;                 const float iA = 1.0f / lsA, iB = 1.0f / lsB;
; #pragma unroll
;                 for (int i = 0; i < 16; ++i) { a0[i] *= iA; a1[i] *= iA; b0[i] *= iB; b1[i] *= iB; }
;                 const float sA = ssq32(a0, a1), sB = ssq32(b0, b1);
;                 if (hh == 0) { lf[512 + wid * 32 + r] = sA; lf[640 + wid * 32 + r] = sB; }
	ds_bpermute_b32 v64, v181, v152
	ds_bpermute_b32 v65, v181, v153
	s_waitcnt lgkmcnt(1)
	v_add_f32_e32 v64, v152, v64
	v_div_scale_f32 v66, s[0:1], v64, v64, 1.0
	v_rcp_f32_e32 v67, v66
	v_div_scale_f32 v68, vcc, 1.0, v64, 1.0
	s_waitcnt lgkmcnt(0)
	v_add_f32_e32 v65, v153, v65
	v_fma_f32 v70, -v66, v67, 1.0
	v_fmac_f32_e32 v67, v70, v67
	v_mul_f32_e32 v70, v68, v67
	v_fma_f32 v71, -v66, v70, v68
	v_div_scale_f32 v69, s[0:1], v65, v65, 1.0
	v_fmac_f32_e32 v70, v71, v67
	v_fma_f32 v66, -v66, v70, v68
	v_rcp_f32_e32 v68, v69
	v_div_fmas_f32 v66, v66, v67, v70
	v_div_fixup_f32 v96, v66, v64, 1.0
	v_mul_f32_e32 v48, v48, v96
	v_mul_f32_e32 v49, v49, v96
	v_fma_f32 v64, -v69, v68, 1.0
	v_fmac_f32_e32 v68, v64, v68
	v_div_scale_f32 v64, vcc, 1.0, v65, 1.0
	v_mul_f32_e32 v66, v64, v68
	v_fma_f32 v67, -v69, v66, v64
	v_fmac_f32_e32 v66, v67, v68
	v_fma_f32 v64, -v69, v66, v64
	v_div_fmas_f32 v64, v64, v68, v66
	v_div_fixup_f32 v104, v64, v65, 1.0
	v_mul_f32_e32 v64, v32, v96
	v_mul_f32_e32 v65, v33, v96
	v_mul_f32_e32 v94, v0, v104
	v_mul_f32_e32 v95, v1, v104
	v_mul_f32_e32 v66, v34, v96
	v_mul_f32_e32 v67, v35, v96
	v_mul_f32_e32 v0, v64, v64
	v_mul_f32_e32 v1, v65, v65
	v_mul_f32_e32 v50, v50, v96
	v_mul_f32_e32 v51, v51, v96
	v_mul_f32_e32 v90, v2, v104
	v_mul_f32_e32 v91, v3, v104
	v_fma_f32 v0, v48, v48, v0
	v_fma_f32 v1, v49, v49, v1
	v_mul_f32_e32 v2, v66, v66
	v_mul_f32_e32 v3, v67, v67
	v_mul_f32_e32 v68, v36, v96
	v_mul_f32_e32 v69, v37, v96
	v_fma_f32 v2, v50, v50, v2
	v_fma_f32 v3, v51, v51, v3
	v_add_f32_e32 v0, v0, v1
	v_mul_f32_e32 v52, v52, v96
	v_mul_f32_e32 v53, v53, v96
	v_mul_f32_e32 v88, v4, v104
	v_mul_f32_e32 v89, v5, v104
	v_mul_f32_e32 v4, v68, v68
	v_mul_f32_e32 v5, v69, v69
	v_add_f32_e32 v0, v2, v0
	v_mul_f32_e32 v70, v38, v96
	v_mul_f32_e32 v71, v39, v96
	v_fma_f32 v4, v52, v52, v4
	v_fma_f32 v5, v53, v53, v5
	v_add_f32_e32 v0, v3, v0
	v_mul_f32_e32 v80, v16, v104
	v_mul_f32_e32 v81, v17, v104
	v_mul_f32_e32 v54, v54, v96
	v_mul_f32_e32 v55, v55, v96
	v_mul_f32_e32 v92, v6, v104
	v_mul_f32_e32 v93, v7, v104
	v_mul_f32_e32 v6, v70, v70
	v_mul_f32_e32 v7, v71, v71
	v_add_f32_e32 v0, v4, v0
	v_mul_f32_e32 v2, v94, v94
	v_mul_f32_e32 v3, v95, v95
	v_mul_f32_e32 v76, v18, v104
	v_mul_f32_e32 v77, v19, v104
	v_mul_f32_e32 v72, v40, v96
	v_mul_f32_e32 v73, v41, v96
	v_fma_f32 v6, v54, v54, v6
	v_fma_f32 v7, v55, v55, v7
	v_add_f32_e32 v0, v5, v0
	v_fma_f32 v2, v80, v80, v2
	v_fma_f32 v3, v81, v81, v3
	v_mul_f32_e32 v4, v90, v90
	v_mul_f32_e32 v5, v91, v91
	v_mul_f32_e32 v56, v56, v96
	v_mul_f32_e32 v57, v57, v96
	v_mul_f32_e32 v102, v8, v104
	v_mul_f32_e32 v103, v9, v104
	v_mul_f32_e32 v8, v72, v72
	v_mul_f32_e32 v9, v73, v73
	v_add_f32_e32 v0, v6, v0
	v_fma_f32 v4, v76, v76, v4
	v_fma_f32 v5, v77, v77, v5
	v_add_f32_e32 v2, v2, v3
	v_mul_f32_e32 v74, v20, v104
	v_mul_f32_e32 v75, v21, v104
	v_mul_f32_e32 v40, v58, v96
	v_mul_f32_e32 v41, v59, v96
	v_mul_f32_e32 v58, v42, v96
	v_mul_f32_e32 v59, v43, v96
	v_fma_f32 v8, v56, v56, v8
	v_fma_f32 v9, v57, v57, v9
	v_add_f32_e32 v0, v7, v0
	v_mul_f32_e32 v6, v88, v88
	v_mul_f32_e32 v7, v89, v89
	v_add_f32_e32 v2, v4, v2
	v_mul_f32_e32 v100, v10, v104
	v_mul_f32_e32 v101, v11, v104
	v_mul_f32_e32 v10, v58, v58
	v_mul_f32_e32 v11, v59, v59
	v_add_f32_e32 v0, v8, v0
	v_fma_f32 v6, v74, v74, v6
	v_fma_f32 v7, v75, v75, v7
	v_add_f32_e32 v2, v5, v2
	v_mul_f32_e32 v78, v22, v104
	v_mul_f32_e32 v79, v23, v104
	v_mul_f32_e32 v42, v60, v96
	v_mul_f32_e32 v43, v61, v96
	v_mul_f32_e32 v60, v44, v96
	v_mul_f32_e32 v61, v45, v96
	v_fma_f32 v10, v40, v40, v10
	v_fma_f32 v11, v41, v41, v11
	v_add_f32_e32 v0, v9, v0
	v_mul_f32_e32 v8, v92, v92
	v_mul_f32_e32 v9, v93, v93
	v_add_f32_e32 v2, v6, v2
	v_mul_f32_e32 v98, v12, v104
	v_mul_f32_e32 v99, v13, v104
	v_mul_f32_e32 v12, v60, v60
	v_mul_f32_e32 v13, v61, v61
	v_add_f32_e32 v0, v10, v0
	v_fma_f32 v8, v78, v78, v8
	v_fma_f32 v9, v79, v79, v9
	v_add_f32_e32 v2, v7, v2
	v_mul_f32_e32 v86, v24, v104
	v_mul_f32_e32 v87, v25, v104
	v_mul_f32_e32 v46, v46, v96
	v_mul_f32_e32 v47, v47, v96
	v_fma_f32 v12, v42, v42, v12
	v_fma_f32 v13, v43, v43, v13
	v_add_f32_e32 v0, v11, v0
	v_mul_f32_e32 v10, v102, v102
	v_mul_f32_e32 v11, v103, v103
	v_add_f32_e32 v2, v8, v2
	v_mul_f32_e32 v84, v26, v104
	v_mul_f32_e32 v85, v27, v104
	v_mul_f32_e32 v82, v28, v104
	v_mul_f32_e32 v83, v29, v104
	v_mul_f32_e32 v44, v62, v96
	v_mul_f32_e32 v45, v63, v96
	v_mul_f32_e32 v62, v30, v104
	v_mul_f32_e32 v63, v31, v104
	v_mul_f32_e32 v105, v15, v104
	v_mul_f32_e32 v104, v14, v104
	v_mul_f32_e32 v14, v46, v46
	v_mul_f32_e32 v15, v47, v47
	v_add_f32_e32 v0, v12, v0
	v_fma_f32 v10, v86, v86, v10
	v_fma_f32 v11, v87, v87, v11
	v_add_f32_e32 v2, v9, v2
	v_fma_f32 v14, v44, v44, v14
	v_fma_f32 v15, v45, v45, v15
	v_add_f32_e32 v0, v13, v0
	v_mul_f32_e32 v12, v100, v100
	v_mul_f32_e32 v13, v101, v101
	v_add_f32_e32 v2, v10, v2
	v_add_f32_e32 v0, v14, v0
	v_fma_f32 v12, v84, v84, v12
	v_fma_f32 v13, v85, v85, v13
	v_add_f32_e32 v2, v11, v2
	v_add_f32_e32 v0, v15, v0
	v_mul_f32_e32 v14, v98, v98
	v_mul_f32_e32 v15, v99, v99
	v_add_f32_e32 v2, v12, v2
	v_fma_f32 v14, v82, v82, v14
	v_fma_f32 v15, v83, v83, v15
	v_add_f32_e32 v2, v13, v2
	v_mul_f32_e32 v16, v104, v104
	v_mul_f32_e32 v17, v105, v105
	v_add_f32_e32 v2, v14, v2
	v_fma_f32 v16, v62, v62, v16
	v_fma_f32 v17, v63, v63, v17
	v_add_f32_e32 v2, v15, v2
	v_add_f32_e32 v2, v16, v2
	v_add_f32_e32 v2, v17, v2
	ds_bpermute_b32 v1, v181, v0
	ds_bpermute_b32 v3, v181, v2
	s_and_saveexec_b64 s[0:1], s[4:5]
	s_cbranch_execz .LBB0_437
	v_lshl_add_u32 v4, v205, 2, s92
	s_waitcnt lgkmcnt(1)
	v_add_f32_e32 v0, v0, v1
	s_waitcnt lgkmcnt(0)
	v_add_f32_e32 v1, v2, v3
	ds_write2st64_b32 v4, v0, v1 offset0:8 offset1:10

; DI void mixer_phase(const Params& p, unsigned char* ldsraw, int vid) {
;     ...
;                 const int cgp = wid - 4, chunk = ln & 7, trow = ln >> 3, ch = 64 * cgp + 8 * chunk;
;                 const f32x4 ga = *(const f32x4*)(p.g_conv + ch), gb = *(const f32x4*)(p.g_conv + ch + 4);
;                 u32x4 gt[8]; float rsv[8];
; #pragma unroll
;                 for (int j = 0; j < 8; ++j) { const int tk = trow + 8 * j; const float* lp = lf + 768 + 128 * (tk >> 5) + (tk & 31);
;                     rsv[j] = rsqrtf(((lp[0] + lp[32]) + (lp[64] + lp[96])) * (1.0f / 256.0f) + EPS);
;                     gt[j] = *(const u32x4*)(gl + gate_off(tk, 512 + ch)); }
.LBB0_438:
	s_mov_b64 s[0:1], -1
	s_and_b64 vcc, exec, s[76:77]
	s_waitcnt lgkmcnt(0)
	s_barrier
	s_cbranch_vccz .LBB0_440
	v_lshlrev_b32_e32 v0, 2, v163
	v_and_b32_e32 v1, 0xfffffe00, v164
	v_and_b32_e32 v20, 0x7c, v0
	v_add3_u32 v0, 0, v1, v20
	v_add_u32_e32 v0, 0xc00, v0
	ds_read2_b32 v[8:9], v0 offset1:32
	ds_read2_b32 v[10:11], v0 offset0:64 offset1:96
	v_add_u32_e32 v16, 8, v163
	v_and_or_b32 v176, v180, 56, s94
	v_lshl_add_u64 v[4:5], v[176:177], 2, s[58:59]
	s_waitcnt lgkmcnt(1)
	v_mov_b32_e32 v12, v8
	s_waitcnt lgkmcnt(0)
	v_mov_b32_e32 v13, v10
	v_mov_b32_e32 v10, v9
	v_add_f32_e32 v8, v12, v10
	v_add_f32_e32 v9, v13, v11
	v_lshlrev_b32_e32 v10, 4, v16
	v_and_b32_e32 v11, 31, v16
	v_and_b32_e32 v10, 0xfffffe00, v10
	v_lshlrev_b32_e32 v11, 2, v11
	v_add3_u32 v10, 0, v10, v11
	v_add_u32_e32 v12, 0xc00, v10
	global_load_dwordx4 v[0:3], v[4:5], off offset:16
	s_nop 0
	global_load_dwordx4 v[4:7], v[4:5], off
	ds_read2_b32 v[10:11], v12 offset1:32
	ds_read2_b32 v[12:13], v12 offset0:64 offset1:96
	v_lshrrev_b32_e32 v109, 3, v176
	v_and_b32_e32 v14, 15, v163
	v_bitop3_b32 v14, v109, v14, 63 bitop3:0x6c
	v_lshl_add_u32 v111, v14, 4, s95
	s_waitcnt lgkmcnt(1)
	v_mov_b32_e32 v14, v10
	s_waitcnt lgkmcnt(0)
	v_mov_b32_e32 v15, v12
	v_mov_b32_e32 v12, v11
	v_add_f32_e32 v10, v14, v12
	v_add_f32_e32 v11, v15, v13
	v_mov_b32_e32 v13, v8
	v_mov_b32_e32 v12, v10
	v_mov_b32_e32 v8, v11
	s_mov_b32 s0, 0x358637bd
	v_add_f32_e32 v8, v12, v8
	v_add_f32_e32 v9, v13, v9
	v_mov_b64_e32 v[10:11], s[0:1]
	v_fma_f32 v8, v8, s88, v10
	v_fma_f32 v9, v9, s88, v10
	v_add_u32_e32 v21, 16, v163
	v_mul_f32_e32 v12, 0x4b800000, v9
	v_cmp_gt_f32_e32 vcc, s98, v9
	v_cmp_gt_f32_e64 s[0:1], s98, v8
	v_add_u32_e32 v22, 24, v163
	v_cndmask_b32_e32 v9, v9, v12, vcc
	v_mul_f32_e32 v12, 0x4b800000, v8
	v_rsq_f32_e32 v9, v9
	v_cndmask_b32_e64 v8, v8, v12, s[0:1]
	v_rsq_f32_e32 v8, v8
	v_lshl_add_u32 v12, v163, 11, v111
	v_mul_f32_e32 v13, 0x45800000, v9
	v_cndmask_b32_e32 v118, v9, v13, vcc
	v_mul_f32_e32 v9, 0x45800000, v8
	v_cndmask_b32_e64 v116, v8, v9, s[0:1]
	v_and_b32_e32 v8, 15, v16
	v_bitop3_b32 v8, v109, v8, 63 bitop3:0x6c
	v_lshlrev_b32_e32 v14, 4, v8
	v_lshlrev_b32_e32 v8, 4, v21
	v_and_b32_e32 v9, 31, v21
	v_and_b32_e32 v8, 0xfffffe00, v8
	v_lshlrev_b32_e32 v9, 2, v9
	v_add3_u32 v8, 0, v8, v9
	v_add_u32_e32 v15, 0xc00, v8
	ds_read2_b32 v[8:9], v15 offset1:32
	v_lshlrev_b32_e32 v13, 11, v16
	v_add3_u32 v13, s95, v14, v13
	ds_read_b128 v[36:39], v12 offset:5120
	ds_read_b128 v[32:35], v13 offset:5120
	ds_read2_b32 v[12:13], v15 offset0:64 offset1:96
	v_and_b32_e32 v15, 31, v22
	s_waitcnt lgkmcnt(3)
	v_mov_b32_e32 v14, v8
	v_lshlrev_b32_e32 v8, 4, v22
	v_and_b32_e32 v8, 0xfffffe00, v8
	v_lshlrev_b32_e32 v15, 2, v15
	v_add3_u32 v8, 0, v8, v15
	v_add_u32_e32 v8, 0xc00, v8
	ds_read2_b32 v[16:17], v8 offset1:32
	ds_read2_b32 v[18:19], v8 offset0:64 offset1:96
	s_waitcnt lgkmcnt(2)
	v_mov_b32_e32 v15, v12
	v_mov_b32_e32 v12, v9
	v_add_f32_e32 v8, v14, v12
	v_add_f32_e32 v9, v15, v13
	s_waitcnt lgkmcnt(1)
	v_mov_b32_e32 v12, v16
	s_waitcnt lgkmcnt(0)
	v_mov_b32_e32 v13, v18
	v_mov_b32_e32 v18, v17
	v_add_f32_e32 v12, v12, v18
	v_add_f32_e32 v13, v13, v19
	v_mov_b32_e32 v15, v8
	v_mov_b32_e32 v14, v12
	v_mov_b32_e32 v8, v13
	v_add_f32_e32 v8, v14, v8
	v_add_f32_e32 v9, v15, v9
	v_add_u32_e32 v113, 48, v163
	v_fma_f32 v8, v8, s88, v10
	v_fma_f32 v9, v9, s88, v10
	v_add_u32_e32 v115, 56, v163
	v_mul_f32_e32 v12, 0x4b800000, v9
	v_cmp_gt_f32_e32 vcc, s98, v9
	v_cmp_gt_f32_e64 s[0:1], s98, v8
	v_lshlrev_b32_e32 v120, 16, v36
	v_cndmask_b32_e32 v9, v9, v12, vcc
	v_mul_f32_e32 v12, 0x4b800000, v8
	v_rsq_f32_e32 v9, v9
	v_cndmask_b32_e64 v8, v8, v12, s[0:1]
	v_rsq_f32_e32 v8, v8
	v_lshl_add_u32 v12, v21, 11, v111
	v_mul_f32_e32 v13, 0x45800000, v9
	v_cndmask_b32_e32 v114, v9, v13, vcc
	v_mul_f32_e32 v9, 0x45800000, v8
	v_cndmask_b32_e64 v112, v8, v9, s[0:1]
	v_and_b32_e32 v8, 15, v22
	v_bitop3_b32 v8, v109, v8, 63 bitop3:0x6c
	v_add_u32_e32 v21, 32, v163
	v_lshlrev_b32_e32 v14, 4, v8
	v_lshlrev_b32_e32 v8, 4, v21
	v_and_b32_e32 v8, 0xfffffe00, v8
	v_add3_u32 v8, 0, v8, v20
	v_add_u32_e32 v15, 0xc00, v8
	ds_read2_b32 v[8:9], v15 offset1:32
	v_lshlrev_b32_e32 v13, 11, v22
	v_add3_u32 v13, s95, v14, v13
	v_add_u32_e32 v20, 40, v163
	ds_read_b128 v[28:31], v12 offset:5120
	ds_read_b128 v[24:27], v13 offset:5120
	ds_read2_b32 v[12:13], v15 offset0:64 offset1:96
	s_waitcnt lgkmcnt(3)
	v_mov_b32_e32 v14, v8
	v_lshlrev_b32_e32 v8, 4, v20
	v_and_b32_e32 v15, 31, v20
	v_and_b32_e32 v8, 0xfffffe00, v8
	v_lshlrev_b32_e32 v15, 2, v15
	v_add3_u32 v8, 0, v8, v15
	v_add_u32_e32 v8, 0xc00, v8
	ds_read2_b32 v[16:17], v8 offset1:32
	ds_read2_b32 v[18:19], v8 offset0:64 offset1:96
	s_waitcnt lgkmcnt(2)
	v_mov_b32_e32 v15, v12
	v_mov_b32_e32 v12, v9
	v_add_f32_e32 v8, v14, v12
	v_add_f32_e32 v9, v15, v13
	s_waitcnt lgkmcnt(1)
	v_mov_b32_e32 v12, v16
	s_waitcnt lgkmcnt(0)
	v_mov_b32_e32 v13, v18
	v_mov_b32_e32 v18, v17
	v_add_f32_e32 v12, v12, v18
	v_add_f32_e32 v13, v13, v19
	v_mov_b32_e32 v15, v8
	v_mov_b32_e32 v14, v12
	v_mov_b32_e32 v8, v13
	v_add_f32_e32 v8, v14, v8
	v_add_f32_e32 v9, v15, v9
	v_and_b32_e32 v121, 0xffff0000, v36
	v_fma_f32 v8, v8, s88, v10
	v_fma_f32 v9, v9, s88, v10
	v_lshlrev_b32_e32 v36, 16, v37
	v_mul_f32_e32 v12, 0x4b800000, v9
	v_cmp_gt_f32_e32 vcc, s98, v9
	v_cmp_gt_f32_e64 s[0:1], s98, v8
	v_and_b32_e32 v37, 0xffff0000, v37
	v_cndmask_b32_e32 v9, v9, v12, vcc
	v_mul_f32_e32 v12, 0x4b800000, v8
	v_rsq_f32_e32 v9, v9
	v_cndmask_b32_e64 v8, v8, v12, s[0:1]
	v_rsq_f32_e32 v8, v8
	v_lshl_add_u32 v12, v21, 11, v111
	v_mul_f32_e32 v13, 0x45800000, v9
	v_cndmask_b32_e32 v110, v9, v13, vcc
	v_mul_f32_e32 v9, 0x45800000, v8
	v_cndmask_b32_e64 v108, v8, v9, s[0:1]
	v_and_b32_e32 v8, 15, v20
	v_bitop3_b32 v8, v109, v8, 63 bitop3:0x6c
	v_lshlrev_b32_e32 v14, 4, v8
	v_lshlrev_b32_e32 v8, 4, v113
	v_and_b32_e32 v9, 31, v113
	v_and_b32_e32 v8, 0xfffffe00, v8
	v_lshlrev_b32_e32 v9, 2, v9
	v_add3_u32 v8, 0, v8, v9
	v_add_u32_e32 v15, 0xc00, v8
	ds_read2_b32 v[8:9], v15 offset1:32
	v_lshlrev_b32_e32 v13, 11, v20
	v_add3_u32 v13, s95, v14, v13
	ds_read_b128 v[20:23], v12 offset:5120
	ds_read_b128 v[16:19], v13 offset:5120
	ds_read2_b32 v[12:13], v15 offset0:64 offset1:96
	v_and_b32_e32 v15, 31, v115
	s_waitcnt lgkmcnt(3)
; DI unsigned pk_bf16(float lo, float hi) { f32x2 v = {lo, hi}; bf2_t b = __builtin_convertvector(v, bf2_t); return __builtin_bit_cast(unsigned, b); }
; DI float bf_lo(unsigned u) { return __uint_as_float(u << 16); }
; DI float bf_hi(unsigned u) { return __uint_as_float(u & 0xffff0000u); }
; DI float silu(float x) { return x * __builtin_amdgcn_rcpf(1.0f + __builtin_amdgcn_exp2f(-1.4426950408889634f * x)); }
; DI void mixer_phase(const Params& p, unsigned char* ldsraw, int vid) {
;     ...
;                 for (int j = 0; j < 8; ++j) { const int tk = trow + 8 * j; const float* lp = lf + 768 + 128 * (tk >> 5) + (tk & 31);
;                     rsv[j] = rsqrtf(((lp[0] + lp[32]) + (lp[64] + lp[96])) * (1.0f / 256.0f) + EPS);
;                     gt[j] = *(const u32x4*)(gl + gate_off(tk, 512 + ch)); }
; #pragma unroll
;                 for (int j = 0; j < 8; ++j) { const int tk = trow + 8 * j;
;                     const f32x16& o = (j < 2) ? a0 : (j < 4) ? a1 : (j < 6) ? b0 : b1; const int b8 = (j & 1) * 8; const float rs = rsv[j];
;                     u32x4 w; w.x = pk_bf16(o[b8 + 0] * rs * ga[0] * silu(bf_lo(gt[j].x)), o[b8 + 1] * rs * ga[1] * silu(bf_hi(gt[j].x)));
;                     w.y = pk_bf16(o[b8 + 2] * rs * ga[2] * silu(bf_lo(gt[j].y)), o[b8 + 3] * rs * ga[3] * silu(bf_hi(gt[j].y)));
;                     w.z = pk_bf16(o[b8 + 4] * rs * gb[0] * silu(bf_lo(gt[j].z)), o[b8 + 5] * rs * gb[1] * silu(bf_hi(gt[j].z)));
;                     w.w = pk_bf16(o[b8 + 6] * rs * gb[2] * silu(bf_lo(gt[j].w)), o[b8 + 7] * rs * gb[3] * silu(bf_hi(gt[j].w)));
;                     *(u32x4*)(Y + (size_t)(t0 + tk) * 1024 + 512 + ch) = w; }
	v_mov_b32_e32 v14, v8
	v_lshlrev_b32_e32 v8, 4, v115
	v_and_b32_e32 v8, 0xfffffe00, v8
	v_lshlrev_b32_e32 v15, 2, v15
	v_add3_u32 v8, 0, v8, v15
	v_add_u32_e32 v8, 0xc00, v8
	ds_read2_b32 v[96:97], v8 offset1:32
	ds_read2_b32 v[106:107], v8 offset0:64 offset1:96
	s_waitcnt lgkmcnt(2)
	v_mov_b32_e32 v15, v12
	v_mov_b32_e32 v12, v9
	v_add_f32_e32 v8, v14, v12
	v_add_f32_e32 v9, v15, v13
	s_waitcnt lgkmcnt(1)
	v_mov_b32_e32 v12, v96
	s_waitcnt lgkmcnt(0)
	v_mov_b32_e32 v13, v106
	v_mov_b32_e32 v106, v97
	v_add_f32_e32 v12, v12, v106
	v_add_f32_e32 v13, v13, v107
	v_mov_b32_e32 v15, v8
	v_mov_b32_e32 v14, v12
	v_mov_b32_e32 v8, v13
	v_add_f32_e32 v8, v14, v8
	v_add_f32_e32 v9, v15, v9
	v_mul_f32_e32 v12, 0xbfb8aa3b, v121
	v_fma_f32 v8, v8, s88, v10
	v_fma_f32 v9, v9, s88, v10
	v_exp_f32_e32 v12, v12
	v_mul_f32_e32 v10, 0x4b800000, v9
	v_cmp_gt_f32_e32 vcc, s98, v9
	v_cmp_gt_f32_e64 s[0:1], s98, v8
	v_mul_f32_e32 v97, 0xbfb8aa3b, v36
	v_cndmask_b32_e32 v9, v9, v10, vcc
	v_rsq_f32_e32 v9, v9
	v_mul_f32_e32 v10, 0x4b800000, v8
	v_cndmask_b32_e64 v8, v8, v10, s[0:1]
	v_rsq_f32_e32 v8, v8
	v_mul_f32_e32 v11, 0x45800000, v9
	v_cndmask_b32_e32 v106, v9, v11, vcc
	v_mul_f32_e32 v11, 0xbfb8aa3b, v120
	v_mul_f32_e32 v9, 0x45800000, v8
	v_exp_f32_e32 v11, v11
	v_cndmask_b32_e64 v96, v8, v9, s[0:1]
	v_and_b32_e32 v9, 15, v115
	v_bitop3_b32 v9, v109, v9, 63 bitop3:0x6c
	v_lshlrev_b32_e32 v8, 11, v115
	v_lshlrev_b32_e32 v9, 4, v9
	v_add3_u32 v8, s95, v9, v8
	v_add_f32_e32 v9, 1.0, v11
	v_rcp_f32_e32 v122, v9
	v_add_f32_e32 v9, 1.0, v12
	v_exp_f32_e32 v97, v97
	v_mul_f32_e32 v107, 0xbfb8aa3b, v37
	v_rcp_f32_e32 v123, v9
	v_exp_f32_e32 v107, v107
	v_add_f32_e32 v97, 1.0, v97
	v_mul_f32_e32 v124, v48, v118
	v_mul_f32_e32 v125, v49, v118
	v_mul_f32_e32 v120, v122, v120
	v_mul_f32_e32 v121, v123, v121
	v_rcp_f32_e32 v122, v97
	v_add_f32_e32 v97, 1.0, v107
	v_rcp_f32_e32 v123, v97
	s_waitcnt vmcnt(0)
	v_mul_f32_e32 v124, v4, v124
	v_mul_f32_e32 v125, v5, v125
	v_ashrrev_i32_e32 v147, 31, v146
	v_mul_f32_e32 v120, v120, v124
	v_mul_f32_e32 v121, v121, v125
	v_mul_f32_e32 v36, v122, v36
	v_mul_f32_e32 v37, v123, v37
	v_lshlrev_b32_e32 v122, 16, v38
	v_and_b32_e32 v123, 0xffff0000, v38
	v_mul_f32_e32 v38, 0xbfb8aa3b, v122
	v_exp_f32_e32 v38, v38
	v_mul_f32_e32 v97, 0xbfb8aa3b, v123
	v_exp_f32_e32 v97, v97
	v_mul_f32_e32 v124, v50, v118
	v_mul_f32_e32 v125, v51, v118
	v_add_f32_e32 v38, 1.0, v38
	v_mul_f32_e32 v124, v6, v124
	v_mul_f32_e32 v125, v7, v125
	v_cvt_pk_bf16_f32 v120, v120, v121
	v_mul_f32_e32 v36, v36, v124
	v_mul_f32_e32 v37, v37, v125
	v_rcp_f32_e32 v124, v38
	v_add_f32_e32 v38, 1.0, v97
	v_rcp_f32_e32 v125, v38
	v_lshlrev_b32_e32 v38, 16, v39
	v_and_b32_e32 v39, 0xffff0000, v39
	v_mul_f32_e32 v97, 0xbfb8aa3b, v38
	v_exp_f32_e32 v97, v97
	v_mul_f32_e32 v107, 0xbfb8aa3b, v39
	v_exp_f32_e32 v107, v107
	v_cvt_pk_bf16_f32 v121, v36, v37
	v_add_f32_e32 v97, 1.0, v97
	v_mul_f32_e32 v36, v52, v118
	v_mul_f32_e32 v37, v53, v118
	v_mul_f32_e32 v122, v124, v122
	v_mul_f32_e32 v123, v125, v123
	v_rcp_f32_e32 v124, v97
	v_add_f32_e32 v97, 1.0, v107
	v_mul_f32_e32 v36, v0, v36
	v_mul_f32_e32 v37, v1, v37
	v_rcp_f32_e32 v125, v97
	v_mul_f32_e32 v36, v122, v36
	v_mul_f32_e32 v37, v123, v37
	v_lshl_add_u32 v10, v113, 11, v111
	v_cvt_pk_bf16_f32 v122, v36, v37
	v_mul_f32_e32 v36, v54, v118
	v_mul_f32_e32 v37, v55, v118
	v_lshlrev_b32_e32 v118, 16, v32
	v_and_b32_e32 v119, 0xffff0000, v32
	v_mul_f32_e32 v32, 0xbfb8aa3b, v118
	v_mul_f32_e32 v36, v2, v36
	v_mul_f32_e32 v37, v3, v37
	v_mul_f32_e32 v38, v124, v38
	v_mul_f32_e32 v39, v125, v39
	v_exp_f32_e32 v32, v32
	v_mul_f32_e32 v97, 0xbfb8aa3b, v119
	v_mul_f32_e32 v36, v38, v36
	v_mul_f32_e32 v37, v39, v37
	v_exp_f32_e32 v97, v97
	v_cvt_pk_bf16_f32 v123, v36, v37
	v_lshlrev_b64 v[36:37], 11, v[146:147]
	v_lshl_add_u64 v[38:39], s[68:69], 0, v[36:37]
	v_lshlrev_b64 v[36:37], 1, v[176:177]
	v_lshl_add_u64 v[38:39], v[38:39], 0, v[36:37]
	v_add_f32_e32 v32, 1.0, v32
	ds_read_b128 v[12:15], v10 offset:5120
	ds_read_b128 v[8:11], v8 offset:5120
	v_rcp_f32_e32 v124, v32
	v_add_f32_e32 v32, 1.0, v97
	global_store_dwordx4 v[38:39], v[120:123], off offset:1024
	v_rcp_f32_e32 v125, v32
	v_mul_f32_e32 v38, v56, v116
	v_mul_f32_e32 v39, v57, v116
	v_lshlrev_b32_e32 v120, 16, v33
	v_and_b32_e32 v121, 0xffff0000, v33
	v_mul_f32_e32 v32, 0xbfb8aa3b, v120
	v_exp_f32_e32 v97, v32
	v_mul_f32_e32 v32, 0xbfb8aa3b, v121
	v_exp_f32_e32 v107, v32
	v_mul_f32_e32 v38, v4, v38
	v_mul_f32_e32 v39, v5, v39
	v_mul_f32_e32 v118, v124, v118
	v_mul_f32_e32 v119, v125, v119
	s_mov_b64 s[0:1], 0
	v_mul_f32_e32 v32, v118, v38
	v_mul_f32_e32 v33, v119, v39
	v_add_f32_e32 v38, 1.0, v97
	v_add_f32_e32 v39, 1.0, v107
	v_rcp_f32_e32 v38, v38
	v_rcp_f32_e32 v39, v39
	v_cvt_pk_bf16_f32 v32, v32, v33
	v_mul_f32_e32 v118, v40, v116
	v_mul_f32_e32 v119, v41, v116
	v_mul_f32_e32 v38, v38, v120
	v_mul_f32_e32 v39, v39, v121
	v_lshlrev_b32_e32 v120, 16, v34
	v_and_b32_e32 v121, 0xffff0000, v34
	v_mul_f32_e32 v33, 0xbfb8aa3b, v120
	v_exp_f32_e32 v33, v33
	v_mul_f32_e32 v34, 0xbfb8aa3b, v121
	v_exp_f32_e32 v34, v34
	v_mul_f32_e32 v118, v6, v118
	v_mul_f32_e32 v119, v7, v119
	v_add_f32_e32 v33, 1.0, v33
	v_mul_f32_e32 v38, v38, v118
	v_mul_f32_e32 v39, v39, v119
	v_rcp_f32_e32 v118, v33
	v_add_f32_e32 v33, 1.0, v34
	v_rcp_f32_e32 v119, v33
	v_cvt_pk_bf16_f32 v33, v38, v39
	v_mul_f32_e32 v38, v42, v116
	v_mul_f32_e32 v39, v43, v116
	v_mul_f32_e32 v117, v45, v116
	v_mul_f32_e32 v116, v44, v116
	v_mul_f32_e32 v118, v118, v120
	v_mul_f32_e32 v119, v119, v121
	v_lshlrev_b32_e32 v120, 16, v35
	v_and_b32_e32 v121, 0xffff0000, v35
	v_mul_f32_e32 v34, 0xbfb8aa3b, v120
; DI unsigned pk_bf16(float lo, float hi) { f32x2 v = {lo, hi}; bf2_t b = __builtin_convertvector(v, bf2_t); return __builtin_bit_cast(unsigned, b); }
; DI float bf_lo(unsigned u) { return __uint_as_float(u << 16); }
; DI float bf_hi(unsigned u) { return __uint_as_float(u & 0xffff0000u); }
; DI float silu(float x) { return x * __builtin_amdgcn_rcpf(1.0f + __builtin_amdgcn_exp2f(-1.4426950408889634f * x)); }
; DI void mixer_phase(const Params& p, unsigned char* ldsraw, int vid) {
;     ...
;                 for (int j = 0; j < 8; ++j) { const int tk = trow + 8 * j;
;                     const f32x16& o = (j < 2) ? a0 : (j < 4) ? a1 : (j < 6) ? b0 : b1; const int b8 = (j & 1) * 8; const float rs = rsv[j];
;                     u32x4 w; w.x = pk_bf16(o[b8 + 0] * rs * ga[0] * silu(bf_lo(gt[j].x)), o[b8 + 1] * rs * ga[1] * silu(bf_hi(gt[j].x)));
;                     w.y = pk_bf16(o[b8 + 2] * rs * ga[2] * silu(bf_lo(gt[j].y)), o[b8 + 3] * rs * ga[3] * silu(bf_hi(gt[j].y)));
;                     w.z = pk_bf16(o[b8 + 4] * rs * gb[0] * silu(bf_lo(gt[j].z)), o[b8 + 5] * rs * gb[1] * silu(bf_hi(gt[j].z)));
;                     w.w = pk_bf16(o[b8 + 6] * rs * gb[2] * silu(bf_lo(gt[j].w)), o[b8 + 7] * rs * gb[3] * silu(bf_hi(gt[j].w)));
;                     *(u32x4*)(Y + (size_t)(t0 + tk) * 1024 + 512 + ch) = w; }
	v_exp_f32_e32 v97, v34
	v_mul_f32_e32 v34, 0xbfb8aa3b, v121
	v_exp_f32_e32 v107, v34
	v_mul_f32_e32 v38, v0, v38
	v_mul_f32_e32 v39, v1, v39
	v_mul_f32_e32 v116, v2, v116
	v_mul_f32_e32 v117, v3, v117
	v_mul_f32_e32 v34, v118, v38
	v_mul_f32_e32 v35, v119, v39
	v_add_f32_e32 v38, 1.0, v97
	v_add_f32_e32 v39, 1.0, v107
	v_rcp_f32_e32 v38, v38
	v_rcp_f32_e32 v39, v39
	v_cvt_pk_bf16_f32 v34, v34, v35
	v_mul_f32_e32 v38, v38, v120
	v_mul_f32_e32 v39, v39, v121
	s_nop 0
	v_mul_f32_e32 v38, v38, v116
	v_mul_f32_e32 v39, v39, v117
	v_lshlrev_b32_e32 v116, 16, v28
	v_and_b32_e32 v117, 0xffff0000, v28
	v_mul_f32_e32 v28, 0xbfb8aa3b, v116
	v_cvt_pk_bf16_f32 v35, v38, v39
	v_add_u32_e32 v38, 8, v146
	v_exp_f32_e32 v28, v28
	v_mul_f32_e32 v97, 0xbfb8aa3b, v117
	v_ashrrev_i32_e32 v39, 31, v38
	v_exp_f32_e32 v97, v97
	v_lshlrev_b64 v[38:39], 11, v[38:39]
	v_lshl_add_u64 v[38:39], s[68:69], 0, v[38:39]
	v_lshl_add_u64 v[38:39], v[38:39], 0, v[36:37]
	v_add_f32_e32 v28, 1.0, v28
	v_rcp_f32_e32 v118, v28
	v_add_f32_e32 v28, 1.0, v97
	global_store_dwordx4 v[38:39], v[32:35], off offset:1024
	v_lshlrev_b32_e32 v38, 16, v29
	v_rcp_f32_e32 v119, v28
	v_and_b32_e32 v39, 0xffff0000, v29
	v_mul_f32_e32 v28, 0xbfb8aa3b, v38
	v_exp_f32_e32 v97, v28
	v_mul_f32_e32 v28, 0xbfb8aa3b, v39
	v_exp_f32_e32 v107, v28
	v_mul_f32_e32 v32, v64, v114
	v_mul_f32_e32 v33, v65, v114
	v_mul_f32_e32 v34, v118, v116
	v_mul_f32_e32 v35, v119, v117
	v_mul_f32_e32 v32, v4, v32
	v_mul_f32_e32 v33, v5, v33
	s_nop 0
	v_mul_f32_e32 v28, v34, v32
	v_mul_f32_e32 v29, v35, v33
	v_add_f32_e32 v32, 1.0, v97
	v_add_f32_e32 v33, 1.0, v107
	v_rcp_f32_e32 v32, v32
	v_rcp_f32_e32 v33, v33
	v_cvt_pk_bf16_f32 v28, v28, v29
	v_mul_f32_e32 v34, v66, v114
	v_mul_f32_e32 v35, v67, v114
	v_mul_f32_e32 v32, v32, v38
	v_mul_f32_e32 v33, v33, v39
	v_lshlrev_b32_e32 v38, 16, v30
	v_and_b32_e32 v39, 0xffff0000, v30
	v_mul_f32_e32 v29, 0xbfb8aa3b, v38
	v_exp_f32_e32 v29, v29
	v_mul_f32_e32 v30, 0xbfb8aa3b, v39
	v_exp_f32_e32 v30, v30
	v_mul_f32_e32 v34, v6, v34
	v_mul_f32_e32 v35, v7, v35
	v_add_f32_e32 v29, 1.0, v29
	v_mul_f32_e32 v32, v32, v34
	v_mul_f32_e32 v33, v33, v35
	v_rcp_f32_e32 v34, v29
	v_add_f32_e32 v29, 1.0, v30
	v_rcp_f32_e32 v35, v29
	v_cvt_pk_bf16_f32 v29, v32, v33
	v_mul_f32_e32 v32, v68, v114
	v_mul_f32_e32 v33, v69, v114
	v_mul_f32_e32 v34, v34, v38
	v_mul_f32_e32 v35, v35, v39
	v_lshlrev_b32_e32 v38, 16, v31
	v_and_b32_e32 v39, 0xffff0000, v31
	v_mul_f32_e32 v30, 0xbfb8aa3b, v38
	v_exp_f32_e32 v97, v30
	v_mul_f32_e32 v30, 0xbfb8aa3b, v39
	v_exp_f32_e32 v107, v30
	v_mul_f32_e32 v32, v0, v32
	v_mul_f32_e32 v33, v1, v33
	s_nop 0
	v_mul_f32_e32 v30, v34, v32
	v_mul_f32_e32 v31, v35, v33
	v_add_f32_e32 v32, 1.0, v97
	v_add_f32_e32 v33, 1.0, v107
	v_rcp_f32_e32 v32, v32
	v_rcp_f32_e32 v33, v33
	v_mul_f32_e32 v34, v70, v114
	v_mul_f32_e32 v35, v71, v114
	v_cvt_pk_bf16_f32 v30, v30, v31
	v_mul_f32_e32 v34, v2, v34
	v_mul_f32_e32 v35, v3, v35
	v_mul_f32_e32 v32, v32, v38
	v_mul_f32_e32 v33, v33, v39
	s_nop 0
	v_mul_f32_e32 v32, v32, v34
	v_mul_f32_e32 v33, v33, v35
	v_lshlrev_b32_e32 v34, 16, v24
	v_and_b32_e32 v35, 0xffff0000, v24
	v_mul_f32_e32 v24, 0xbfb8aa3b, v34
	v_exp_f32_e32 v24, v24
	v_mul_f32_e32 v38, 0xbfb8aa3b, v35
	v_exp_f32_e32 v39, v38
	v_cvt_pk_bf16_f32 v31, v32, v33
	v_add_u32_e32 v32, 16, v146
	v_ashrrev_i32_e32 v33, 31, v32
	v_add_f32_e32 v24, 1.0, v24
	v_lshlrev_b64 v[32:33], 11, v[32:33]
	v_rcp_f32_e32 v38, v24
	v_add_f32_e32 v24, 1.0, v39
	v_lshl_add_u64 v[32:33], s[68:69], 0, v[32:33]
	v_rcp_f32_e32 v39, v24
	v_lshl_add_u64 v[32:33], v[32:33], 0, v[36:37]
	global_store_dwordx4 v[32:33], v[28:31], off offset:1024
	v_lshlrev_b32_e32 v32, 16, v25
	v_and_b32_e32 v33, 0xffff0000, v25
	v_mul_f32_e32 v24, 0xbfb8aa3b, v32
	v_mul_f32_e32 v30, v38, v34
	v_mul_f32_e32 v31, v39, v35
	v_exp_f32_e32 v34, v24
	v_mul_f32_e32 v24, 0xbfb8aa3b, v33
	v_exp_f32_e32 v35, v24
	v_mul_f32_e32 v28, v72, v112
	v_mul_f32_e32 v29, v73, v112
	s_nop 0
	v_mul_f32_e32 v28, v4, v28
	v_mul_f32_e32 v29, v5, v29
	s_nop 0
	v_mul_f32_e32 v24, v30, v28
	v_mul_f32_e32 v25, v31, v29
	v_add_f32_e32 v28, 1.0, v34
	v_add_f32_e32 v29, 1.0, v35
	v_rcp_f32_e32 v28, v28
	v_rcp_f32_e32 v29, v29
	v_cvt_pk_bf16_f32 v24, v24, v25
	v_mul_f32_e32 v30, v58, v112
	v_mul_f32_e32 v31, v59, v112
	v_mul_f32_e32 v28, v28, v32
	v_mul_f32_e32 v29, v29, v33
	v_lshlrev_b32_e32 v32, 16, v26
	v_and_b32_e32 v33, 0xffff0000, v26
	v_mul_f32_e32 v25, 0xbfb8aa3b, v32
	v_exp_f32_e32 v25, v25
	v_mul_f32_e32 v26, 0xbfb8aa3b, v33
	v_exp_f32_e32 v26, v26
	v_mul_f32_e32 v30, v6, v30
	v_mul_f32_e32 v31, v7, v31
	v_add_f32_e32 v25, 1.0, v25
	v_mul_f32_e32 v28, v28, v30
	v_mul_f32_e32 v29, v29, v31
	v_rcp_f32_e32 v30, v25
	v_add_f32_e32 v25, 1.0, v26
	v_rcp_f32_e32 v31, v25
	v_cvt_pk_bf16_f32 v25, v28, v29
	v_mul_f32_e32 v28, v60, v112
	v_mul_f32_e32 v29, v61, v112
	v_mul_f32_e32 v30, v30, v32
	v_mul_f32_e32 v31, v31, v33
	v_lshlrev_b32_e32 v32, 16, v27
	v_and_b32_e32 v33, 0xffff0000, v27
	v_mul_f32_e32 v26, 0xbfb8aa3b, v32
	v_exp_f32_e32 v34, v26
	v_mul_f32_e32 v26, 0xbfb8aa3b, v33
	v_exp_f32_e32 v35, v26
	v_mul_f32_e32 v28, v0, v28
	v_mul_f32_e32 v29, v1, v29
	s_nop 0
	v_mul_f32_e32 v26, v30, v28
	v_mul_f32_e32 v27, v31, v29
	v_add_f32_e32 v28, 1.0, v34
	v_add_f32_e32 v29, 1.0, v35
	v_rcp_f32_e32 v28, v28
	v_rcp_f32_e32 v29, v29
	v_mul_f32_e32 v30, v46, v112
	v_mul_f32_e32 v31, v47, v112
	v_cvt_pk_bf16_f32 v26, v26, v27
	v_mul_f32_e32 v30, v2, v30
	v_mul_f32_e32 v31, v3, v31
	v_mul_f32_e32 v28, v28, v32
	v_mul_f32_e32 v29, v29, v33
	s_nop 0
	v_mul_f32_e32 v28, v28, v30
	v_mul_f32_e32 v29, v29, v31
	v_lshlrev_b32_e32 v30, 16, v20
	v_and_b32_e32 v31, 0xffff0000, v20
; DI unsigned pk_bf16(float lo, float hi) { f32x2 v = {lo, hi}; bf2_t b = __builtin_convertvector(v, bf2_t); return __builtin_bit_cast(unsigned, b); }
; DI float bf_lo(unsigned u) { return __uint_as_float(u << 16); }
; DI float bf_hi(unsigned u) { return __uint_as_float(u & 0xffff0000u); }
; DI float silu(float x) { return x * __builtin_amdgcn_rcpf(1.0f + __builtin_amdgcn_exp2f(-1.4426950408889634f * x)); }
; DI void mixer_phase(const Params& p, unsigned char* ldsraw, int vid) {
;     ...
;                 for (int j = 0; j < 8; ++j) { const int tk = trow + 8 * j;
;                     const f32x16& o = (j < 2) ? a0 : (j < 4) ? a1 : (j < 6) ? b0 : b1; const int b8 = (j & 1) * 8; const float rs = rsv[j];
;                     u32x4 w; w.x = pk_bf16(o[b8 + 0] * rs * ga[0] * silu(bf_lo(gt[j].x)), o[b8 + 1] * rs * ga[1] * silu(bf_hi(gt[j].x)));
;                     w.y = pk_bf16(o[b8 + 2] * rs * ga[2] * silu(bf_lo(gt[j].y)), o[b8 + 3] * rs * ga[3] * silu(bf_hi(gt[j].y)));
;                     w.z = pk_bf16(o[b8 + 4] * rs * gb[0] * silu(bf_lo(gt[j].z)), o[b8 + 5] * rs * gb[1] * silu(bf_hi(gt[j].z)));
;                     w.w = pk_bf16(o[b8 + 6] * rs * gb[2] * silu(bf_lo(gt[j].w)), o[b8 + 7] * rs * gb[3] * silu(bf_hi(gt[j].w)));
;                     *(u32x4*)(Y + (size_t)(t0 + tk) * 1024 + 512 + ch) = w; }
	v_mul_f32_e32 v20, 0xbfb8aa3b, v30
	v_exp_f32_e32 v20, v20
	v_mul_f32_e32 v32, 0xbfb8aa3b, v31
	v_exp_f32_e32 v33, v32
	v_cvt_pk_bf16_f32 v27, v28, v29
	v_add_u32_e32 v28, 24, v146
	v_ashrrev_i32_e32 v29, 31, v28
	v_add_f32_e32 v20, 1.0, v20
	v_lshlrev_b64 v[28:29], 11, v[28:29]
	v_rcp_f32_e32 v32, v20
	v_add_f32_e32 v20, 1.0, v33
	v_lshl_add_u64 v[28:29], s[68:69], 0, v[28:29]
	v_rcp_f32_e32 v33, v20
	v_lshl_add_u64 v[28:29], v[28:29], 0, v[36:37]
	global_store_dwordx4 v[28:29], v[24:27], off offset:1024
	v_lshlrev_b32_e32 v28, 16, v21
	v_and_b32_e32 v29, 0xffff0000, v21
	v_mul_f32_e32 v20, 0xbfb8aa3b, v28
	v_mul_f32_e32 v26, v32, v30
	v_mul_f32_e32 v27, v33, v31
	v_exp_f32_e32 v30, v20
	v_mul_f32_e32 v20, 0xbfb8aa3b, v29
	v_exp_f32_e32 v31, v20
	v_mul_f32_e32 v24, v80, v110
	v_mul_f32_e32 v25, v81, v110
	s_nop 0
	v_mul_f32_e32 v24, v4, v24
	v_mul_f32_e32 v25, v5, v25
	s_nop 0
	v_mul_f32_e32 v20, v26, v24
	v_mul_f32_e32 v21, v27, v25
	v_add_f32_e32 v24, 1.0, v30
	v_add_f32_e32 v25, 1.0, v31
	v_rcp_f32_e32 v24, v24
	v_rcp_f32_e32 v25, v25
	v_cvt_pk_bf16_f32 v20, v20, v21
	v_mul_f32_e32 v26, v76, v110
	v_mul_f32_e32 v27, v77, v110
	v_mul_f32_e32 v24, v24, v28
	v_mul_f32_e32 v25, v25, v29
	v_lshlrev_b32_e32 v28, 16, v22
	v_and_b32_e32 v29, 0xffff0000, v22
	v_mul_f32_e32 v21, 0xbfb8aa3b, v28
	v_exp_f32_e32 v21, v21
	v_mul_f32_e32 v22, 0xbfb8aa3b, v29
	v_exp_f32_e32 v22, v22
	v_mul_f32_e32 v26, v6, v26
	v_mul_f32_e32 v27, v7, v27
	v_add_f32_e32 v21, 1.0, v21
	v_mul_f32_e32 v24, v24, v26
	v_mul_f32_e32 v25, v25, v27
	v_rcp_f32_e32 v26, v21
	v_add_f32_e32 v21, 1.0, v22
	v_rcp_f32_e32 v27, v21
	v_cvt_pk_bf16_f32 v21, v24, v25
	v_mul_f32_e32 v24, v74, v110
	v_mul_f32_e32 v25, v75, v110
	v_mul_f32_e32 v26, v26, v28
	v_mul_f32_e32 v27, v27, v29
	v_lshlrev_b32_e32 v28, 16, v23
	v_and_b32_e32 v29, 0xffff0000, v23
	v_mul_f32_e32 v22, 0xbfb8aa3b, v28
	v_exp_f32_e32 v30, v22
	v_mul_f32_e32 v22, 0xbfb8aa3b, v29
	v_exp_f32_e32 v31, v22
	v_mul_f32_e32 v24, v0, v24
	v_mul_f32_e32 v25, v1, v25
	s_nop 0
	v_mul_f32_e32 v22, v26, v24
	v_mul_f32_e32 v23, v27, v25
	v_add_f32_e32 v24, 1.0, v30
	v_add_f32_e32 v25, 1.0, v31
	v_rcp_f32_e32 v24, v24
	v_rcp_f32_e32 v25, v25
	v_mul_f32_e32 v26, v78, v110
	v_mul_f32_e32 v27, v79, v110
	v_cvt_pk_bf16_f32 v22, v22, v23
	v_mul_f32_e32 v26, v2, v26
	v_mul_f32_e32 v27, v3, v27
	v_mul_f32_e32 v24, v24, v28
	v_mul_f32_e32 v25, v25, v29
	s_nop 0
	v_mul_f32_e32 v24, v24, v26
	v_mul_f32_e32 v25, v25, v27
	v_lshlrev_b32_e32 v26, 16, v16
	v_and_b32_e32 v27, 0xffff0000, v16
	v_mul_f32_e32 v16, 0xbfb8aa3b, v26
	v_exp_f32_e32 v16, v16
	v_mul_f32_e32 v28, 0xbfb8aa3b, v27
	v_exp_f32_e32 v29, v28
	v_cvt_pk_bf16_f32 v23, v24, v25
	v_add_u32_e32 v24, 32, v146
	v_ashrrev_i32_e32 v25, 31, v24
	v_add_f32_e32 v16, 1.0, v16
	v_lshlrev_b64 v[24:25], 11, v[24:25]
	v_rcp_f32_e32 v28, v16
	v_add_f32_e32 v16, 1.0, v29
	v_lshl_add_u64 v[24:25], s[68:69], 0, v[24:25]
	v_rcp_f32_e32 v29, v16
	v_lshl_add_u64 v[24:25], v[24:25], 0, v[36:37]
	global_store_dwordx4 v[24:25], v[20:23], off offset:1024
	v_lshlrev_b32_e32 v24, 16, v17
	v_and_b32_e32 v25, 0xffff0000, v17
	v_mul_f32_e32 v16, 0xbfb8aa3b, v24
	v_mul_f32_e32 v22, v28, v26
	v_mul_f32_e32 v23, v29, v27
	v_exp_f32_e32 v26, v16
	v_mul_f32_e32 v16, 0xbfb8aa3b, v25
	v_exp_f32_e32 v27, v16
	v_mul_f32_e32 v20, v86, v108
	v_mul_f32_e32 v21, v87, v108
	s_nop 0
	v_mul_f32_e32 v20, v4, v20
	v_mul_f32_e32 v21, v5, v21
	s_nop 0
	v_mul_f32_e32 v16, v22, v20
	v_mul_f32_e32 v17, v23, v21
	v_add_f32_e32 v20, 1.0, v26
	v_add_f32_e32 v21, 1.0, v27
	v_rcp_f32_e32 v20, v20
	v_rcp_f32_e32 v21, v21
	v_cvt_pk_bf16_f32 v16, v16, v17
	v_mul_f32_e32 v22, v84, v108
	v_mul_f32_e32 v23, v85, v108
	v_mul_f32_e32 v20, v20, v24
	v_mul_f32_e32 v21, v21, v25
	v_lshlrev_b32_e32 v24, 16, v18
	v_and_b32_e32 v25, 0xffff0000, v18
	v_mul_f32_e32 v17, 0xbfb8aa3b, v24
	v_exp_f32_e32 v17, v17
	v_mul_f32_e32 v18, 0xbfb8aa3b, v25
	v_exp_f32_e32 v18, v18
	v_mul_f32_e32 v22, v6, v22
	v_mul_f32_e32 v23, v7, v23
	v_add_f32_e32 v17, 1.0, v17
	v_mul_f32_e32 v20, v20, v22
	v_mul_f32_e32 v21, v21, v23
	v_rcp_f32_e32 v22, v17
	v_add_f32_e32 v17, 1.0, v18
	v_rcp_f32_e32 v23, v17
	v_cvt_pk_bf16_f32 v17, v20, v21
	v_mul_f32_e32 v20, v82, v108
	v_mul_f32_e32 v21, v83, v108
	v_mul_f32_e32 v22, v22, v24
	v_mul_f32_e32 v23, v23, v25
	v_lshlrev_b32_e32 v24, 16, v19
	v_and_b32_e32 v25, 0xffff0000, v19
	v_mul_f32_e32 v18, 0xbfb8aa3b, v24
	v_exp_f32_e32 v26, v18
	v_mul_f32_e32 v18, 0xbfb8aa3b, v25
	v_exp_f32_e32 v27, v18
	v_mul_f32_e32 v20, v0, v20
	v_mul_f32_e32 v21, v1, v21
	s_nop 0
	v_mul_f32_e32 v18, v22, v20
	v_mul_f32_e32 v19, v23, v21
	v_add_f32_e32 v20, 1.0, v26
	v_add_f32_e32 v21, 1.0, v27
	v_rcp_f32_e32 v20, v20
	v_rcp_f32_e32 v21, v21
	v_mul_f32_e32 v22, v62, v108
	v_mul_f32_e32 v23, v63, v108
	v_cvt_pk_bf16_f32 v18, v18, v19
	v_mul_f32_e32 v22, v2, v22
	v_mul_f32_e32 v23, v3, v23
	v_mul_f32_e32 v20, v20, v24
	v_mul_f32_e32 v21, v21, v25
	s_nop 0
	v_mul_f32_e32 v20, v20, v22
	v_mul_f32_e32 v21, v21, v23
	s_waitcnt lgkmcnt(1)
; DI unsigned pk_bf16(float lo, float hi) { f32x2 v = {lo, hi}; bf2_t b = __builtin_convertvector(v, bf2_t); return __builtin_bit_cast(unsigned, b); }
; DI float bf_lo(unsigned u) { return __uint_as_float(u << 16); }
; DI float bf_hi(unsigned u) { return __uint_as_float(u & 0xffff0000u); }
; DI float silu(float x) { return x * __builtin_amdgcn_rcpf(1.0f + __builtin_amdgcn_exp2f(-1.4426950408889634f * x)); }
; DI void mixer_phase(const Params& p, unsigned char* ldsraw, int vid) {
;     ...
;                 for (int j = 0; j < 8; ++j) { const int tk = trow + 8 * j;
;                     const f32x16& o = (j < 2) ? a0 : (j < 4) ? a1 : (j < 6) ? b0 : b1; const int b8 = (j & 1) * 8; const float rs = rsv[j];
;                     u32x4 w; w.x = pk_bf16(o[b8 + 0] * rs * ga[0] * silu(bf_lo(gt[j].x)), o[b8 + 1] * rs * ga[1] * silu(bf_hi(gt[j].x)));
;                     w.y = pk_bf16(o[b8 + 2] * rs * ga[2] * silu(bf_lo(gt[j].y)), o[b8 + 3] * rs * ga[3] * silu(bf_hi(gt[j].y)));
;                     w.z = pk_bf16(o[b8 + 4] * rs * gb[0] * silu(bf_lo(gt[j].z)), o[b8 + 5] * rs * gb[1] * silu(bf_hi(gt[j].z)));
;                     w.w = pk_bf16(o[b8 + 6] * rs * gb[2] * silu(bf_lo(gt[j].w)), o[b8 + 7] * rs * gb[3] * silu(bf_hi(gt[j].w)));
;                     *(u32x4*)(Y + (size_t)(t0 + tk) * 1024 + 512 + ch) = w; }
	v_lshlrev_b32_e32 v22, 16, v12
	v_and_b32_e32 v23, 0xffff0000, v12
	v_mul_f32_e32 v12, 0xbfb8aa3b, v22
	v_exp_f32_e32 v12, v12
	v_mul_f32_e32 v24, 0xbfb8aa3b, v23
	v_exp_f32_e32 v25, v24
	v_cvt_pk_bf16_f32 v19, v20, v21
	v_add_u32_e32 v20, 40, v146
	v_ashrrev_i32_e32 v21, 31, v20
	v_add_f32_e32 v12, 1.0, v12
	v_lshlrev_b64 v[20:21], 11, v[20:21]
	v_rcp_f32_e32 v24, v12
	v_add_f32_e32 v12, 1.0, v25
	v_lshl_add_u64 v[20:21], s[68:69], 0, v[20:21]
	v_rcp_f32_e32 v25, v12
	v_lshl_add_u64 v[20:21], v[20:21], 0, v[36:37]
	global_store_dwordx4 v[20:21], v[16:19], off offset:1024
	v_lshlrev_b32_e32 v20, 16, v13
	v_and_b32_e32 v21, 0xffff0000, v13
	v_mul_f32_e32 v12, 0xbfb8aa3b, v20
	v_mul_f32_e32 v18, v24, v22
	v_mul_f32_e32 v19, v25, v23
	v_exp_f32_e32 v22, v12
	v_mul_f32_e32 v12, 0xbfb8aa3b, v21
	v_exp_f32_e32 v23, v12
	v_mul_f32_e32 v16, v94, v106
	v_mul_f32_e32 v17, v95, v106
	s_nop 0
	v_mul_f32_e32 v16, v4, v16
	v_mul_f32_e32 v17, v5, v17
	s_nop 0
	v_mul_f32_e32 v12, v18, v16
	v_mul_f32_e32 v13, v19, v17
	v_add_f32_e32 v16, 1.0, v22
	v_add_f32_e32 v17, 1.0, v23
	v_rcp_f32_e32 v16, v16
	v_rcp_f32_e32 v17, v17
	v_cvt_pk_bf16_f32 v12, v12, v13
	v_mul_f32_e32 v18, v90, v106
	v_mul_f32_e32 v19, v91, v106
	v_mul_f32_e32 v16, v16, v20
	v_mul_f32_e32 v17, v17, v21
	v_lshlrev_b32_e32 v20, 16, v14
	v_and_b32_e32 v21, 0xffff0000, v14
	v_mul_f32_e32 v13, 0xbfb8aa3b, v20
	v_exp_f32_e32 v13, v13
	v_mul_f32_e32 v14, 0xbfb8aa3b, v21
	v_exp_f32_e32 v14, v14
	v_mul_f32_e32 v18, v6, v18
	v_mul_f32_e32 v19, v7, v19
	v_add_f32_e32 v13, 1.0, v13
	v_mul_f32_e32 v16, v16, v18
	v_mul_f32_e32 v17, v17, v19
	v_rcp_f32_e32 v18, v13
	v_add_f32_e32 v13, 1.0, v14
	v_rcp_f32_e32 v19, v13
	v_cvt_pk_bf16_f32 v13, v16, v17
	v_mul_f32_e32 v16, v88, v106
	v_mul_f32_e32 v17, v89, v106
	v_mul_f32_e32 v18, v18, v20
	v_mul_f32_e32 v19, v19, v21
	v_lshlrev_b32_e32 v20, 16, v15
	v_and_b32_e32 v21, 0xffff0000, v15
	v_mul_f32_e32 v14, 0xbfb8aa3b, v20
	v_exp_f32_e32 v22, v14
	v_mul_f32_e32 v14, 0xbfb8aa3b, v21
	v_exp_f32_e32 v23, v14
	v_mul_f32_e32 v16, v0, v16
	v_mul_f32_e32 v17, v1, v17
	s_nop 0
	v_mul_f32_e32 v14, v18, v16
	v_mul_f32_e32 v15, v19, v17
	v_add_f32_e32 v16, 1.0, v22
	v_add_f32_e32 v17, 1.0, v23
	v_rcp_f32_e32 v16, v16
	v_rcp_f32_e32 v17, v17
	v_mul_f32_e32 v18, v92, v106
	v_mul_f32_e32 v19, v93, v106
	v_cvt_pk_bf16_f32 v14, v14, v15
	v_mul_f32_e32 v18, v2, v18
	v_mul_f32_e32 v19, v3, v19
	v_mul_f32_e32 v16, v16, v20
	v_mul_f32_e32 v17, v17, v21
	s_nop 0
	v_mul_f32_e32 v16, v16, v18
	v_mul_f32_e32 v17, v17, v19
	s_waitcnt lgkmcnt(0)
	v_lshlrev_b32_e32 v18, 16, v8
	v_and_b32_e32 v19, 0xffff0000, v8
	v_mul_f32_e32 v8, 0xbfb8aa3b, v18
	v_exp_f32_e32 v8, v8
	v_mul_f32_e32 v20, 0xbfb8aa3b, v19
	v_exp_f32_e32 v21, v20
	v_cvt_pk_bf16_f32 v15, v16, v17
	v_add_u32_e32 v16, 48, v146
	v_ashrrev_i32_e32 v17, 31, v16
	v_lshlrev_b64 v[16:17], 11, v[16:17]
	v_add_f32_e32 v8, 1.0, v8
	v_lshl_add_u64 v[16:17], s[68:69], 0, v[16:17]
	v_rcp_f32_e32 v20, v8
	v_add_f32_e32 v8, 1.0, v21
	v_lshl_add_u64 v[16:17], v[16:17], 0, v[36:37]
	v_rcp_f32_e32 v21, v8
	v_lshlrev_b32_e32 v8, 16, v9
	v_and_b32_e32 v9, 0xffff0000, v9
	global_store_dwordx4 v[16:17], v[12:15], off offset:1024
	s_nop 1
	v_mul_f32_e32 v14, 0xbfb8aa3b, v8
	v_mul_f32_e32 v15, 0xbfb8aa3b, v9
	v_exp_f32_e32 v14, v14
	v_exp_f32_e32 v15, v15
	v_mul_f32_e32 v12, v102, v96
	v_mul_f32_e32 v13, v103, v96
	s_nop 0
	v_mul_f32_e32 v4, v4, v12
	v_mul_f32_e32 v5, v5, v13
	v_mul_f32_e32 v12, v20, v18
	v_mul_f32_e32 v13, v21, v19
	s_nop 0
	v_mul_f32_e32 v4, v12, v4
	v_mul_f32_e32 v5, v13, v5
	v_add_f32_e32 v12, 1.0, v14
	v_add_f32_e32 v13, 1.0, v15
	v_rcp_f32_e32 v12, v12
	v_rcp_f32_e32 v13, v13
	v_cvt_pk_bf16_f32 v4, v4, v5
	v_mul_f32_e32 v14, v100, v96
	v_mul_f32_e32 v15, v101, v96
	v_mul_f32_e32 v8, v12, v8
	v_mul_f32_e32 v9, v13, v9
	v_lshlrev_b32_e32 v12, 16, v10
	v_and_b32_e32 v13, 0xffff0000, v10
	v_mul_f32_e32 v5, 0xbfb8aa3b, v12
	v_exp_f32_e32 v5, v5
	v_mul_f32_e32 v10, 0xbfb8aa3b, v13
	v_exp_f32_e32 v10, v10
	v_mul_f32_e32 v6, v6, v14
	v_mul_f32_e32 v7, v7, v15
	v_add_f32_e32 v5, 1.0, v5
	v_mul_f32_e32 v6, v8, v6
	v_mul_f32_e32 v7, v9, v7
	v_rcp_f32_e32 v8, v5
	v_add_f32_e32 v5, 1.0, v10
	v_rcp_f32_e32 v9, v5
	v_cvt_pk_bf16_f32 v5, v6, v7
	v_mul_f32_e32 v6, v98, v96
	v_mul_f32_e32 v7, v99, v96
	s_nop 0
	v_mul_f32_e32 v0, v0, v6
	v_mul_f32_e32 v1, v1, v7
	v_mul_f32_e32 v6, v8, v12
	v_mul_f32_e32 v7, v9, v13
	v_lshlrev_b32_e32 v8, 16, v11
	v_and_b32_e32 v9, 0xffff0000, v11
	v_mul_f32_e32 v10, 0xbfb8aa3b, v8
	v_exp_f32_e32 v10, v10
	v_mul_f32_e32 v11, 0xbfb8aa3b, v9
	v_exp_f32_e32 v11, v11
	v_mul_f32_e32 v0, v6, v0
	v_mul_f32_e32 v1, v7, v1
	v_add_f32_e32 v6, 1.0, v10
	v_rcp_f32_e32 v10, v6
	v_add_f32_e32 v6, 1.0, v11
	v_rcp_f32_e32 v11, v6
	v_cvt_pk_bf16_f32 v6, v0, v1
	v_mul_f32_e32 v0, v104, v96
	v_mul_f32_e32 v1, v105, v96
	s_nop 0
	v_mul_f32_e32 v0, v2, v0
	v_mul_f32_e32 v1, v3, v1
	v_mul_f32_e32 v2, v10, v8
	v_mul_f32_e32 v3, v11, v9
	s_nop 0
	v_mul_f32_e32 v0, v2, v0
	v_mul_f32_e32 v1, v3, v1
	s_nop 0
	v_cvt_pk_bf16_f32 v7, v0, v1
	v_add_u32_e32 v0, 56, v146
	v_ashrrev_i32_e32 v1, 31, v0
	v_lshlrev_b64 v[0:1], 11, v[0:1]
	v_lshl_add_u64 v[0:1], s[68:69], 0, v[0:1]
	v_lshl_add_u64 v[0:1], v[0:1], 0, v[36:37]
	global_store_dwordx4 v[0:1], v[4:7], off offset:1024
; DI unsigned pk_bf16(float lo, float hi) { f32x2 v = {lo, hi}; bf2_t b = __builtin_convertvector(v, bf2_t); return __builtin_bit_cast(unsigned, b); }
; DI float bf_lo(unsigned u) { return __uint_as_float(u << 16); }
; DI float bf_hi(unsigned u) { return __uint_as_float(u & 0xffff0000u); }
; DI float silu(float x) { return x * __builtin_amdgcn_rcpf(1.0f + __builtin_amdgcn_exp2f(-1.4426950408889634f * x)); }
; DI void store_head(const f32x16& o0, const f32x16& o1, float rs, const unsigned char* gl, int tr, int ch0, const float* gs, bf16_t* yp) {
;     u32x2 gt[8]; f32x4 gv[8];
; #pragma unroll
;     for (int q = 0; q < 8; ++q) { const int d = 32 * (q >> 2) + 8 * (q & 3); gt[q] = *(const u32x2*)(gl + gate_off(tr, ch0 + d)); gv[q] = *(const f32x4*)(gs + d); }
; #pragma unroll
;     for (int q = 0; q < 8; ++q) { const int d = 32 * (q >> 2) + 8 * (q & 3), g = q & 3;
;         const f32x16& o = (q >> 2) ? o1 : o0;
;         u32x2 w; w.x = pk_bf16(o[4 * g + 0] * rs * gv[q][0] * silu(bf_lo(gt[q].x)), o[4 * g + 1] * rs * gv[q][1] * silu(bf_hi(gt[q].x)));
;         w.y = pk_bf16(o[4 * g + 2] * rs * gv[q][2] * silu(bf_lo(gt[q].y)), o[4 * g + 3] * rs * gv[q][3] * silu(bf_hi(gt[q].y)));
;         *(u32x2*)(yp + d) = w; }
; DI void mixer_phase(const Params& p, unsigned char* ldsraw, int vid) {
;     ...
;             if (wid < 4) {
;                 const float totA = (lf[512 + r] + lf[544 + r]) + (lf[576 + r] + lf[608 + r]), totB = (lf[640 + r] + lf[672 + r]) + (lf[704 + r] + lf[736 + r]);
;                 const float* gs = p.g_memo + 64 * wid + 4 * hh;
;                 store_head(a0, a1, rsqrtf(totA * (1.0f / 256.0f) + EPS), gl, r, 768 + 64 * wid + 4 * hh, gs, Y + (size_t)tqA * 1024 + 768 + 64 * wid + 4 * hh);
.LBB0_440:
	s_andn2_b64 vcc, exec, s[0:1]
	s_cbranch_vccnz .LBB0_395
	v_add_u32_e32 v6, 0x800, v161
	ds_read2_b32 v[0:1], v6 offset1:32
	ds_read2_b32 v[2:3], v6 offset0:64 offset1:96
	ds_read2_b32 v[4:5], v6 offset0:128 offset1:160
	ds_read2_b32 v[6:7], v6 offset0:192 offset1:224
	v_add_u32_e32 v26, 0x330, v158
	s_waitcnt lgkmcnt(3)
	v_mov_b32_e32 v8, v0
	s_waitcnt lgkmcnt(2)
	v_mov_b32_e32 v9, v2
	v_mov_b32_e32 v2, v1
	s_waitcnt lgkmcnt(1)
	v_mov_b32_e32 v0, v4
	s_waitcnt lgkmcnt(0)
	v_mov_b32_e32 v1, v6
	v_mov_b32_e32 v6, v5
	v_add_f32_e32 v36, v0, v6
	v_add_f32_e32 v37, v1, v7
	v_add_u32_e32 v6, 0x310, v158
	v_lshlrev_b32_e32 v7, 1, v6
	v_lshrrev_b32_e32 v6, 3, v6
	v_bitop3_b32 v6, v6, v160, 63 bitop3:0x6c
	v_add_f32_e32 v34, v8, v2
	v_add_f32_e32 v35, v9, v3
	v_add_u32_e32 v0, 0x300, v158
	v_and_b32_e32 v8, 0xfffffc00, v7
	v_lshlrev_b32_e32 v6, 4, v6
	v_and_b32_e32 v120, 8, v7
	v_add_u32_e32 v7, 0x318, v158
	v_lshlrev_b32_e32 v1, 1, v0
	v_lshrrev_b32_e32 v0, 3, v0
	v_add3_u32 v121, 0, v6, v8
	v_lshlrev_b32_e32 v8, 1, v7
	v_lshrrev_b32_e32 v7, 3, v7
	v_bitop3_b32 v0, v0, v160, 63 bitop3:0x6c
	v_bitop3_b32 v7, v7, v160, 63 bitop3:0x6c
	v_and_b32_e32 v2, 0xfffffc00, v1
	v_lshlrev_b32_e32 v0, 4, v0
	v_and_b32_e32 v9, 0xfffffc00, v8
	v_lshlrev_b32_e32 v7, 4, v7
	v_and_b32_e32 v122, 8, v8
	v_add_u32_e32 v8, 0x320, v158
	v_add3_u32 v117, 0, v0, v2
	v_add_u32_e32 v0, 0x308, v158
	v_add3_u32 v123, 0, v7, v9
	v_lshlrev_b32_e32 v9, 1, v8
	v_lshrrev_b32_e32 v8, 3, v8
	v_and_b32_e32 v116, 8, v1
	v_lshlrev_b32_e32 v1, 1, v0
	v_lshrrev_b32_e32 v0, 3, v0
	v_bitop3_b32 v8, v8, v160, 63 bitop3:0x6c
	v_lshlrev_b32_e32 v27, 1, v26
	v_lshrrev_b32_e32 v26, 3, v26
	v_bitop3_b32 v0, v0, v160, 63 bitop3:0x6c
	v_and_b32_e32 v10, 0xfffffc00, v9
	v_lshlrev_b32_e32 v8, 4, v8
	v_bitop3_b32 v26, v26, v160, 63 bitop3:0x6c
	v_and_b32_e32 v2, 0xfffffc00, v1
	v_lshlrev_b32_e32 v0, 4, v0
	v_add3_u32 v155, 0, v8, v10
	v_add_u32_e32 v8, 0x328, v158
	v_and_b32_e32 v28, 0xfffffc00, v27
	v_lshlrev_b32_e32 v26, 4, v26
	v_and_b32_e32 v161, 8, v27
	v_add_u32_e32 v27, 0x338, v158
	v_lshl_add_u64 v[32:33], v[144:145], 2, s[60:61]
	v_add3_u32 v4, v117, v159, v116
	v_and_b32_e32 v118, 8, v1
	v_add3_u32 v119, 0, v0, v2
	v_and_b32_e32 v154, 8, v9
	v_lshlrev_b32_e32 v9, 1, v8
	v_lshrrev_b32_e32 v8, 3, v8
	v_add3_u32 v163, 0, v26, v28
	v_lshlrev_b32_e32 v28, 1, v27
	v_lshrrev_b32_e32 v27, 3, v27
	v_add3_u32 v5, v119, v159, v118
	global_load_dwordx4 v[12:15], v[32:33], off
	global_load_dwordx4 v[0:3], v[32:33], off offset:32
	v_add3_u32 v6, v121, v159, v120
	v_add3_u32 v7, v123, v159, v122
	ds_read_b64 v[38:39], v4 offset:4096
	ds_read_b64 v[108:109], v5 offset:4096
	ds_read_b64 v[114:115], v6 offset:4096
	ds_read_b64 v[124:125], v7 offset:4096
	v_bitop3_b32 v8, v8, v160, 63 bitop3:0x6c
	v_bitop3_b32 v27, v27, v160, 63 bitop3:0x6c
	v_and_b32_e32 v10, 0xfffffc00, v9
	v_lshlrev_b32_e32 v8, 4, v8
	v_and_b32_e32 v29, 0xfffffc00, v28
	v_lshlrev_b32_e32 v27, 4, v27
	v_add3_u32 v24, v155, v159, v154
	v_and_b32_e32 v156, 8, v9
	v_add3_u32 v157, 0, v8, v10
	v_and_b32_e32 v158, 8, v28
	v_add3_u32 v160, 0, v27, v29
	s_waitcnt lgkmcnt(3)
	v_lshlrev_b32_e32 v106, 16, v38
	global_load_dwordx4 v[16:19], v[32:33], off offset:64
	global_load_dwordx4 v[4:7], v[32:33], off offset:96
	v_add3_u32 v25, v157, v159, v156
	global_load_dwordx4 v[20:23], v[32:33], off offset:128
	global_load_dwordx4 v[8:11], v[32:33], off offset:160
	v_add3_u32 v26, v163, v159, v161
	v_add3_u32 v27, v160, v159, v158
	ds_read_b64 v[126:127], v24 offset:4096
	ds_read_b64 v[128:129], v25 offset:4096
	ds_read_b64 v[112:113], v26 offset:4096
	ds_read_b64 v[96:97], v27 offset:4096
	v_and_b32_e32 v107, 0xffff0000, v38
	v_mul_f32_e32 v24, 0xbfb8aa3b, v106
	v_exp_f32_e32 v38, v24
	v_mul_f32_e32 v24, 0xbfb8aa3b, v107
	v_exp_f32_e32 v111, v24
	v_lshlrev_b32_e32 v130, 16, v39
	v_add_f32_e32 v38, 1.0, v38
	v_rcp_f32_e32 v110, v38
	v_add_f32_e32 v38, 1.0, v111
	v_rcp_f32_e32 v111, v38
	v_and_b32_e32 v131, 0xffff0000, v39
	v_mul_f32_e32 v38, 0xbfb8aa3b, v130
	v_exp_f32_e32 v132, v38
	v_mul_f32_e32 v38, 0xbfb8aa3b, v131
	v_exp_f32_e32 v133, v38
	v_mul_f32_e32 v38, v110, v106
	v_mul_f32_e32 v39, v111, v107
	s_waitcnt lgkmcnt(6)
	v_lshlrev_b32_e32 v110, 16, v108
	v_and_b32_e32 v111, 0xffff0000, v108
	v_mul_f32_e32 v108, 0xbfb8aa3b, v110
	v_add_f32_e32 v106, 1.0, v132
	v_add_f32_e32 v107, 1.0, v133
	v_exp_f32_e32 v108, v108
	v_mul_f32_e32 v132, 0xbfb8aa3b, v111
	v_rcp_f32_e32 v106, v106
	v_rcp_f32_e32 v107, v107
	v_exp_f32_e32 v132, v132
	v_add_f32_e32 v108, 1.0, v108
	v_and_b32_e32 v133, 0xffff0000, v109
	v_mul_f32_e32 v106, v106, v130
	v_mul_f32_e32 v107, v107, v131
	v_rcp_f32_e32 v130, v108
	v_add_f32_e32 v108, 1.0, v132
	v_lshlrev_b32_e32 v132, 16, v109
	v_rcp_f32_e32 v131, v108
	v_mul_f32_e32 v108, 0xbfb8aa3b, v132
	v_exp_f32_e32 v134, v108
	v_mul_f32_e32 v108, 0xbfb8aa3b, v133
	v_exp_f32_e32 v135, v108
	v_mul_f32_e32 v108, v130, v110
	v_mul_f32_e32 v109, v131, v111
	s_waitcnt lgkmcnt(5)
	v_lshlrev_b32_e32 v130, 16, v114
	v_and_b32_e32 v131, 0xffff0000, v114
	v_mul_f32_e32 v114, 0xbfb8aa3b, v130
	v_add_f32_e32 v110, 1.0, v134
	v_add_f32_e32 v111, 1.0, v135
	v_exp_f32_e32 v114, v114
	v_mul_f32_e32 v134, 0xbfb8aa3b, v131
	v_rcp_f32_e32 v110, v110
	v_rcp_f32_e32 v111, v111
	v_exp_f32_e32 v134, v134
	v_add_f32_e32 v114, 1.0, v114
	v_and_b32_e32 v135, 0xffff0000, v115
	v_mul_f32_e32 v110, v110, v132
	v_mul_f32_e32 v111, v111, v133
	v_rcp_f32_e32 v132, v114
	v_add_f32_e32 v114, 1.0, v134
	v_lshlrev_b32_e32 v134, 16, v115
	v_rcp_f32_e32 v133, v114
	v_mul_f32_e32 v114, 0xbfb8aa3b, v134
	v_exp_f32_e32 v136, v114
	v_mul_f32_e32 v114, 0xbfb8aa3b, v135
	v_exp_f32_e32 v137, v114
	v_mul_f32_e32 v114, v132, v130
	v_mul_f32_e32 v115, v133, v131
	s_waitcnt lgkmcnt(4)
; DI unsigned pk_bf16(float lo, float hi) { f32x2 v = {lo, hi}; bf2_t b = __builtin_convertvector(v, bf2_t); return __builtin_bit_cast(unsigned, b); }
; DI float bf_lo(unsigned u) { return __uint_as_float(u << 16); }
; DI float bf_hi(unsigned u) { return __uint_as_float(u & 0xffff0000u); }
; DI float silu(float x) { return x * __builtin_amdgcn_rcpf(1.0f + __builtin_amdgcn_exp2f(-1.4426950408889634f * x)); }
; DI void store_head(const f32x16& o0, const f32x16& o1, float rs, const unsigned char* gl, int tr, int ch0, const float* gs, bf16_t* yp) {
;     u32x2 gt[8]; f32x4 gv[8];
; #pragma unroll
;     for (int q = 0; q < 8; ++q) { const int d = 32 * (q >> 2) + 8 * (q & 3); gt[q] = *(const u32x2*)(gl + gate_off(tr, ch0 + d)); gv[q] = *(const f32x4*)(gs + d); }
; #pragma unroll
;     for (int q = 0; q < 8; ++q) { const int d = 32 * (q >> 2) + 8 * (q & 3), g = q & 3;
;         const f32x16& o = (q >> 2) ? o1 : o0;
;         u32x2 w; w.x = pk_bf16(o[4 * g + 0] * rs * gv[q][0] * silu(bf_lo(gt[q].x)), o[4 * g + 1] * rs * gv[q][1] * silu(bf_hi(gt[q].x)));
;         w.y = pk_bf16(o[4 * g + 2] * rs * gv[q][2] * silu(bf_lo(gt[q].y)), o[4 * g + 3] * rs * gv[q][3] * silu(bf_hi(gt[q].y)));
;         *(u32x2*)(yp + d) = w; }
; DI void mixer_phase(const Params& p, unsigned char* ldsraw, int vid) {
;     ...
;                 const float totA = (lf[512 + r] + lf[544 + r]) + (lf[576 + r] + lf[608 + r]), totB = (lf[640 + r] + lf[672 + r]) + (lf[704 + r] + lf[736 + r]);
;                 const float* gs = p.g_memo + 64 * wid + 4 * hh;
;                 store_head(a0, a1, rsqrtf(totA * (1.0f / 256.0f) + EPS), gl, r, 768 + 64 * wid + 4 * hh, gs, Y + (size_t)tqA * 1024 + 768 + 64 * wid + 4 * hh);
	v_lshlrev_b32_e32 v132, 16, v124
	v_and_b32_e32 v133, 0xffff0000, v124
	v_mul_f32_e32 v124, 0xbfb8aa3b, v132
	v_add_f32_e32 v130, 1.0, v136
	v_add_f32_e32 v131, 1.0, v137
	v_exp_f32_e32 v124, v124
	v_mul_f32_e32 v136, 0xbfb8aa3b, v133
	v_rcp_f32_e32 v130, v130
	v_rcp_f32_e32 v131, v131
	v_exp_f32_e32 v136, v136
	v_add_f32_e32 v124, 1.0, v124
	global_load_dwordx4 v[28:31], v[32:33], off offset:192
	global_load_dwordx4 v[24:27], v[32:33], off offset:224
	v_mul_f32_e32 v130, v130, v134
	v_mul_f32_e32 v131, v131, v135
	v_rcp_f32_e32 v134, v124
	v_add_f32_e32 v124, 1.0, v136
	v_rcp_f32_e32 v135, v124
	v_lshlrev_b32_e32 v124, 16, v125
	v_and_b32_e32 v125, 0xffff0000, v125
	v_mul_f32_e32 v136, 0xbfb8aa3b, v124
	v_exp_f32_e32 v136, v136
	v_mul_f32_e32 v137, 0xbfb8aa3b, v125
	v_exp_f32_e32 v137, v137
	v_mul_f32_e32 v132, v134, v132
	v_mul_f32_e32 v133, v135, v133
	v_add_f32_e32 v134, 1.0, v136
	s_waitcnt lgkmcnt(3)
	v_lshlrev_b32_e32 v136, 16, v126
	v_add_f32_e32 v135, 1.0, v137
	v_and_b32_e32 v137, 0xffff0000, v126
	v_mul_f32_e32 v126, 0xbfb8aa3b, v136
	v_exp_f32_e32 v126, v126
	v_mul_f32_e32 v138, 0xbfb8aa3b, v137
	v_rcp_f32_e32 v134, v134
	v_rcp_f32_e32 v135, v135
	v_exp_f32_e32 v138, v138
	v_add_f32_e32 v126, 1.0, v126
	s_waitcnt lgkmcnt(0)
	v_and_b32_e32 v149, 0xffff0000, v97
	v_mul_f32_e32 v124, v134, v124
	v_mul_f32_e32 v125, v135, v125
	v_rcp_f32_e32 v134, v126
	v_add_f32_e32 v126, 1.0, v138
	v_rcp_f32_e32 v135, v126
	v_lshlrev_b32_e32 v126, 16, v127
	v_and_b32_e32 v127, 0xffff0000, v127
	v_mul_f32_e32 v138, 0xbfb8aa3b, v126
	v_exp_f32_e32 v138, v138
	v_mul_f32_e32 v139, 0xbfb8aa3b, v127
	v_exp_f32_e32 v139, v139
	v_mul_f32_e32 v134, v134, v136
	v_mul_f32_e32 v135, v135, v137
	v_add_f32_e32 v136, 1.0, v138
	v_lshlrev_b32_e32 v138, 16, v128
	v_add_f32_e32 v137, 1.0, v139
	v_and_b32_e32 v139, 0xffff0000, v128
	v_mul_f32_e32 v128, 0xbfb8aa3b, v138
	v_exp_f32_e32 v128, v128
	v_mul_f32_e32 v144, 0xbfb8aa3b, v139
	v_rcp_f32_e32 v136, v136
	v_rcp_f32_e32 v137, v137
	v_exp_f32_e32 v144, v144
	v_add_f32_e32 v128, 1.0, v128
	v_mov_b32_e32 v153, v34
	v_mul_f32_e32 v126, v136, v126
	v_mul_f32_e32 v127, v137, v127
	v_rcp_f32_e32 v136, v128
	v_add_f32_e32 v128, 1.0, v144
	v_rcp_f32_e32 v137, v128
	v_lshlrev_b32_e32 v128, 16, v129
	v_and_b32_e32 v129, 0xffff0000, v129
	v_mul_f32_e32 v144, 0xbfb8aa3b, v128
	v_exp_f32_e32 v144, v144
	v_mul_f32_e32 v145, 0xbfb8aa3b, v129
	v_exp_f32_e32 v145, v145
	v_mul_f32_e32 v136, v136, v138
	v_mul_f32_e32 v137, v137, v139
	v_add_f32_e32 v138, 1.0, v144
	v_lshlrev_b32_e32 v144, 16, v112
	v_add_f32_e32 v139, 1.0, v145
	v_and_b32_e32 v145, 0xffff0000, v112
	v_mul_f32_e32 v112, 0xbfb8aa3b, v144
	v_exp_f32_e32 v112, v112
	v_mul_f32_e32 v146, 0xbfb8aa3b, v145
	v_rcp_f32_e32 v138, v138
	v_rcp_f32_e32 v139, v139
	v_exp_f32_e32 v146, v146
	v_add_f32_e32 v112, 1.0, v112
	v_mov_b32_e32 v34, v37
	v_mul_f32_e32 v128, v138, v128
	v_mul_f32_e32 v129, v139, v129
	v_rcp_f32_e32 v138, v112
	v_add_f32_e32 v112, 1.0, v146
	v_rcp_f32_e32 v139, v112
	v_lshlrev_b32_e32 v112, 16, v113
	v_and_b32_e32 v113, 0xffff0000, v113
	v_mul_f32_e32 v147, 0xbfb8aa3b, v113
	v_exp_f32_e32 v147, v147
	v_mul_f32_e32 v138, v138, v144
	v_mul_f32_e32 v139, v139, v145
	v_mul_f32_e32 v146, 0xbfb8aa3b, v112
	v_exp_f32_e32 v146, v146
	v_add_f32_e32 v145, 1.0, v147
	v_and_b32_e32 v147, 0xffff0000, v96
	v_mul_f32_e32 v148, 0xbfb8aa3b, v147
	v_exp_f32_e32 v148, v148
	v_add_f32_e32 v144, 1.0, v146
	v_rcp_f32_e32 v144, v144
	v_rcp_f32_e32 v145, v145
	v_add_f32_e32 v150, 1.0, v148
	v_lshlrev_b32_e32 v148, 16, v97
	v_mul_f32_e32 v97, 0xbfb8aa3b, v148
	v_exp_f32_e32 v151, v97
	v_mul_f32_e32 v97, 0xbfb8aa3b, v149
	v_exp_f32_e32 v152, v97
	v_rcp_f32_e32 v97, v150
	v_add_f32_e32 v150, 1.0, v151
	v_lshlrev_b32_e32 v146, 16, v96
	v_add_f32_e32 v151, 1.0, v152
	v_mov_b32_e32 v152, v36
	v_add_f32_e32 v34, v152, v34
	v_add_f32_e32 v35, v153, v35
	v_mul_f32_e32 v96, 0xbfb8aa3b, v146
	v_fma_f32 v34, v34, s88, v178
	v_fma_f32 v35, v35, s88, v178
	v_exp_f32_e32 v96, v96
	v_mul_f32_e32 v36, 0x4b800000, v35
	v_cmp_gt_f32_e32 vcc, s98, v35
	v_rcp_f32_e32 v150, v150
	v_add_f32_e32 v96, 1.0, v96
	v_cndmask_b32_e32 v35, v35, v36, vcc
	v_rsq_f32_e32 v35, v35
	v_mul_f32_e32 v36, v144, v112
	v_mul_f32_e32 v37, v145, v113
	v_rcp_f32_e32 v96, v96
	v_rcp_f32_e32 v151, v151
	v_mul_f32_e32 v144, 0x45800000, v35
	v_cndmask_b32_e32 v144, v35, v144, vcc
	v_mul_f32_e32 v48, v48, v144
	v_mul_f32_e32 v49, v49, v144
	v_mul_f32_e32 v96, v96, v146
	v_mul_f32_e32 v97, v97, v147
	s_waitcnt vmcnt(7)
	v_mul_f32_e32 v12, v12, v48
	v_mul_f32_e32 v13, v13, v49
	v_mul_f32_e32 v112, v150, v148
	v_mul_f32_e32 v113, v151, v149
	v_mul_f32_e32 v12, v12, v38
	v_mul_f32_e32 v13, v13, v39
	v_mul_f32_e32 v38, v50, v144
	v_mul_f32_e32 v39, v51, v144
	v_cvt_pk_bf16_f32 v236, v12, v13
	v_mul_f32_e32 v14, v14, v38
	v_mul_f32_e32 v15, v15, v39
	v_cmp_gt_f32_e32 vcc, s98, v34
	v_mul_f32_e32 v14, v14, v106
	v_mul_f32_e32 v15, v15, v107
	s_nop 0
	v_cvt_pk_bf16_f32 v237, v14, v15
	v_and_b32_e32 v252, 32, v205
	v_lshrrev_b32_e32 v252, 2, v252
	v_mov_b32_e32 v253, 0
	v_lshl_add_u64 v[254:255], v[140:141], 0, v[252:253]
	v_mul_f32_e32 v12, v52, v144
	v_mul_f32_e32 v13, v53, v144
	s_waitcnt vmcnt(6)
	v_mul_f32_e32 v0, v0, v12
	v_mul_f32_e32 v1, v1, v13
	v_mul_f32_e32 v12, v54, v144
	v_mul_f32_e32 v13, v55, v144
	v_mul_f32_e32 v0, v0, v108
	v_mul_f32_e32 v1, v1, v109
	v_mul_f32_e32 v2, v2, v12
	v_mul_f32_e32 v3, v3, v13
	v_cvt_pk_bf16_f32 v238, v0, v1
	v_mul_f32_e32 v2, v2, v110
	v_mul_f32_e32 v3, v3, v111
	s_nop 0
	v_cvt_pk_bf16_f32 v239, v2, v3
	s_nop 1
	v_permlane32_swap_b32_e32 v236, v238
	v_permlane32_swap_b32_e32 v237, v239
	global_store_dwordx4 v[254:255], v[236:239], off offset:1536
	v_mul_f32_e32 v0, v56, v144
	v_mul_f32_e32 v1, v57, v144
	v_mul_f32_e32 v2, v40, v144
	v_mul_f32_e32 v3, v41, v144
	s_waitcnt vmcnt(6)
; DI unsigned pk_bf16(float lo, float hi) { f32x2 v = {lo, hi}; bf2_t b = __builtin_convertvector(v, bf2_t); return __builtin_bit_cast(unsigned, b); }
; DI float bf_lo(unsigned u) { return __uint_as_float(u << 16); }
; DI float bf_hi(unsigned u) { return __uint_as_float(u & 0xffff0000u); }
; DI float silu(float x) { return x * __builtin_amdgcn_rcpf(1.0f + __builtin_amdgcn_exp2f(-1.4426950408889634f * x)); }
; DI void store_head(const f32x16& o0, const f32x16& o1, float rs, const unsigned char* gl, int tr, int ch0, const float* gs, bf16_t* yp) {
;     u32x2 gt[8]; f32x4 gv[8];
; #pragma unroll
;     for (int q = 0; q < 8; ++q) { const int d = 32 * (q >> 2) + 8 * (q & 3); gt[q] = *(const u32x2*)(gl + gate_off(tr, ch0 + d)); gv[q] = *(const f32x4*)(gs + d); }
; #pragma unroll
;     for (int q = 0; q < 8; ++q) { const int d = 32 * (q >> 2) + 8 * (q & 3), g = q & 3;
;         const f32x16& o = (q >> 2) ? o1 : o0;
;         u32x2 w; w.x = pk_bf16(o[4 * g + 0] * rs * gv[q][0] * silu(bf_lo(gt[q].x)), o[4 * g + 1] * rs * gv[q][1] * silu(bf_hi(gt[q].x)));
;         w.y = pk_bf16(o[4 * g + 2] * rs * gv[q][2] * silu(bf_lo(gt[q].y)), o[4 * g + 3] * rs * gv[q][3] * silu(bf_hi(gt[q].y)));
;         *(u32x2*)(yp + d) = w; }
; DI void mixer_phase(const Params& p, unsigned char* ldsraw, int vid) {
;     ...
;                 store_head(a0, a1, rsqrtf(totA * (1.0f / 256.0f) + EPS), gl, r, 768 + 64 * wid + 4 * hh, gs, Y + (size_t)tqA * 1024 + 768 + 64 * wid + 4 * hh);
;                 store_head(b0, b1, rsqrtf(totB * (1.0f / 256.0f) + EPS), gl, r + 32, 768 + 64 * wid + 4 * hh, gs, Y + (size_t)tqB * 1024 + 768 + 64 * wid + 4 * hh);
	v_mul_f32_e32 v0, v0, v16
	v_mul_f32_e32 v1, v1, v17
	v_mul_f32_e32 v2, v2, v18
	v_mul_f32_e32 v3, v3, v19
	v_mul_f32_e32 v0, v0, v114
	v_mul_f32_e32 v1, v1, v115
	v_mul_f32_e32 v2, v2, v130
	v_mul_f32_e32 v3, v3, v131
	v_cvt_pk_bf16_f32 v240, v0, v1
	v_cvt_pk_bf16_f32 v241, v2, v3
	v_mul_f32_e32 v0, v42, v144
	v_mul_f32_e32 v1, v43, v144
	v_mul_f32_e32 v2, v44, v144
	v_mul_f32_e32 v3, v45, v144
	s_waitcnt vmcnt(5)
	v_mul_f32_e32 v0, v0, v4
	v_mul_f32_e32 v1, v1, v5
	v_mul_f32_e32 v2, v2, v6
	v_mul_f32_e32 v3, v3, v7
	v_mul_f32_e32 v0, v0, v132
	v_mul_f32_e32 v1, v1, v133
	v_mul_f32_e32 v2, v2, v124
	v_mul_f32_e32 v3, v3, v125
	v_cvt_pk_bf16_f32 v242, v0, v1
	v_cvt_pk_bf16_f32 v243, v2, v3
	s_nop 1
	v_permlane32_swap_b32_e32 v240, v242
	v_permlane32_swap_b32_e32 v241, v243
	global_store_dwordx4 v[254:255], v[240:243], off offset:1568
	v_mul_f32_e32 v0, v64, v144
	v_mul_f32_e32 v1, v65, v144
	v_mul_f32_e32 v2, v66, v144
	v_mul_f32_e32 v3, v67, v144
	s_waitcnt vmcnt(5)
	v_mul_f32_e32 v0, v0, v20
	v_mul_f32_e32 v1, v1, v21
	v_mul_f32_e32 v2, v2, v22
	v_mul_f32_e32 v3, v3, v23
	v_mul_f32_e32 v0, v0, v134
	v_mul_f32_e32 v1, v1, v135
	v_mul_f32_e32 v2, v2, v126
	v_mul_f32_e32 v3, v3, v127
	v_cvt_pk_bf16_f32 v244, v0, v1
	v_cvt_pk_bf16_f32 v245, v2, v3
	v_mul_f32_e32 v0, v68, v144
	v_mul_f32_e32 v1, v69, v144
	v_mul_f32_e32 v2, v70, v144
	v_mul_f32_e32 v3, v71, v144
	s_waitcnt vmcnt(4)
	v_mul_f32_e32 v0, v0, v8
	v_mul_f32_e32 v1, v1, v9
	v_mul_f32_e32 v2, v2, v10
	v_mul_f32_e32 v3, v3, v11
	v_mul_f32_e32 v0, v0, v136
	v_mul_f32_e32 v1, v1, v137
	v_mul_f32_e32 v2, v2, v128
	v_mul_f32_e32 v3, v3, v129
	v_cvt_pk_bf16_f32 v246, v0, v1
	v_cvt_pk_bf16_f32 v247, v2, v3
	s_nop 1
	v_permlane32_swap_b32_e32 v244, v246
	v_permlane32_swap_b32_e32 v245, v247
	global_store_dwordx4 v[254:255], v[244:247], off offset:1600
	v_mul_f32_e32 v0, v72, v144
	v_mul_f32_e32 v1, v73, v144
	v_mul_f32_e32 v2, v58, v144
	v_mul_f32_e32 v3, v59, v144
	s_waitcnt vmcnt(4)
	v_mul_f32_e32 v0, v0, v28
	v_mul_f32_e32 v1, v1, v29
	v_mul_f32_e32 v2, v2, v30
	v_mul_f32_e32 v3, v3, v31
	v_mul_f32_e32 v0, v0, v138
	v_mul_f32_e32 v1, v1, v139
	v_mul_f32_e32 v2, v2, v36
	v_mul_f32_e32 v3, v3, v37
	v_cvt_pk_bf16_f32 v248, v0, v1
	v_cvt_pk_bf16_f32 v249, v2, v3
	v_mul_f32_e32 v0, v60, v144
	v_mul_f32_e32 v1, v61, v144
	v_mul_f32_e32 v2, v46, v144
	v_mul_f32_e32 v3, v47, v144
	s_waitcnt vmcnt(3)
	v_mul_f32_e32 v0, v0, v24
	v_mul_f32_e32 v1, v1, v25
	v_mul_f32_e32 v2, v2, v26
	v_mul_f32_e32 v3, v3, v27
	v_mul_f32_e32 v0, v0, v96
	v_mul_f32_e32 v1, v1, v97
	v_mul_f32_e32 v2, v2, v112
	v_mul_f32_e32 v3, v3, v113
	v_cvt_pk_bf16_f32 v250, v0, v1
	v_cvt_pk_bf16_f32 v251, v2, v3
	s_nop 1
	v_permlane32_swap_b32_e32 v248, v250
	v_permlane32_swap_b32_e32 v249, v251
	global_store_dwordx4 v[254:255], v[248:251], off offset:1632
	global_load_dwordx4 v[24:27], v[32:33], off
	global_load_dwordx4 v[28:31], v[32:33], off offset:32
	v_mul_f32_e32 v0, 0x4b800000, v34
	v_cndmask_b32_e32 v0, v34, v0, vcc
	v_rsq_f32_e32 v0, v0
	v_add3_u32 v2, v121, v162, v120
	v_add3_u32 v3, v123, v162, v122
	v_mul_f32_e32 v1, 0x45800000, v0
	v_cndmask_b32_e32 v16, v0, v1, vcc
	v_add3_u32 v0, v117, v162, v116
	v_add3_u32 v1, v119, v162, v118
	ds_read_b64 v[42:43], v0 offset:4096
	ds_read_b64 v[44:45], v1 offset:4096
	ds_read_b64 v[46:47], v2 offset:4096
	ds_read_b64 v[48:49], v3 offset:4096
	global_load_dwordx4 v[34:37], v[32:33], off offset:64
	global_load_dwordx4 v[38:41], v[32:33], off offset:96
	s_waitcnt lgkmcnt(3)
	v_lshlrev_b32_e32 v50, 16, v42
	v_and_b32_e32 v51, 0xffff0000, v42
	v_mul_f32_e32 v4, 0xbfb8aa3b, v50
	v_exp_f32_e32 v4, v4
	v_mul_f32_e32 v5, 0xbfb8aa3b, v51
	v_exp_f32_e32 v5, v5
	v_add3_u32 v0, v155, v162, v154
	v_add3_u32 v1, v157, v162, v156
	global_load_dwordx4 v[12:15], v[32:33], off offset:128
	global_load_dwordx4 v[8:11], v[32:33], off offset:160
	v_add3_u32 v2, v163, v162, v161
	v_add3_u32 v3, v160, v162, v158
	ds_read_b64 v[52:53], v0 offset:4096
	ds_read_b64 v[22:23], v1 offset:4096
	ds_read_b64 v[20:21], v2 offset:4096
	ds_read_b64 v[18:19], v3 offset:4096
	v_add_f32_e32 v0, 1.0, v4
	v_rcp_f32_e32 v54, v0
	v_add_f32_e32 v0, 1.0, v5
	v_rcp_f32_e32 v55, v0
	v_lshlrev_b32_e32 v42, 16, v43
	global_load_dwordx4 v[4:7], v[32:33], off offset:192
	global_load_dwordx4 v[0:3], v[32:33], off offset:224
	v_mul_f32_e32 v32, v80, v16
	v_mul_f32_e32 v33, v81, v16
	v_and_b32_e32 v43, 0xffff0000, v43
	v_mul_f32_e32 v17, 0xbfb8aa3b, v42
	v_exp_f32_e32 v17, v17
	s_waitcnt vmcnt(7)
	v_mul_f32_e32 v24, v32, v24
	v_mul_f32_e32 v25, v33, v25
	v_mul_f32_e32 v32, v54, v50
	v_mul_f32_e32 v33, v55, v51
	v_mul_f32_e32 v50, 0xbfb8aa3b, v43
	v_exp_f32_e32 v50, v50
	v_add_f32_e32 v17, 1.0, v17
	v_mul_f32_e32 v24, v24, v32
	v_mul_f32_e32 v25, v25, v33
	v_rcp_f32_e32 v32, v17
	v_add_f32_e32 v17, 1.0, v50
	v_rcp_f32_e32 v33, v17
	v_mul_f32_e32 v50, v76, v16
	v_mul_f32_e32 v51, v77, v16
	v_cvt_pk_bf16_f32 v236, v24, v25
	v_mul_f32_e32 v26, v50, v26
	v_mul_f32_e32 v27, v51, v27
	v_mul_f32_e32 v32, v32, v42
	v_mul_f32_e32 v33, v33, v43
	s_nop 0
	v_mul_f32_e32 v26, v26, v32
	v_mul_f32_e32 v27, v27, v33
	s_waitcnt lgkmcnt(6)
	v_lshlrev_b32_e32 v32, 16, v44
	v_and_b32_e32 v33, 0xffff0000, v44
	v_mul_f32_e32 v17, 0xbfb8aa3b, v32
	v_exp_f32_e32 v17, v17
	v_mul_f32_e32 v25, 0xbfb8aa3b, v33
	v_exp_f32_e32 v42, v25
	v_cvt_pk_bf16_f32 v237, v26, v27
	v_add_f32_e32 v17, 1.0, v17
	v_rcp_f32_e32 v26, v17
	v_add_f32_e32 v17, 1.0, v42
	v_rcp_f32_e32 v27, v17
	v_and_b32_e32 v252, 32, v205
	v_lshrrev_b32_e32 v252, 2, v252
	v_mov_b32_e32 v253, 0
	v_lshl_add_u64 v[254:255], v[142:143], 0, v[252:253]
	v_mul_f32_e32 v24, v74, v16
	v_mul_f32_e32 v25, v75, v16
	v_mul_f32_e32 v26, v26, v32
	v_mul_f32_e32 v27, v27, v33
	s_waitcnt vmcnt(6)
; DI unsigned pk_bf16(float lo, float hi) { f32x2 v = {lo, hi}; bf2_t b = __builtin_convertvector(v, bf2_t); return __builtin_bit_cast(unsigned, b); }
; DI float bf_lo(unsigned u) { return __uint_as_float(u << 16); }
; DI float bf_hi(unsigned u) { return __uint_as_float(u & 0xffff0000u); }
; DI float silu(float x) { return x * __builtin_amdgcn_rcpf(1.0f + __builtin_amdgcn_exp2f(-1.4426950408889634f * x)); }
; DI void store_head(const f32x16& o0, const f32x16& o1, float rs, const unsigned char* gl, int tr, int ch0, const float* gs, bf16_t* yp) {
;     u32x2 gt[8]; f32x4 gv[8];
; #pragma unroll
;     for (int q = 0; q < 8; ++q) { const int d = 32 * (q >> 2) + 8 * (q & 3); gt[q] = *(const u32x2*)(gl + gate_off(tr, ch0 + d)); gv[q] = *(const f32x4*)(gs + d); }
; #pragma unroll
;     for (int q = 0; q < 8; ++q) { const int d = 32 * (q >> 2) + 8 * (q & 3), g = q & 3;
;         const f32x16& o = (q >> 2) ? o1 : o0;
;         u32x2 w; w.x = pk_bf16(o[4 * g + 0] * rs * gv[q][0] * silu(bf_lo(gt[q].x)), o[4 * g + 1] * rs * gv[q][1] * silu(bf_hi(gt[q].x)));
;         w.y = pk_bf16(o[4 * g + 2] * rs * gv[q][2] * silu(bf_lo(gt[q].y)), o[4 * g + 3] * rs * gv[q][3] * silu(bf_hi(gt[q].y)));
;         *(u32x2*)(yp + d) = w; }
; DI void mixer_phase(const Params& p, unsigned char* ldsraw, int vid) {
;     ...
;                 store_head(b0, b1, rsqrtf(totB * (1.0f / 256.0f) + EPS), gl, r + 32, 768 + 64 * wid + 4 * hh, gs, Y + (size_t)tqB * 1024 + 768 + 64 * wid + 4 * hh);
	v_mul_f32_e32 v24, v24, v28
	v_mul_f32_e32 v25, v25, v29
	v_lshlrev_b32_e32 v28, 16, v45
	v_and_b32_e32 v29, 0xffff0000, v45
	v_mul_f32_e32 v17, 0xbfb8aa3b, v28
	v_exp_f32_e32 v17, v17
	v_mul_f32_e32 v32, 0xbfb8aa3b, v29
	v_exp_f32_e32 v32, v32
	v_mul_f32_e32 v24, v24, v26
	v_mul_f32_e32 v25, v25, v27
	v_add_f32_e32 v17, 1.0, v17
	v_rcp_f32_e32 v26, v17
	v_add_f32_e32 v17, 1.0, v32
	v_rcp_f32_e32 v27, v17
	v_mul_f32_e32 v32, v78, v16
	v_mul_f32_e32 v33, v79, v16
	v_cvt_pk_bf16_f32 v238, v24, v25
	v_mul_f32_e32 v30, v32, v30
	v_mul_f32_e32 v31, v33, v31
	v_mul_f32_e32 v26, v26, v28
	v_mul_f32_e32 v27, v27, v29
	s_waitcnt lgkmcnt(5)
	v_lshlrev_b32_e32 v28, 16, v46
	v_and_b32_e32 v29, 0xffff0000, v46
	v_mul_f32_e32 v17, 0xbfb8aa3b, v28
	v_exp_f32_e32 v17, v17
	v_mul_f32_e32 v25, 0xbfb8aa3b, v29
	v_mul_f32_e32 v26, v30, v26
	v_mul_f32_e32 v27, v31, v27
	v_exp_f32_e32 v30, v25
	v_add_f32_e32 v17, 1.0, v17
	v_cvt_pk_bf16_f32 v239, v26, v27
	v_rcp_f32_e32 v26, v17
	v_add_f32_e32 v17, 1.0, v30
	v_rcp_f32_e32 v27, v17
	s_nop 1
	v_permlane32_swap_b32_e32 v236, v238
	v_permlane32_swap_b32_e32 v237, v239
	global_store_dwordx4 v[254:255], v[236:239], off offset:1536
	v_mul_f32_e32 v24, v86, v16
	v_mul_f32_e32 v25, v87, v16
	v_mul_f32_e32 v26, v26, v28
	v_mul_f32_e32 v27, v27, v29
	v_lshlrev_b32_e32 v28, 16, v47
	v_and_b32_e32 v29, 0xffff0000, v47
	v_mul_f32_e32 v17, 0xbfb8aa3b, v28
	v_exp_f32_e32 v17, v17
	v_mul_f32_e32 v30, 0xbfb8aa3b, v29
	v_exp_f32_e32 v30, v30
	s_waitcnt vmcnt(6)
	v_mul_f32_e32 v24, v24, v34
	v_mul_f32_e32 v25, v25, v35
	v_add_f32_e32 v17, 1.0, v17
	v_mul_f32_e32 v24, v24, v26
	v_mul_f32_e32 v25, v25, v27
	v_rcp_f32_e32 v26, v17
	v_add_f32_e32 v17, 1.0, v30
	v_rcp_f32_e32 v27, v17
	v_mul_f32_e32 v30, v84, v16
	v_mul_f32_e32 v31, v85, v16
	v_cvt_pk_bf16_f32 v240, v24, v25
	v_mul_f32_e32 v30, v30, v36
	v_mul_f32_e32 v31, v31, v37
	v_mul_f32_e32 v26, v26, v28
	v_mul_f32_e32 v27, v27, v29
	s_waitcnt lgkmcnt(4)
	v_lshlrev_b32_e32 v28, 16, v48
	v_and_b32_e32 v29, 0xffff0000, v48
	v_mul_f32_e32 v17, 0xbfb8aa3b, v28
	v_exp_f32_e32 v17, v17
	v_mul_f32_e32 v25, 0xbfb8aa3b, v29
	v_mul_f32_e32 v26, v30, v26
	v_mul_f32_e32 v27, v31, v27
	v_exp_f32_e32 v30, v25
	v_add_f32_e32 v17, 1.0, v17
	v_cvt_pk_bf16_f32 v241, v26, v27
	v_rcp_f32_e32 v26, v17
	v_add_f32_e32 v17, 1.0, v30
	v_rcp_f32_e32 v27, v17
	v_mul_f32_e32 v24, v82, v16
	v_mul_f32_e32 v25, v83, v16
	v_mul_f32_e32 v26, v26, v28
	v_mul_f32_e32 v27, v27, v29
	v_lshlrev_b32_e32 v28, 16, v49
	v_and_b32_e32 v29, 0xffff0000, v49
	v_mul_f32_e32 v17, 0xbfb8aa3b, v28
	v_exp_f32_e32 v17, v17
	v_mul_f32_e32 v30, 0xbfb8aa3b, v29
	v_exp_f32_e32 v30, v30
	s_waitcnt vmcnt(5)
	v_mul_f32_e32 v24, v24, v38
	v_mul_f32_e32 v25, v25, v39
	v_add_f32_e32 v17, 1.0, v17
	v_mul_f32_e32 v24, v24, v26
	v_mul_f32_e32 v25, v25, v27
	v_rcp_f32_e32 v26, v17
	v_add_f32_e32 v17, 1.0, v30
	v_rcp_f32_e32 v27, v17
	v_mul_f32_e32 v30, v62, v16
	v_mul_f32_e32 v31, v63, v16
	v_cvt_pk_bf16_f32 v242, v24, v25
	v_mul_f32_e32 v30, v30, v40
	v_mul_f32_e32 v31, v31, v41
	v_mul_f32_e32 v26, v26, v28
	v_mul_f32_e32 v27, v27, v29
	s_waitcnt lgkmcnt(3)
	v_lshlrev_b32_e32 v28, 16, v52
	v_and_b32_e32 v29, 0xffff0000, v52
	v_mul_f32_e32 v17, 0xbfb8aa3b, v28
	v_exp_f32_e32 v17, v17
	v_mul_f32_e32 v25, 0xbfb8aa3b, v29
	v_mul_f32_e32 v26, v30, v26
	v_mul_f32_e32 v27, v31, v27
	v_exp_f32_e32 v30, v25
	v_add_f32_e32 v17, 1.0, v17
	v_cvt_pk_bf16_f32 v243, v26, v27
	v_rcp_f32_e32 v26, v17
	v_add_f32_e32 v17, 1.0, v30
	v_rcp_f32_e32 v27, v17
	s_nop 1
	v_permlane32_swap_b32_e32 v240, v242
	v_permlane32_swap_b32_e32 v241, v243
	global_store_dwordx4 v[254:255], v[240:243], off offset:1568
	v_mul_f32_e32 v24, v94, v16
	v_mul_f32_e32 v25, v95, v16
	s_waitcnt vmcnt(5)
	v_mul_f32_e32 v12, v24, v12
	v_mul_f32_e32 v13, v25, v13
	v_mul_f32_e32 v24, v26, v28
	v_mul_f32_e32 v25, v27, v29
	v_lshlrev_b32_e32 v26, 16, v53
	v_and_b32_e32 v27, 0xffff0000, v53
	v_mul_f32_e32 v17, 0xbfb8aa3b, v26
	v_exp_f32_e32 v17, v17
	v_mul_f32_e32 v28, 0xbfb8aa3b, v27
	v_exp_f32_e32 v28, v28
	v_mul_f32_e32 v12, v12, v24
	v_mul_f32_e32 v13, v13, v25
	v_add_f32_e32 v17, 1.0, v17
	v_rcp_f32_e32 v24, v17
	v_add_f32_e32 v17, 1.0, v28
	v_rcp_f32_e32 v25, v17
	v_mul_f32_e32 v28, v90, v16
	v_mul_f32_e32 v29, v91, v16
	v_cvt_pk_bf16_f32 v244, v12, v13
	v_mul_f32_e32 v14, v28, v14
	v_mul_f32_e32 v15, v29, v15
	v_mul_f32_e32 v24, v24, v26
	v_mul_f32_e32 v25, v25, v27
	s_nop 0
	v_mul_f32_e32 v14, v14, v24
	v_mul_f32_e32 v15, v15, v25
	s_waitcnt lgkmcnt(2)
; DI unsigned pk_bf16(float lo, float hi) { f32x2 v = {lo, hi}; bf2_t b = __builtin_convertvector(v, bf2_t); return __builtin_bit_cast(unsigned, b); }
; DI float bf_lo(unsigned u) { return __uint_as_float(u << 16); }
; DI float bf_hi(unsigned u) { return __uint_as_float(u & 0xffff0000u); }
; DI float silu(float x) { return x * __builtin_amdgcn_rcpf(1.0f + __builtin_amdgcn_exp2f(-1.4426950408889634f * x)); }
; DI void store_head(const f32x16& o0, const f32x16& o1, float rs, const unsigned char* gl, int tr, int ch0, const float* gs, bf16_t* yp) {
;     u32x2 gt[8]; f32x4 gv[8];
; #pragma unroll
;     for (int q = 0; q < 8; ++q) { const int d = 32 * (q >> 2) + 8 * (q & 3); gt[q] = *(const u32x2*)(gl + gate_off(tr, ch0 + d)); gv[q] = *(const f32x4*)(gs + d); }
; #pragma unroll
;     for (int q = 0; q < 8; ++q) { const int d = 32 * (q >> 2) + 8 * (q & 3), g = q & 3;
;         const f32x16& o = (q >> 2) ? o1 : o0;
;         u32x2 w; w.x = pk_bf16(o[4 * g + 0] * rs * gv[q][0] * silu(bf_lo(gt[q].x)), o[4 * g + 1] * rs * gv[q][1] * silu(bf_hi(gt[q].x)));
;         w.y = pk_bf16(o[4 * g + 2] * rs * gv[q][2] * silu(bf_lo(gt[q].y)), o[4 * g + 3] * rs * gv[q][3] * silu(bf_hi(gt[q].y)));
;         *(u32x2*)(yp + d) = w; }
; DI void mixer_phase(const Params& p, unsigned char* ldsraw, int vid) {
;     ...
;                 store_head(b0, b1, rsqrtf(totB * (1.0f / 256.0f) + EPS), gl, r + 32, 768 + 64 * wid + 4 * hh, gs, Y + (size_t)tqB * 1024 + 768 + 64 * wid + 4 * hh);
	v_lshlrev_b32_e32 v24, 16, v22
	v_and_b32_e32 v25, 0xffff0000, v22
	v_mul_f32_e32 v13, 0xbfb8aa3b, v24
	v_exp_f32_e32 v17, v13
	v_mul_f32_e32 v13, 0xbfb8aa3b, v25
	v_exp_f32_e32 v22, v13
	v_cvt_pk_bf16_f32 v245, v14, v15
	v_add_f32_e32 v14, 1.0, v17
	v_rcp_f32_e32 v14, v14
	v_add_f32_e32 v15, 1.0, v22
	v_rcp_f32_e32 v15, v15
	v_mul_f32_e32 v12, v88, v16
	v_mul_f32_e32 v13, v89, v16
	s_waitcnt vmcnt(4)
	v_mul_f32_e32 v8, v12, v8
	v_mul_f32_e32 v9, v13, v9
	v_mul_f32_e32 v12, v14, v24
	v_mul_f32_e32 v13, v15, v25
	v_lshlrev_b32_e32 v14, 16, v23
	v_and_b32_e32 v15, 0xffff0000, v23
	v_mul_f32_e32 v17, 0xbfb8aa3b, v14
	v_mul_f32_e32 v22, 0xbfb8aa3b, v15
	v_exp_f32_e32 v17, v17
	v_exp_f32_e32 v22, v22
	v_mul_f32_e32 v8, v8, v12
	v_mul_f32_e32 v9, v9, v13
	v_add_f32_e32 v12, 1.0, v17
	v_add_f32_e32 v13, 1.0, v22
	v_rcp_f32_e32 v12, v12
	v_rcp_f32_e32 v13, v13
	v_mul_f32_e32 v22, v92, v16
	v_mul_f32_e32 v23, v93, v16
	v_cvt_pk_bf16_f32 v246, v8, v9
	v_mul_f32_e32 v10, v22, v10
	v_mul_f32_e32 v11, v23, v11
	v_mul_f32_e32 v12, v12, v14
	v_mul_f32_e32 v13, v13, v15
	s_nop 0
	v_mul_f32_e32 v10, v10, v12
	v_mul_f32_e32 v11, v11, v13
	s_waitcnt lgkmcnt(1)
	v_lshlrev_b32_e32 v12, 16, v20
	v_and_b32_e32 v13, 0xffff0000, v20
	v_mul_f32_e32 v9, 0xbfb8aa3b, v12
	v_exp_f32_e32 v14, v9
	v_mul_f32_e32 v9, 0xbfb8aa3b, v13
	v_exp_f32_e32 v15, v9
	v_cvt_pk_bf16_f32 v247, v10, v11
	v_add_f32_e32 v10, 1.0, v14
	v_rcp_f32_e32 v10, v10
	v_add_f32_e32 v11, 1.0, v15
	v_rcp_f32_e32 v11, v11
	s_nop 1
	v_permlane32_swap_b32_e32 v244, v246
	v_permlane32_swap_b32_e32 v245, v247
	global_store_dwordx4 v[254:255], v[244:247], off offset:1600
	v_mul_f32_e32 v8, v102, v16
	v_mul_f32_e32 v9, v103, v16
	s_waitcnt vmcnt(4)
	v_mul_f32_e32 v4, v8, v4
	v_mul_f32_e32 v5, v9, v5
	v_mul_f32_e32 v8, v10, v12
	v_mul_f32_e32 v9, v11, v13
	v_lshlrev_b32_e32 v10, 16, v21
	v_and_b32_e32 v11, 0xffff0000, v21
	v_mul_f32_e32 v12, 0xbfb8aa3b, v10
	v_mul_f32_e32 v13, 0xbfb8aa3b, v11
	v_exp_f32_e32 v12, v12
	v_exp_f32_e32 v13, v13
	v_mul_f32_e32 v4, v4, v8
	v_mul_f32_e32 v5, v5, v9
	v_add_f32_e32 v8, 1.0, v12
	v_add_f32_e32 v9, 1.0, v13
	v_rcp_f32_e32 v8, v8
	v_rcp_f32_e32 v9, v9
	v_mul_f32_e32 v12, v100, v16
	v_mul_f32_e32 v13, v101, v16
	v_cvt_pk_bf16_f32 v248, v4, v5
	v_mul_f32_e32 v6, v12, v6
	v_mul_f32_e32 v7, v13, v7
	v_mul_f32_e32 v8, v8, v10
	v_mul_f32_e32 v9, v9, v11
	s_nop 0
	v_mul_f32_e32 v6, v6, v8
	v_mul_f32_e32 v7, v7, v9
	s_waitcnt lgkmcnt(0)
	v_lshlrev_b32_e32 v8, 16, v18
	v_and_b32_e32 v9, 0xffff0000, v18
	v_mul_f32_e32 v5, 0xbfb8aa3b, v8
	v_exp_f32_e32 v10, v5
	v_mul_f32_e32 v5, 0xbfb8aa3b, v9
	v_exp_f32_e32 v11, v5
	v_cvt_pk_bf16_f32 v249, v6, v7
	v_add_f32_e32 v6, 1.0, v10
	v_rcp_f32_e32 v6, v6
	v_add_f32_e32 v7, 1.0, v11
	v_rcp_f32_e32 v7, v7
	v_mul_f32_e32 v4, v98, v16
	v_mul_f32_e32 v5, v99, v16
	s_waitcnt vmcnt(3)
	v_mul_f32_e32 v0, v4, v0
	v_mul_f32_e32 v1, v5, v1
	v_mul_f32_e32 v4, v6, v8
	v_mul_f32_e32 v5, v7, v9
	v_lshlrev_b32_e32 v6, 16, v19
	v_and_b32_e32 v7, 0xffff0000, v19
	v_mul_f32_e32 v8, 0xbfb8aa3b, v6
	v_mul_f32_e32 v9, 0xbfb8aa3b, v7
	v_exp_f32_e32 v8, v8
	v_exp_f32_e32 v9, v9
	v_mul_f32_e32 v0, v0, v4
	v_mul_f32_e32 v1, v1, v5
	v_add_f32_e32 v4, 1.0, v8
	v_add_f32_e32 v5, 1.0, v9
	v_rcp_f32_e32 v4, v4
	v_rcp_f32_e32 v5, v5
	v_mul_f32_e32 v8, v104, v16
	v_mul_f32_e32 v9, v105, v16
	v_cvt_pk_bf16_f32 v250, v0, v1
	v_mul_f32_e32 v2, v8, v2
	v_mul_f32_e32 v3, v9, v3
	v_mul_f32_e32 v4, v4, v6
	v_mul_f32_e32 v5, v5, v7
	s_nop 0
	v_mul_f32_e32 v2, v2, v4
	v_mul_f32_e32 v3, v3, v5
	s_nop 0
	v_cvt_pk_bf16_f32 v251, v2, v3
	s_nop 1
	v_permlane32_swap_b32_e32 v248, v250
	v_permlane32_swap_b32_e32 v249, v251
	global_store_dwordx4 v[254:255], v[248:251], off offset:1632
	s_branch .LBB0_395
